# expert loop: cross-row reduction stage via v_permlane16_swap instead of a bpermute exchange (bit-identical)
# speedup vs baseline: 1.0639x; 1.0029x over previous
.Lxg_loop_p6:
	s_waitcnt lgkmcnt(0)
	v_lshl_add_u32 v250, v240, 9, v241
	v_lshl_add_u32 v251, v242, 9, v241
	v_lshl_add_u32 v252, v246, 9, v241
	v_lshl_add_u32 v253, v248, 9, v241
	global_load_dwordx4 v[192:195], v250, s[98:99]
	global_load_dwordx4 v[196:199], v251, s[98:99]
	global_load_dwordx4 v[200:203], v252, s[98:99]
	global_load_dwordx4 v[204:207], v253, s[98:99]
	global_load_dwordx4 v[208:211], v250, s[100:101]
	global_load_dwordx4 v[212:215], v251, s[100:101]
	global_load_dwordx4 v[216:219], v252, s[100:101]
	global_load_dwordx4 v[220:223], v253, s[100:101]
	s_add_u32 s23, s22, 2
	s_cmp_lt_u32 s23, 8
	s_cselect_b64 s[8:9], -1, 0
	s_and_b32 s23, s23, 7
	s_lshl_b32 s23, s23, 5
	v_cndmask_b32_e64 v126, v96, v94, s[8:9]
	v_lshl_add_u32 v129, v139, 2, s23
	ds_bpermute_b32 v240, v129, v126
	ds_bpermute_b32 v242, v129, v126 offset:8
	ds_bpermute_b32 v246, v129, v126 offset:16
	ds_bpermute_b32 v248, v129, v126 offset:24
	s_add_u32 s23, s22, 0
	s_cmp_lt_u32 s23, 8
	s_cselect_b64 s[8:9], -1, 0
	s_and_b32 s23, s23, 7
	s_lshl_b32 s23, s23, 5
	v_cndmask_b32_e64 v127, v150, v149, s[8:9]
	v_cndmask_b32_e64 v128, v152, v151, s[8:9]
	v_lshl_add_u32 v130, v140, 2, s23
	ds_bpermute_b32 v156, v130, v127
	ds_bpermute_b32 v157, v130, v128
	s_waitcnt vmcnt(14)
	v_cvt_scalef32_pk_f32_fp4 v[224:225], v160, 1.0
	v_cvt_scalef32_pk_f32_fp4 v[226:227], v164, 1.0
	v_cvt_scalef32_pk_f32_fp4 v[228:229], v160, 1.0 op_sel:[1,0,0]
	v_cvt_scalef32_pk_f32_fp4 v[230:231], v164, 1.0 op_sel:[1,0,0]
	v_pk_fma_f32 v[232:233], v[24:25], v[224:225], 0 op_sel_hi:[1,1,0]
	v_pk_fma_f32 v[234:235], v[24:25], v[226:227], 0 op_sel_hi:[1,1,0]
	v_cvt_scalef32_pk_f32_fp4 v[224:225], v160, 1.0 op_sel:[0,1,0]
	v_cvt_scalef32_pk_f32_fp4 v[226:227], v164, 1.0 op_sel:[0,1,0]
	v_pk_fma_f32 v[232:233], v[26:27], v[228:229], v[232:233]
	v_pk_fma_f32 v[234:235], v[26:27], v[230:231], v[234:235]
	v_cvt_scalef32_pk_f32_fp4 v[228:229], v160, 1.0 op_sel:[1,1,0]
	v_cvt_scalef32_pk_f32_fp4 v[230:231], v164, 1.0 op_sel:[1,1,0]
	v_pk_fma_f32 v[232:233], v[12:13], v[224:225], v[232:233]
	v_pk_fma_f32 v[234:235], v[12:13], v[226:227], v[234:235]
	v_cvt_scalef32_pk_f32_fp4 v[224:225], v161, 1.0
	v_cvt_scalef32_pk_f32_fp4 v[226:227], v165, 1.0
	v_pk_fma_f32 v[232:233], v[14:15], v[228:229], v[232:233]
	v_pk_fma_f32 v[234:235], v[14:15], v[230:231], v[234:235]
	v_cvt_scalef32_pk_f32_fp4 v[228:229], v161, 1.0 op_sel:[1,0,0]
	v_cvt_scalef32_pk_f32_fp4 v[230:231], v165, 1.0 op_sel:[1,0,0]
	v_pk_fma_f32 v[232:233], v[4:5], v[224:225], v[232:233]
	v_pk_fma_f32 v[234:235], v[4:5], v[226:227], v[234:235]
	v_cvt_scalef32_pk_f32_fp4 v[224:225], v161, 1.0 op_sel:[0,1,0]
	v_cvt_scalef32_pk_f32_fp4 v[226:227], v165, 1.0 op_sel:[0,1,0]
	v_pk_fma_f32 v[232:233], v[6:7], v[228:229], v[232:233]
	v_pk_fma_f32 v[234:235], v[6:7], v[230:231], v[234:235]
	v_cvt_scalef32_pk_f32_fp4 v[228:229], v161, 1.0 op_sel:[1,1,0]
	v_cvt_scalef32_pk_f32_fp4 v[230:231], v165, 1.0 op_sel:[1,1,0]
	v_pk_fma_f32 v[232:233], v[0:1], v[224:225], v[232:233]
	v_pk_fma_f32 v[234:235], v[0:1], v[226:227], v[234:235]
	v_cvt_scalef32_pk_f32_fp4 v[224:225], v162, 1.0
	v_cvt_scalef32_pk_f32_fp4 v[226:227], v166, 1.0
	v_pk_fma_f32 v[232:233], v[2:3], v[228:229], v[232:233]
	v_pk_fma_f32 v[234:235], v[2:3], v[230:231], v[234:235]
	v_cvt_scalef32_pk_f32_fp4 v[228:229], v162, 1.0 op_sel:[1,0,0]
	v_cvt_scalef32_pk_f32_fp4 v[230:231], v166, 1.0 op_sel:[1,0,0]
	v_pk_fma_f32 v[232:233], v[28:29], v[224:225], v[232:233]
	v_pk_fma_f32 v[234:235], v[28:29], v[226:227], v[234:235]
	v_cvt_scalef32_pk_f32_fp4 v[224:225], v162, 1.0 op_sel:[0,1,0]
	v_cvt_scalef32_pk_f32_fp4 v[226:227], v166, 1.0 op_sel:[0,1,0]
	v_pk_fma_f32 v[232:233], v[30:31], v[228:229], v[232:233]
	v_pk_fma_f32 v[234:235], v[30:31], v[230:231], v[234:235]
	v_cvt_scalef32_pk_f32_fp4 v[228:229], v162, 1.0 op_sel:[1,1,0]
	v_cvt_scalef32_pk_f32_fp4 v[230:231], v166, 1.0 op_sel:[1,1,0]
	v_pk_fma_f32 v[232:233], v[16:17], v[224:225], v[232:233]
	v_pk_fma_f32 v[234:235], v[16:17], v[226:227], v[234:235]
	v_cvt_scalef32_pk_f32_fp4 v[224:225], v163, 1.0
	v_cvt_scalef32_pk_f32_fp4 v[226:227], v167, 1.0
	v_pk_fma_f32 v[232:233], v[18:19], v[228:229], v[232:233]
	v_pk_fma_f32 v[234:235], v[18:19], v[230:231], v[234:235]
	v_cvt_scalef32_pk_f32_fp4 v[228:229], v163, 1.0 op_sel:[1,0,0]
	v_cvt_scalef32_pk_f32_fp4 v[230:231], v167, 1.0 op_sel:[1,0,0]
	v_pk_fma_f32 v[232:233], v[8:9], v[224:225], v[232:233]
	v_pk_fma_f32 v[234:235], v[8:9], v[226:227], v[234:235]
	v_cvt_scalef32_pk_f32_fp4 v[224:225], v163, 1.0 op_sel:[0,1,0]
	v_cvt_scalef32_pk_f32_fp4 v[226:227], v167, 1.0 op_sel:[0,1,0]
	v_pk_fma_f32 v[232:233], v[10:11], v[228:229], v[232:233]
	v_pk_fma_f32 v[234:235], v[10:11], v[230:231], v[234:235]
	v_cvt_scalef32_pk_f32_fp4 v[228:229], v163, 1.0 op_sel:[1,1,0]
	v_cvt_scalef32_pk_f32_fp4 v[230:231], v167, 1.0 op_sel:[1,1,0]
	v_pk_fma_f32 v[232:233], v[20:21], v[224:225], v[232:233]
	v_pk_fma_f32 v[234:235], v[20:21], v[226:227], v[234:235]
	v_pk_fma_f32 v[232:233], v[22:23], v[228:229], v[232:233]
	v_pk_fma_f32 v[234:235], v[22:23], v[230:231], v[234:235]
	v_add_f32_e32 v32, v232, v233
	v_add_f32_e32 v33, v234, v235
	s_waitcnt vmcnt(12)
	v_cvt_scalef32_pk_f32_fp4 v[224:225], v168, 1.0
	v_cvt_scalef32_pk_f32_fp4 v[226:227], v172, 1.0
	v_cvt_scalef32_pk_f32_fp4 v[228:229], v168, 1.0 op_sel:[1,0,0]
	v_cvt_scalef32_pk_f32_fp4 v[230:231], v172, 1.0 op_sel:[1,0,0]
	v_pk_fma_f32 v[236:237], v[24:25], v[224:225], 0 op_sel_hi:[1,1,0]
	v_pk_fma_f32 v[238:239], v[24:25], v[226:227], 0 op_sel_hi:[1,1,0]
	v_cvt_scalef32_pk_f32_fp4 v[224:225], v168, 1.0 op_sel:[0,1,0]
	v_cvt_scalef32_pk_f32_fp4 v[226:227], v172, 1.0 op_sel:[0,1,0]
	v_pk_fma_f32 v[236:237], v[26:27], v[228:229], v[236:237]
	v_pk_fma_f32 v[238:239], v[26:27], v[230:231], v[238:239]
	v_cvt_scalef32_pk_f32_fp4 v[228:229], v168, 1.0 op_sel:[1,1,0]
	v_cvt_scalef32_pk_f32_fp4 v[230:231], v172, 1.0 op_sel:[1,1,0]
	v_pk_fma_f32 v[236:237], v[12:13], v[224:225], v[236:237]
	v_pk_fma_f32 v[238:239], v[12:13], v[226:227], v[238:239]
	v_cvt_scalef32_pk_f32_fp4 v[224:225], v169, 1.0
	v_cvt_scalef32_pk_f32_fp4 v[226:227], v173, 1.0
	v_pk_fma_f32 v[236:237], v[14:15], v[228:229], v[236:237]
	v_pk_fma_f32 v[238:239], v[14:15], v[230:231], v[238:239]
	v_cvt_scalef32_pk_f32_fp4 v[228:229], v169, 1.0 op_sel:[1,0,0]
	v_cvt_scalef32_pk_f32_fp4 v[230:231], v173, 1.0 op_sel:[1,0,0]
	v_pk_fma_f32 v[236:237], v[4:5], v[224:225], v[236:237]
	v_pk_fma_f32 v[238:239], v[4:5], v[226:227], v[238:239]
	v_cvt_scalef32_pk_f32_fp4 v[224:225], v169, 1.0 op_sel:[0,1,0]
	v_cvt_scalef32_pk_f32_fp4 v[226:227], v173, 1.0 op_sel:[0,1,0]
	v_pk_fma_f32 v[236:237], v[6:7], v[228:229], v[236:237]
	v_pk_fma_f32 v[238:239], v[6:7], v[230:231], v[238:239]
	v_cvt_scalef32_pk_f32_fp4 v[228:229], v169, 1.0 op_sel:[1,1,0]
	v_cvt_scalef32_pk_f32_fp4 v[230:231], v173, 1.0 op_sel:[1,1,0]
	v_pk_fma_f32 v[236:237], v[0:1], v[224:225], v[236:237]
	v_pk_fma_f32 v[238:239], v[0:1], v[226:227], v[238:239]
	v_cvt_scalef32_pk_f32_fp4 v[224:225], v170, 1.0
	v_cvt_scalef32_pk_f32_fp4 v[226:227], v174, 1.0
	v_pk_fma_f32 v[236:237], v[2:3], v[228:229], v[236:237]
	v_pk_fma_f32 v[238:239], v[2:3], v[230:231], v[238:239]
	v_cvt_scalef32_pk_f32_fp4 v[228:229], v170, 1.0 op_sel:[1,0,0]
	v_cvt_scalef32_pk_f32_fp4 v[230:231], v174, 1.0 op_sel:[1,0,0]
	v_pk_fma_f32 v[236:237], v[28:29], v[224:225], v[236:237]
	v_pk_fma_f32 v[238:239], v[28:29], v[226:227], v[238:239]
	v_cvt_scalef32_pk_f32_fp4 v[224:225], v170, 1.0 op_sel:[0,1,0]
	v_cvt_scalef32_pk_f32_fp4 v[226:227], v174, 1.0 op_sel:[0,1,0]
	v_pk_fma_f32 v[236:237], v[30:31], v[228:229], v[236:237]
	v_pk_fma_f32 v[238:239], v[30:31], v[230:231], v[238:239]
	v_cvt_scalef32_pk_f32_fp4 v[228:229], v170, 1.0 op_sel:[1,1,0]
	v_cvt_scalef32_pk_f32_fp4 v[230:231], v174, 1.0 op_sel:[1,1,0]
	v_pk_fma_f32 v[236:237], v[16:17], v[224:225], v[236:237]
	v_pk_fma_f32 v[238:239], v[16:17], v[226:227], v[238:239]
	v_cvt_scalef32_pk_f32_fp4 v[224:225], v171, 1.0
	v_cvt_scalef32_pk_f32_fp4 v[226:227], v175, 1.0
	v_pk_fma_f32 v[236:237], v[18:19], v[228:229], v[236:237]
	v_pk_fma_f32 v[238:239], v[18:19], v[230:231], v[238:239]
	v_cvt_scalef32_pk_f32_fp4 v[228:229], v171, 1.0 op_sel:[1,0,0]
	v_cvt_scalef32_pk_f32_fp4 v[230:231], v175, 1.0 op_sel:[1,0,0]
	v_pk_fma_f32 v[236:237], v[8:9], v[224:225], v[236:237]
	v_pk_fma_f32 v[238:239], v[8:9], v[226:227], v[238:239]
	v_cvt_scalef32_pk_f32_fp4 v[224:225], v171, 1.0 op_sel:[0,1,0]
	v_cvt_scalef32_pk_f32_fp4 v[226:227], v175, 1.0 op_sel:[0,1,0]
	v_pk_fma_f32 v[236:237], v[10:11], v[228:229], v[236:237]
	v_pk_fma_f32 v[238:239], v[10:11], v[230:231], v[238:239]
	v_cvt_scalef32_pk_f32_fp4 v[228:229], v171, 1.0 op_sel:[1,1,0]
	v_cvt_scalef32_pk_f32_fp4 v[230:231], v175, 1.0 op_sel:[1,1,0]
	v_pk_fma_f32 v[236:237], v[20:21], v[224:225], v[236:237]
	v_pk_fma_f32 v[238:239], v[20:21], v[226:227], v[238:239]
	v_pk_fma_f32 v[236:237], v[22:23], v[228:229], v[236:237]
	v_pk_fma_f32 v[238:239], v[22:23], v[230:231], v[238:239]
	v_add_f32_e32 v34, v236, v237
	v_add_f32_e32 v35, v238, v239
	s_nop 1
	v_permlane16_swap_b32_e32 v32, v34
	v_permlane16_swap_b32_e32 v33, v35
	v_add_f32_e32 v36, v32, v34
	v_add_f32_e32 v38, v33, v35
	s_waitcnt lgkmcnt(0)
	v_cndmask_b32_e64 v40, v38, v36, s[4:5]
	v_cndmask_b32_e64 v41, v36, v38, s[4:5]
	s_nop 1
	v_add_f32_dpp v40, v41, v40 row_ror:8 row_mask:0xf bank_mask:0xf
	s_nop 1
	v_add_f32_dpp v40, v40, v40 quad_perm:[1,0,3,2] row_mask:0xf bank_mask:0xf
	s_nop 1
	v_add_f32_dpp v40, v40, v40 quad_perm:[2,3,0,1] row_mask:0xf bank_mask:0xf
	s_nop 1
	v_add_f32_dpp v40, v40, v40 row_half_mirror row_mask:0xf bank_mask:0xf
	v_mul_f32_e32 v42, v40, v156
	v_fma_f32 v43, |v42|, s19, 1.0
	v_rcp_f32_e32 v43, v43
	v_cmp_gt_f32_e64 s[8:9], 0, v42
	v_mul_f32_e32 v45, v42, v42
	v_fmamk_f32 v44, v43, 0x3f07dc22, v145
	v_fmaak_f32 v44, v43, v44, 0x3f35f0e3
	v_fmaak_f32 v44, v43, v44, 0xbe11a98e
	v_fmaak_f32 v44, v43, v44, 0x3e027906
	v_mul_f32_e32 v45, 0xbf38aa3b, v45
	v_exp_f32_e32 v45, v45
	v_mul_f32_e32 v43, v43, v44
	v_mul_f32_e32 v43, v45, v43
	v_mul_f32_e32 v44, v42, v43
	v_fma_f32 v42, -v42, v43, v42
	v_cndmask_b32_e64 v42, v42, v44, s[8:9]
	v_mul_f32_e32 v158, v42, v157
	ds_bpermute_b32 v118, v141, v158
	ds_bpermute_b32 v120, v142, v158
	ds_bpermute_b32 v122, v143, v158
	ds_bpermute_b32 v124, v144, v158
	s_waitcnt vmcnt(11)
	v_cvt_scalef32_pk_f32_fp4 v[224:225], v176, 1.0
	v_cvt_scalef32_pk_f32_fp4 v[226:227], v176, 1.0 op_sel:[1,0,0]
	s_waitcnt lgkmcnt(0)
	v_cvt_scalef32_pk_f32_fp4 v[228:229], v176, 1.0 op_sel:[0,1,0]
	v_pk_fma_f32 v[114:115], v[224:225], v[118:119], v[114:115] op_sel_hi:[1,0,1]
	v_cvt_scalef32_pk_f32_fp4 v[230:231], v176, 1.0 op_sel:[1,1,0]
	v_pk_fma_f32 v[110:111], v[226:227], v[118:119], v[110:111] op_sel_hi:[1,0,1]
	v_cvt_scalef32_pk_f32_fp4 v[224:225], v177, 1.0
	v_pk_fma_f32 v[102:103], v[228:229], v[118:119], v[102:103] op_sel_hi:[1,0,1]
	v_cvt_scalef32_pk_f32_fp4 v[226:227], v177, 1.0 op_sel:[1,0,0]
	v_pk_fma_f32 v[100:101], v[230:231], v[118:119], v[100:101] op_sel_hi:[1,0,1]
	v_cvt_scalef32_pk_f32_fp4 v[228:229], v177, 1.0 op_sel:[0,1,0]
	v_pk_fma_f32 v[54:55], v[224:225], v[118:119], v[54:55] op_sel_hi:[1,0,1]
	v_cvt_scalef32_pk_f32_fp4 v[230:231], v177, 1.0 op_sel:[1,1,0]
	v_pk_fma_f32 v[58:59], v[226:227], v[118:119], v[58:59] op_sel_hi:[1,0,1]
	v_cvt_scalef32_pk_f32_fp4 v[224:225], v178, 1.0
	v_pk_fma_f32 v[52:53], v[228:229], v[118:119], v[52:53] op_sel_hi:[1,0,1]
	v_cvt_scalef32_pk_f32_fp4 v[226:227], v178, 1.0 op_sel:[1,0,0]
	v_pk_fma_f32 v[48:49], v[230:231], v[118:119], v[48:49] op_sel_hi:[1,0,1]
	v_cvt_scalef32_pk_f32_fp4 v[228:229], v178, 1.0 op_sel:[0,1,0]
	v_pk_fma_f32 v[108:109], v[224:225], v[118:119], v[108:109] op_sel_hi:[1,0,1]
	v_cvt_scalef32_pk_f32_fp4 v[230:231], v178, 1.0 op_sel:[1,1,0]
	v_pk_fma_f32 v[106:107], v[226:227], v[118:119], v[106:107] op_sel_hi:[1,0,1]
	v_cvt_scalef32_pk_f32_fp4 v[224:225], v179, 1.0
	v_pk_fma_f32 v[98:99], v[228:229], v[118:119], v[98:99] op_sel_hi:[1,0,1]
	v_cvt_scalef32_pk_f32_fp4 v[226:227], v179, 1.0 op_sel:[1,0,0]
	v_pk_fma_f32 v[56:57], v[230:231], v[118:119], v[56:57] op_sel_hi:[1,0,1]
	v_cvt_scalef32_pk_f32_fp4 v[228:229], v179, 1.0 op_sel:[0,1,0]
	v_pk_fma_f32 v[50:51], v[224:225], v[118:119], v[50:51] op_sel_hi:[1,0,1]
	v_cvt_scalef32_pk_f32_fp4 v[230:231], v179, 1.0 op_sel:[1,1,0]
	v_pk_fma_f32 v[116:117], v[226:227], v[118:119], v[116:117] op_sel_hi:[1,0,1]
	v_pk_fma_f32 v[112:113], v[228:229], v[118:119], v[112:113] op_sel_hi:[1,0,1]
	v_pk_fma_f32 v[104:105], v[230:231], v[118:119], v[104:105] op_sel_hi:[1,0,1]
	s_waitcnt vmcnt(10)
	v_cvt_scalef32_pk_f32_fp4 v[224:225], v180, 1.0
	v_cvt_scalef32_pk_f32_fp4 v[226:227], v180, 1.0 op_sel:[1,0,0]
	v_cvt_scalef32_pk_f32_fp4 v[228:229], v180, 1.0 op_sel:[0,1,0]
	v_pk_fma_f32 v[114:115], v[224:225], v[120:121], v[114:115] op_sel_hi:[1,0,1]
	v_cvt_scalef32_pk_f32_fp4 v[230:231], v180, 1.0 op_sel:[1,1,0]
	v_pk_fma_f32 v[110:111], v[226:227], v[120:121], v[110:111] op_sel_hi:[1,0,1]
	v_cvt_scalef32_pk_f32_fp4 v[224:225], v181, 1.0
	v_pk_fma_f32 v[102:103], v[228:229], v[120:121], v[102:103] op_sel_hi:[1,0,1]
	v_cvt_scalef32_pk_f32_fp4 v[226:227], v181, 1.0 op_sel:[1,0,0]
	v_pk_fma_f32 v[100:101], v[230:231], v[120:121], v[100:101] op_sel_hi:[1,0,1]
	v_cvt_scalef32_pk_f32_fp4 v[228:229], v181, 1.0 op_sel:[0,1,0]
	v_pk_fma_f32 v[54:55], v[224:225], v[120:121], v[54:55] op_sel_hi:[1,0,1]
	v_cvt_scalef32_pk_f32_fp4 v[230:231], v181, 1.0 op_sel:[1,1,0]
	v_pk_fma_f32 v[58:59], v[226:227], v[120:121], v[58:59] op_sel_hi:[1,0,1]
	v_cvt_scalef32_pk_f32_fp4 v[224:225], v182, 1.0
	v_pk_fma_f32 v[52:53], v[228:229], v[120:121], v[52:53] op_sel_hi:[1,0,1]
	v_cvt_scalef32_pk_f32_fp4 v[226:227], v182, 1.0 op_sel:[1,0,0]
	v_pk_fma_f32 v[48:49], v[230:231], v[120:121], v[48:49] op_sel_hi:[1,0,1]
	v_cvt_scalef32_pk_f32_fp4 v[228:229], v182, 1.0 op_sel:[0,1,0]
	v_pk_fma_f32 v[108:109], v[224:225], v[120:121], v[108:109] op_sel_hi:[1,0,1]
	v_cvt_scalef32_pk_f32_fp4 v[230:231], v182, 1.0 op_sel:[1,1,0]
	v_pk_fma_f32 v[106:107], v[226:227], v[120:121], v[106:107] op_sel_hi:[1,0,1]
	v_cvt_scalef32_pk_f32_fp4 v[224:225], v183, 1.0
	v_pk_fma_f32 v[98:99], v[228:229], v[120:121], v[98:99] op_sel_hi:[1,0,1]
	v_cvt_scalef32_pk_f32_fp4 v[226:227], v183, 1.0 op_sel:[1,0,0]
	v_pk_fma_f32 v[56:57], v[230:231], v[120:121], v[56:57] op_sel_hi:[1,0,1]
	v_cvt_scalef32_pk_f32_fp4 v[228:229], v183, 1.0 op_sel:[0,1,0]
	v_pk_fma_f32 v[50:51], v[224:225], v[120:121], v[50:51] op_sel_hi:[1,0,1]
	v_cvt_scalef32_pk_f32_fp4 v[230:231], v183, 1.0 op_sel:[1,1,0]
	v_pk_fma_f32 v[116:117], v[226:227], v[120:121], v[116:117] op_sel_hi:[1,0,1]
	v_pk_fma_f32 v[112:113], v[228:229], v[120:121], v[112:113] op_sel_hi:[1,0,1]
	v_pk_fma_f32 v[104:105], v[230:231], v[120:121], v[104:105] op_sel_hi:[1,0,1]
	s_waitcnt vmcnt(9)
	v_cvt_scalef32_pk_f32_fp4 v[224:225], v184, 1.0
	v_cvt_scalef32_pk_f32_fp4 v[226:227], v184, 1.0 op_sel:[1,0,0]
	v_cvt_scalef32_pk_f32_fp4 v[228:229], v184, 1.0 op_sel:[0,1,0]
	v_pk_fma_f32 v[114:115], v[224:225], v[122:123], v[114:115] op_sel_hi:[1,0,1]
	v_cvt_scalef32_pk_f32_fp4 v[230:231], v184, 1.0 op_sel:[1,1,0]
	v_pk_fma_f32 v[110:111], v[226:227], v[122:123], v[110:111] op_sel_hi:[1,0,1]
	v_cvt_scalef32_pk_f32_fp4 v[224:225], v185, 1.0
	v_pk_fma_f32 v[102:103], v[228:229], v[122:123], v[102:103] op_sel_hi:[1,0,1]
	v_cvt_scalef32_pk_f32_fp4 v[226:227], v185, 1.0 op_sel:[1,0,0]
	v_pk_fma_f32 v[100:101], v[230:231], v[122:123], v[100:101] op_sel_hi:[1,0,1]
	v_cvt_scalef32_pk_f32_fp4 v[228:229], v185, 1.0 op_sel:[0,1,0]
	v_pk_fma_f32 v[54:55], v[224:225], v[122:123], v[54:55] op_sel_hi:[1,0,1]
	v_cvt_scalef32_pk_f32_fp4 v[230:231], v185, 1.0 op_sel:[1,1,0]
	v_pk_fma_f32 v[58:59], v[226:227], v[122:123], v[58:59] op_sel_hi:[1,0,1]
	v_cvt_scalef32_pk_f32_fp4 v[224:225], v186, 1.0
	v_pk_fma_f32 v[52:53], v[228:229], v[122:123], v[52:53] op_sel_hi:[1,0,1]
	v_cvt_scalef32_pk_f32_fp4 v[226:227], v186, 1.0 op_sel:[1,0,0]
	v_pk_fma_f32 v[48:49], v[230:231], v[122:123], v[48:49] op_sel_hi:[1,0,1]
	v_cvt_scalef32_pk_f32_fp4 v[228:229], v186, 1.0 op_sel:[0,1,0]
	v_pk_fma_f32 v[108:109], v[224:225], v[122:123], v[108:109] op_sel_hi:[1,0,1]
	v_cvt_scalef32_pk_f32_fp4 v[230:231], v186, 1.0 op_sel:[1,1,0]
	v_pk_fma_f32 v[106:107], v[226:227], v[122:123], v[106:107] op_sel_hi:[1,0,1]
	v_cvt_scalef32_pk_f32_fp4 v[224:225], v187, 1.0
	v_pk_fma_f32 v[98:99], v[228:229], v[122:123], v[98:99] op_sel_hi:[1,0,1]
	v_cvt_scalef32_pk_f32_fp4 v[226:227], v187, 1.0 op_sel:[1,0,0]
	v_pk_fma_f32 v[56:57], v[230:231], v[122:123], v[56:57] op_sel_hi:[1,0,1]
	v_cvt_scalef32_pk_f32_fp4 v[228:229], v187, 1.0 op_sel:[0,1,0]
	v_pk_fma_f32 v[50:51], v[224:225], v[122:123], v[50:51] op_sel_hi:[1,0,1]
	v_cvt_scalef32_pk_f32_fp4 v[230:231], v187, 1.0 op_sel:[1,1,0]
	v_pk_fma_f32 v[116:117], v[226:227], v[122:123], v[116:117] op_sel_hi:[1,0,1]
	v_pk_fma_f32 v[112:113], v[228:229], v[122:123], v[112:113] op_sel_hi:[1,0,1]
	v_pk_fma_f32 v[104:105], v[230:231], v[122:123], v[104:105] op_sel_hi:[1,0,1]
	s_waitcnt vmcnt(8)
	v_cvt_scalef32_pk_f32_fp4 v[224:225], v188, 1.0
	v_cvt_scalef32_pk_f32_fp4 v[226:227], v188, 1.0 op_sel:[1,0,0]
	v_cvt_scalef32_pk_f32_fp4 v[228:229], v188, 1.0 op_sel:[0,1,0]
	v_pk_fma_f32 v[114:115], v[224:225], v[124:125], v[114:115] op_sel_hi:[1,0,1]
	v_cvt_scalef32_pk_f32_fp4 v[230:231], v188, 1.0 op_sel:[1,1,0]
	v_pk_fma_f32 v[110:111], v[226:227], v[124:125], v[110:111] op_sel_hi:[1,0,1]
	v_cvt_scalef32_pk_f32_fp4 v[224:225], v189, 1.0
	v_pk_fma_f32 v[102:103], v[228:229], v[124:125], v[102:103] op_sel_hi:[1,0,1]
	v_cvt_scalef32_pk_f32_fp4 v[226:227], v189, 1.0 op_sel:[1,0,0]
	v_pk_fma_f32 v[100:101], v[230:231], v[124:125], v[100:101] op_sel_hi:[1,0,1]
	v_cvt_scalef32_pk_f32_fp4 v[228:229], v189, 1.0 op_sel:[0,1,0]
	v_pk_fma_f32 v[54:55], v[224:225], v[124:125], v[54:55] op_sel_hi:[1,0,1]
	v_cvt_scalef32_pk_f32_fp4 v[230:231], v189, 1.0 op_sel:[1,1,0]
	v_pk_fma_f32 v[58:59], v[226:227], v[124:125], v[58:59] op_sel_hi:[1,0,1]
	v_cvt_scalef32_pk_f32_fp4 v[224:225], v190, 1.0
	v_pk_fma_f32 v[52:53], v[228:229], v[124:125], v[52:53] op_sel_hi:[1,0,1]
	v_cvt_scalef32_pk_f32_fp4 v[226:227], v190, 1.0 op_sel:[1,0,0]
	v_pk_fma_f32 v[48:49], v[230:231], v[124:125], v[48:49] op_sel_hi:[1,0,1]
	v_cvt_scalef32_pk_f32_fp4 v[228:229], v190, 1.0 op_sel:[0,1,0]
	v_pk_fma_f32 v[108:109], v[224:225], v[124:125], v[108:109] op_sel_hi:[1,0,1]
	v_cvt_scalef32_pk_f32_fp4 v[230:231], v190, 1.0 op_sel:[1,1,0]
	v_pk_fma_f32 v[106:107], v[226:227], v[124:125], v[106:107] op_sel_hi:[1,0,1]
	v_cvt_scalef32_pk_f32_fp4 v[224:225], v191, 1.0
	v_pk_fma_f32 v[98:99], v[228:229], v[124:125], v[98:99] op_sel_hi:[1,0,1]
	v_cvt_scalef32_pk_f32_fp4 v[226:227], v191, 1.0 op_sel:[1,0,0]
	v_pk_fma_f32 v[56:57], v[230:231], v[124:125], v[56:57] op_sel_hi:[1,0,1]
	v_cvt_scalef32_pk_f32_fp4 v[228:229], v191, 1.0 op_sel:[0,1,0]
	v_pk_fma_f32 v[50:51], v[224:225], v[124:125], v[50:51] op_sel_hi:[1,0,1]
	v_cvt_scalef32_pk_f32_fp4 v[230:231], v191, 1.0 op_sel:[1,1,0]
	v_pk_fma_f32 v[116:117], v[226:227], v[124:125], v[116:117] op_sel_hi:[1,0,1]
	v_pk_fma_f32 v[112:113], v[228:229], v[124:125], v[112:113] op_sel_hi:[1,0,1]
	v_pk_fma_f32 v[104:105], v[230:231], v[124:125], v[104:105] op_sel_hi:[1,0,1]
	s_waitcnt lgkmcnt(0)
	v_lshl_add_u32 v250, v240, 9, v241
	v_lshl_add_u32 v251, v242, 9, v241
	v_lshl_add_u32 v252, v246, 9, v241
	v_lshl_add_u32 v253, v248, 9, v241
	global_load_dwordx4 v[160:163], v250, s[98:99]
	global_load_dwordx4 v[164:167], v251, s[98:99]
	global_load_dwordx4 v[168:171], v252, s[98:99]
	global_load_dwordx4 v[172:175], v253, s[98:99]
	global_load_dwordx4 v[176:179], v250, s[100:101]
	global_load_dwordx4 v[180:183], v251, s[100:101]
	global_load_dwordx4 v[184:187], v252, s[100:101]
	global_load_dwordx4 v[188:191], v253, s[100:101]
	s_add_u32 s23, s22, 3
	s_cmp_lt_u32 s23, 8
	s_cselect_b64 s[8:9], -1, 0
	s_and_b32 s23, s23, 7
	s_lshl_b32 s23, s23, 5
	v_cndmask_b32_e64 v126, v96, v94, s[8:9]
	v_lshl_add_u32 v129, v139, 2, s23
	ds_bpermute_b32 v240, v129, v126
	ds_bpermute_b32 v242, v129, v126 offset:8
	ds_bpermute_b32 v246, v129, v126 offset:16
	ds_bpermute_b32 v248, v129, v126 offset:24
	s_add_u32 s23, s22, 1
	s_cmp_lt_u32 s23, 8
	s_cselect_b64 s[8:9], -1, 0
	s_and_b32 s23, s23, 7
	s_lshl_b32 s23, s23, 5
	v_cndmask_b32_e64 v127, v150, v149, s[8:9]
	v_cndmask_b32_e64 v128, v152, v151, s[8:9]
	v_lshl_add_u32 v130, v140, 2, s23
	ds_bpermute_b32 v156, v130, v127
	ds_bpermute_b32 v157, v130, v128
	s_waitcnt vmcnt(14)
	v_cvt_scalef32_pk_f32_fp4 v[224:225], v192, 1.0
	v_cvt_scalef32_pk_f32_fp4 v[226:227], v196, 1.0
	v_cvt_scalef32_pk_f32_fp4 v[228:229], v192, 1.0 op_sel:[1,0,0]
	v_cvt_scalef32_pk_f32_fp4 v[230:231], v196, 1.0 op_sel:[1,0,0]
	v_pk_fma_f32 v[232:233], v[24:25], v[224:225], 0 op_sel_hi:[1,1,0]
	v_pk_fma_f32 v[234:235], v[24:25], v[226:227], 0 op_sel_hi:[1,1,0]
	v_cvt_scalef32_pk_f32_fp4 v[224:225], v192, 1.0 op_sel:[0,1,0]
	v_cvt_scalef32_pk_f32_fp4 v[226:227], v196, 1.0 op_sel:[0,1,0]
	v_pk_fma_f32 v[232:233], v[26:27], v[228:229], v[232:233]
	v_pk_fma_f32 v[234:235], v[26:27], v[230:231], v[234:235]
	v_cvt_scalef32_pk_f32_fp4 v[228:229], v192, 1.0 op_sel:[1,1,0]
	v_cvt_scalef32_pk_f32_fp4 v[230:231], v196, 1.0 op_sel:[1,1,0]
	v_pk_fma_f32 v[232:233], v[12:13], v[224:225], v[232:233]
	v_pk_fma_f32 v[234:235], v[12:13], v[226:227], v[234:235]
	v_cvt_scalef32_pk_f32_fp4 v[224:225], v193, 1.0
	v_cvt_scalef32_pk_f32_fp4 v[226:227], v197, 1.0
	v_pk_fma_f32 v[232:233], v[14:15], v[228:229], v[232:233]
	v_pk_fma_f32 v[234:235], v[14:15], v[230:231], v[234:235]
	v_cvt_scalef32_pk_f32_fp4 v[228:229], v193, 1.0 op_sel:[1,0,0]
	v_cvt_scalef32_pk_f32_fp4 v[230:231], v197, 1.0 op_sel:[1,0,0]
	v_pk_fma_f32 v[232:233], v[4:5], v[224:225], v[232:233]
	v_pk_fma_f32 v[234:235], v[4:5], v[226:227], v[234:235]
	v_cvt_scalef32_pk_f32_fp4 v[224:225], v193, 1.0 op_sel:[0,1,0]
	v_cvt_scalef32_pk_f32_fp4 v[226:227], v197, 1.0 op_sel:[0,1,0]
	v_pk_fma_f32 v[232:233], v[6:7], v[228:229], v[232:233]
	v_pk_fma_f32 v[234:235], v[6:7], v[230:231], v[234:235]
	v_cvt_scalef32_pk_f32_fp4 v[228:229], v193, 1.0 op_sel:[1,1,0]
	v_cvt_scalef32_pk_f32_fp4 v[230:231], v197, 1.0 op_sel:[1,1,0]
	v_pk_fma_f32 v[232:233], v[0:1], v[224:225], v[232:233]
	v_pk_fma_f32 v[234:235], v[0:1], v[226:227], v[234:235]
	v_cvt_scalef32_pk_f32_fp4 v[224:225], v194, 1.0
	v_cvt_scalef32_pk_f32_fp4 v[226:227], v198, 1.0
	v_pk_fma_f32 v[232:233], v[2:3], v[228:229], v[232:233]
	v_pk_fma_f32 v[234:235], v[2:3], v[230:231], v[234:235]
	v_cvt_scalef32_pk_f32_fp4 v[228:229], v194, 1.0 op_sel:[1,0,0]
	v_cvt_scalef32_pk_f32_fp4 v[230:231], v198, 1.0 op_sel:[1,0,0]
	v_pk_fma_f32 v[232:233], v[28:29], v[224:225], v[232:233]
	v_pk_fma_f32 v[234:235], v[28:29], v[226:227], v[234:235]
	v_cvt_scalef32_pk_f32_fp4 v[224:225], v194, 1.0 op_sel:[0,1,0]
	v_cvt_scalef32_pk_f32_fp4 v[226:227], v198, 1.0 op_sel:[0,1,0]
	v_pk_fma_f32 v[232:233], v[30:31], v[228:229], v[232:233]
	v_pk_fma_f32 v[234:235], v[30:31], v[230:231], v[234:235]
	v_cvt_scalef32_pk_f32_fp4 v[228:229], v194, 1.0 op_sel:[1,1,0]
	v_cvt_scalef32_pk_f32_fp4 v[230:231], v198, 1.0 op_sel:[1,1,0]
	v_pk_fma_f32 v[232:233], v[16:17], v[224:225], v[232:233]
	v_pk_fma_f32 v[234:235], v[16:17], v[226:227], v[234:235]
	v_cvt_scalef32_pk_f32_fp4 v[224:225], v195, 1.0
	v_cvt_scalef32_pk_f32_fp4 v[226:227], v199, 1.0
	v_pk_fma_f32 v[232:233], v[18:19], v[228:229], v[232:233]
	v_pk_fma_f32 v[234:235], v[18:19], v[230:231], v[234:235]
	v_cvt_scalef32_pk_f32_fp4 v[228:229], v195, 1.0 op_sel:[1,0,0]
	v_cvt_scalef32_pk_f32_fp4 v[230:231], v199, 1.0 op_sel:[1,0,0]
	v_pk_fma_f32 v[232:233], v[8:9], v[224:225], v[232:233]
	v_pk_fma_f32 v[234:235], v[8:9], v[226:227], v[234:235]
	v_cvt_scalef32_pk_f32_fp4 v[224:225], v195, 1.0 op_sel:[0,1,0]
	v_cvt_scalef32_pk_f32_fp4 v[226:227], v199, 1.0 op_sel:[0,1,0]
	v_pk_fma_f32 v[232:233], v[10:11], v[228:229], v[232:233]
	v_pk_fma_f32 v[234:235], v[10:11], v[230:231], v[234:235]
	v_cvt_scalef32_pk_f32_fp4 v[228:229], v195, 1.0 op_sel:[1,1,0]
	v_cvt_scalef32_pk_f32_fp4 v[230:231], v199, 1.0 op_sel:[1,1,0]
	v_pk_fma_f32 v[232:233], v[20:21], v[224:225], v[232:233]
	v_pk_fma_f32 v[234:235], v[20:21], v[226:227], v[234:235]
	v_pk_fma_f32 v[232:233], v[22:23], v[228:229], v[232:233]
	v_pk_fma_f32 v[234:235], v[22:23], v[230:231], v[234:235]
	v_add_f32_e32 v32, v232, v233
	v_add_f32_e32 v33, v234, v235
	s_waitcnt vmcnt(12)
	v_cvt_scalef32_pk_f32_fp4 v[224:225], v200, 1.0
	v_cvt_scalef32_pk_f32_fp4 v[226:227], v204, 1.0
	v_cvt_scalef32_pk_f32_fp4 v[228:229], v200, 1.0 op_sel:[1,0,0]
	v_cvt_scalef32_pk_f32_fp4 v[230:231], v204, 1.0 op_sel:[1,0,0]
	v_pk_fma_f32 v[236:237], v[24:25], v[224:225], 0 op_sel_hi:[1,1,0]
	v_pk_fma_f32 v[238:239], v[24:25], v[226:227], 0 op_sel_hi:[1,1,0]
	v_cvt_scalef32_pk_f32_fp4 v[224:225], v200, 1.0 op_sel:[0,1,0]
	v_cvt_scalef32_pk_f32_fp4 v[226:227], v204, 1.0 op_sel:[0,1,0]
	v_pk_fma_f32 v[236:237], v[26:27], v[228:229], v[236:237]
	v_pk_fma_f32 v[238:239], v[26:27], v[230:231], v[238:239]
	v_cvt_scalef32_pk_f32_fp4 v[228:229], v200, 1.0 op_sel:[1,1,0]
	v_cvt_scalef32_pk_f32_fp4 v[230:231], v204, 1.0 op_sel:[1,1,0]
	v_pk_fma_f32 v[236:237], v[12:13], v[224:225], v[236:237]
	v_pk_fma_f32 v[238:239], v[12:13], v[226:227], v[238:239]
	v_cvt_scalef32_pk_f32_fp4 v[224:225], v201, 1.0
	v_cvt_scalef32_pk_f32_fp4 v[226:227], v205, 1.0
	v_pk_fma_f32 v[236:237], v[14:15], v[228:229], v[236:237]
	v_pk_fma_f32 v[238:239], v[14:15], v[230:231], v[238:239]
	v_cvt_scalef32_pk_f32_fp4 v[228:229], v201, 1.0 op_sel:[1,0,0]
	v_cvt_scalef32_pk_f32_fp4 v[230:231], v205, 1.0 op_sel:[1,0,0]
	v_pk_fma_f32 v[236:237], v[4:5], v[224:225], v[236:237]
	v_pk_fma_f32 v[238:239], v[4:5], v[226:227], v[238:239]
	v_cvt_scalef32_pk_f32_fp4 v[224:225], v201, 1.0 op_sel:[0,1,0]
	v_cvt_scalef32_pk_f32_fp4 v[226:227], v205, 1.0 op_sel:[0,1,0]
	v_pk_fma_f32 v[236:237], v[6:7], v[228:229], v[236:237]
	v_pk_fma_f32 v[238:239], v[6:7], v[230:231], v[238:239]
	v_cvt_scalef32_pk_f32_fp4 v[228:229], v201, 1.0 op_sel:[1,1,0]
	v_cvt_scalef32_pk_f32_fp4 v[230:231], v205, 1.0 op_sel:[1,1,0]
	v_pk_fma_f32 v[236:237], v[0:1], v[224:225], v[236:237]
	v_pk_fma_f32 v[238:239], v[0:1], v[226:227], v[238:239]
	v_cvt_scalef32_pk_f32_fp4 v[224:225], v202, 1.0
	v_cvt_scalef32_pk_f32_fp4 v[226:227], v206, 1.0
	v_pk_fma_f32 v[236:237], v[2:3], v[228:229], v[236:237]
	v_pk_fma_f32 v[238:239], v[2:3], v[230:231], v[238:239]
	v_cvt_scalef32_pk_f32_fp4 v[228:229], v202, 1.0 op_sel:[1,0,0]
	v_cvt_scalef32_pk_f32_fp4 v[230:231], v206, 1.0 op_sel:[1,0,0]
	v_pk_fma_f32 v[236:237], v[28:29], v[224:225], v[236:237]
	v_pk_fma_f32 v[238:239], v[28:29], v[226:227], v[238:239]
	v_cvt_scalef32_pk_f32_fp4 v[224:225], v202, 1.0 op_sel:[0,1,0]
	v_cvt_scalef32_pk_f32_fp4 v[226:227], v206, 1.0 op_sel:[0,1,0]
	v_pk_fma_f32 v[236:237], v[30:31], v[228:229], v[236:237]
	v_pk_fma_f32 v[238:239], v[30:31], v[230:231], v[238:239]
	v_cvt_scalef32_pk_f32_fp4 v[228:229], v202, 1.0 op_sel:[1,1,0]
	v_cvt_scalef32_pk_f32_fp4 v[230:231], v206, 1.0 op_sel:[1,1,0]
	v_pk_fma_f32 v[236:237], v[16:17], v[224:225], v[236:237]
	v_pk_fma_f32 v[238:239], v[16:17], v[226:227], v[238:239]
	v_cvt_scalef32_pk_f32_fp4 v[224:225], v203, 1.0
	v_cvt_scalef32_pk_f32_fp4 v[226:227], v207, 1.0
	v_pk_fma_f32 v[236:237], v[18:19], v[228:229], v[236:237]
	v_pk_fma_f32 v[238:239], v[18:19], v[230:231], v[238:239]
	v_cvt_scalef32_pk_f32_fp4 v[228:229], v203, 1.0 op_sel:[1,0,0]
	v_cvt_scalef32_pk_f32_fp4 v[230:231], v207, 1.0 op_sel:[1,0,0]
	v_pk_fma_f32 v[236:237], v[8:9], v[224:225], v[236:237]
	v_pk_fma_f32 v[238:239], v[8:9], v[226:227], v[238:239]
	v_cvt_scalef32_pk_f32_fp4 v[224:225], v203, 1.0 op_sel:[0,1,0]
	v_cvt_scalef32_pk_f32_fp4 v[226:227], v207, 1.0 op_sel:[0,1,0]
	v_pk_fma_f32 v[236:237], v[10:11], v[228:229], v[236:237]
	v_pk_fma_f32 v[238:239], v[10:11], v[230:231], v[238:239]
	v_cvt_scalef32_pk_f32_fp4 v[228:229], v203, 1.0 op_sel:[1,1,0]
	v_cvt_scalef32_pk_f32_fp4 v[230:231], v207, 1.0 op_sel:[1,1,0]
	v_pk_fma_f32 v[236:237], v[20:21], v[224:225], v[236:237]
	v_pk_fma_f32 v[238:239], v[20:21], v[226:227], v[238:239]
	v_pk_fma_f32 v[236:237], v[22:23], v[228:229], v[236:237]
	v_pk_fma_f32 v[238:239], v[22:23], v[230:231], v[238:239]
	v_add_f32_e32 v34, v236, v237
	v_add_f32_e32 v35, v238, v239
	s_nop 1
	v_permlane16_swap_b32_e32 v32, v34
	v_permlane16_swap_b32_e32 v33, v35
	v_add_f32_e32 v36, v32, v34
	v_add_f32_e32 v38, v33, v35
	s_waitcnt lgkmcnt(0)
	v_cndmask_b32_e64 v40, v38, v36, s[4:5]
	v_cndmask_b32_e64 v41, v36, v38, s[4:5]
	s_nop 1
	v_add_f32_dpp v40, v41, v40 row_ror:8 row_mask:0xf bank_mask:0xf
	s_nop 1
	v_add_f32_dpp v40, v40, v40 quad_perm:[1,0,3,2] row_mask:0xf bank_mask:0xf
	s_nop 1
	v_add_f32_dpp v40, v40, v40 quad_perm:[2,3,0,1] row_mask:0xf bank_mask:0xf
	s_nop 1
	v_add_f32_dpp v40, v40, v40 row_half_mirror row_mask:0xf bank_mask:0xf
	v_mul_f32_e32 v42, v40, v156
	v_fma_f32 v43, |v42|, s19, 1.0
	v_rcp_f32_e32 v43, v43
	v_cmp_gt_f32_e64 s[8:9], 0, v42
	v_mul_f32_e32 v45, v42, v42
	v_fmamk_f32 v44, v43, 0x3f07dc22, v145
	v_fmaak_f32 v44, v43, v44, 0x3f35f0e3
	v_fmaak_f32 v44, v43, v44, 0xbe11a98e
	v_fmaak_f32 v44, v43, v44, 0x3e027906
	v_mul_f32_e32 v45, 0xbf38aa3b, v45
	v_exp_f32_e32 v45, v45
	v_mul_f32_e32 v43, v43, v44
	v_mul_f32_e32 v43, v45, v43
	v_mul_f32_e32 v44, v42, v43
	v_fma_f32 v42, -v42, v43, v42
	v_cndmask_b32_e64 v42, v42, v44, s[8:9]
	v_mul_f32_e32 v158, v42, v157
	ds_bpermute_b32 v118, v141, v158
	ds_bpermute_b32 v120, v142, v158
	ds_bpermute_b32 v122, v143, v158
	ds_bpermute_b32 v124, v144, v158
	s_waitcnt vmcnt(11)
	v_cvt_scalef32_pk_f32_fp4 v[224:225], v208, 1.0
	v_cvt_scalef32_pk_f32_fp4 v[226:227], v208, 1.0 op_sel:[1,0,0]
	s_waitcnt lgkmcnt(0)
	v_cvt_scalef32_pk_f32_fp4 v[228:229], v208, 1.0 op_sel:[0,1,0]
	v_pk_fma_f32 v[114:115], v[224:225], v[118:119], v[114:115] op_sel_hi:[1,0,1]
	v_cvt_scalef32_pk_f32_fp4 v[230:231], v208, 1.0 op_sel:[1,1,0]
	v_pk_fma_f32 v[110:111], v[226:227], v[118:119], v[110:111] op_sel_hi:[1,0,1]
	v_cvt_scalef32_pk_f32_fp4 v[224:225], v209, 1.0
	v_pk_fma_f32 v[102:103], v[228:229], v[118:119], v[102:103] op_sel_hi:[1,0,1]
	v_cvt_scalef32_pk_f32_fp4 v[226:227], v209, 1.0 op_sel:[1,0,0]
	v_pk_fma_f32 v[100:101], v[230:231], v[118:119], v[100:101] op_sel_hi:[1,0,1]
	v_cvt_scalef32_pk_f32_fp4 v[228:229], v209, 1.0 op_sel:[0,1,0]
	v_pk_fma_f32 v[54:55], v[224:225], v[118:119], v[54:55] op_sel_hi:[1,0,1]
	v_cvt_scalef32_pk_f32_fp4 v[230:231], v209, 1.0 op_sel:[1,1,0]
	v_pk_fma_f32 v[58:59], v[226:227], v[118:119], v[58:59] op_sel_hi:[1,0,1]
	v_cvt_scalef32_pk_f32_fp4 v[224:225], v210, 1.0
	v_pk_fma_f32 v[52:53], v[228:229], v[118:119], v[52:53] op_sel_hi:[1,0,1]
	v_cvt_scalef32_pk_f32_fp4 v[226:227], v210, 1.0 op_sel:[1,0,0]
	v_pk_fma_f32 v[48:49], v[230:231], v[118:119], v[48:49] op_sel_hi:[1,0,1]
	v_cvt_scalef32_pk_f32_fp4 v[228:229], v210, 1.0 op_sel:[0,1,0]
	v_pk_fma_f32 v[108:109], v[224:225], v[118:119], v[108:109] op_sel_hi:[1,0,1]
	v_cvt_scalef32_pk_f32_fp4 v[230:231], v210, 1.0 op_sel:[1,1,0]
	v_pk_fma_f32 v[106:107], v[226:227], v[118:119], v[106:107] op_sel_hi:[1,0,1]
	v_cvt_scalef32_pk_f32_fp4 v[224:225], v211, 1.0
	v_pk_fma_f32 v[98:99], v[228:229], v[118:119], v[98:99] op_sel_hi:[1,0,1]
	v_cvt_scalef32_pk_f32_fp4 v[226:227], v211, 1.0 op_sel:[1,0,0]
	v_pk_fma_f32 v[56:57], v[230:231], v[118:119], v[56:57] op_sel_hi:[1,0,1]
	v_cvt_scalef32_pk_f32_fp4 v[228:229], v211, 1.0 op_sel:[0,1,0]
	v_pk_fma_f32 v[50:51], v[224:225], v[118:119], v[50:51] op_sel_hi:[1,0,1]
	v_cvt_scalef32_pk_f32_fp4 v[230:231], v211, 1.0 op_sel:[1,1,0]
	v_pk_fma_f32 v[116:117], v[226:227], v[118:119], v[116:117] op_sel_hi:[1,0,1]
	v_pk_fma_f32 v[112:113], v[228:229], v[118:119], v[112:113] op_sel_hi:[1,0,1]
	v_pk_fma_f32 v[104:105], v[230:231], v[118:119], v[104:105] op_sel_hi:[1,0,1]
	s_waitcnt vmcnt(10)
	v_cvt_scalef32_pk_f32_fp4 v[224:225], v212, 1.0
	v_cvt_scalef32_pk_f32_fp4 v[226:227], v212, 1.0 op_sel:[1,0,0]
	v_cvt_scalef32_pk_f32_fp4 v[228:229], v212, 1.0 op_sel:[0,1,0]
	v_pk_fma_f32 v[114:115], v[224:225], v[120:121], v[114:115] op_sel_hi:[1,0,1]
	v_cvt_scalef32_pk_f32_fp4 v[230:231], v212, 1.0 op_sel:[1,1,0]
	v_pk_fma_f32 v[110:111], v[226:227], v[120:121], v[110:111] op_sel_hi:[1,0,1]
	v_cvt_scalef32_pk_f32_fp4 v[224:225], v213, 1.0
	v_pk_fma_f32 v[102:103], v[228:229], v[120:121], v[102:103] op_sel_hi:[1,0,1]
	v_cvt_scalef32_pk_f32_fp4 v[226:227], v213, 1.0 op_sel:[1,0,0]
	v_pk_fma_f32 v[100:101], v[230:231], v[120:121], v[100:101] op_sel_hi:[1,0,1]
	v_cvt_scalef32_pk_f32_fp4 v[228:229], v213, 1.0 op_sel:[0,1,0]
	v_pk_fma_f32 v[54:55], v[224:225], v[120:121], v[54:55] op_sel_hi:[1,0,1]
	v_cvt_scalef32_pk_f32_fp4 v[230:231], v213, 1.0 op_sel:[1,1,0]
	v_pk_fma_f32 v[58:59], v[226:227], v[120:121], v[58:59] op_sel_hi:[1,0,1]
	v_cvt_scalef32_pk_f32_fp4 v[224:225], v214, 1.0
	v_pk_fma_f32 v[52:53], v[228:229], v[120:121], v[52:53] op_sel_hi:[1,0,1]
	v_cvt_scalef32_pk_f32_fp4 v[226:227], v214, 1.0 op_sel:[1,0,0]
	v_pk_fma_f32 v[48:49], v[230:231], v[120:121], v[48:49] op_sel_hi:[1,0,1]
	v_cvt_scalef32_pk_f32_fp4 v[228:229], v214, 1.0 op_sel:[0,1,0]
	v_pk_fma_f32 v[108:109], v[224:225], v[120:121], v[108:109] op_sel_hi:[1,0,1]
	v_cvt_scalef32_pk_f32_fp4 v[230:231], v214, 1.0 op_sel:[1,1,0]
	v_pk_fma_f32 v[106:107], v[226:227], v[120:121], v[106:107] op_sel_hi:[1,0,1]
	v_cvt_scalef32_pk_f32_fp4 v[224:225], v215, 1.0
	v_pk_fma_f32 v[98:99], v[228:229], v[120:121], v[98:99] op_sel_hi:[1,0,1]
	v_cvt_scalef32_pk_f32_fp4 v[226:227], v215, 1.0 op_sel:[1,0,0]
	v_pk_fma_f32 v[56:57], v[230:231], v[120:121], v[56:57] op_sel_hi:[1,0,1]
	v_cvt_scalef32_pk_f32_fp4 v[228:229], v215, 1.0 op_sel:[0,1,0]
	v_pk_fma_f32 v[50:51], v[224:225], v[120:121], v[50:51] op_sel_hi:[1,0,1]
	v_cvt_scalef32_pk_f32_fp4 v[230:231], v215, 1.0 op_sel:[1,1,0]
	v_pk_fma_f32 v[116:117], v[226:227], v[120:121], v[116:117] op_sel_hi:[1,0,1]
	v_pk_fma_f32 v[112:113], v[228:229], v[120:121], v[112:113] op_sel_hi:[1,0,1]
	v_pk_fma_f32 v[104:105], v[230:231], v[120:121], v[104:105] op_sel_hi:[1,0,1]
	s_waitcnt vmcnt(9)
	v_cvt_scalef32_pk_f32_fp4 v[224:225], v216, 1.0
	v_cvt_scalef32_pk_f32_fp4 v[226:227], v216, 1.0 op_sel:[1,0,0]
	v_cvt_scalef32_pk_f32_fp4 v[228:229], v216, 1.0 op_sel:[0,1,0]
	v_pk_fma_f32 v[114:115], v[224:225], v[122:123], v[114:115] op_sel_hi:[1,0,1]
	v_cvt_scalef32_pk_f32_fp4 v[230:231], v216, 1.0 op_sel:[1,1,0]
	v_pk_fma_f32 v[110:111], v[226:227], v[122:123], v[110:111] op_sel_hi:[1,0,1]
	v_cvt_scalef32_pk_f32_fp4 v[224:225], v217, 1.0
	v_pk_fma_f32 v[102:103], v[228:229], v[122:123], v[102:103] op_sel_hi:[1,0,1]
	v_cvt_scalef32_pk_f32_fp4 v[226:227], v217, 1.0 op_sel:[1,0,0]
	v_pk_fma_f32 v[100:101], v[230:231], v[122:123], v[100:101] op_sel_hi:[1,0,1]
	v_cvt_scalef32_pk_f32_fp4 v[228:229], v217, 1.0 op_sel:[0,1,0]
	v_pk_fma_f32 v[54:55], v[224:225], v[122:123], v[54:55] op_sel_hi:[1,0,1]
	v_cvt_scalef32_pk_f32_fp4 v[230:231], v217, 1.0 op_sel:[1,1,0]
	v_pk_fma_f32 v[58:59], v[226:227], v[122:123], v[58:59] op_sel_hi:[1,0,1]
	v_cvt_scalef32_pk_f32_fp4 v[224:225], v218, 1.0
	v_pk_fma_f32 v[52:53], v[228:229], v[122:123], v[52:53] op_sel_hi:[1,0,1]
	v_cvt_scalef32_pk_f32_fp4 v[226:227], v218, 1.0 op_sel:[1,0,0]
	v_pk_fma_f32 v[48:49], v[230:231], v[122:123], v[48:49] op_sel_hi:[1,0,1]
	v_cvt_scalef32_pk_f32_fp4 v[228:229], v218, 1.0 op_sel:[0,1,0]
	v_pk_fma_f32 v[108:109], v[224:225], v[122:123], v[108:109] op_sel_hi:[1,0,1]
	v_cvt_scalef32_pk_f32_fp4 v[230:231], v218, 1.0 op_sel:[1,1,0]
	v_pk_fma_f32 v[106:107], v[226:227], v[122:123], v[106:107] op_sel_hi:[1,0,1]
	v_cvt_scalef32_pk_f32_fp4 v[224:225], v219, 1.0
	v_pk_fma_f32 v[98:99], v[228:229], v[122:123], v[98:99] op_sel_hi:[1,0,1]
	v_cvt_scalef32_pk_f32_fp4 v[226:227], v219, 1.0 op_sel:[1,0,0]
	v_pk_fma_f32 v[56:57], v[230:231], v[122:123], v[56:57] op_sel_hi:[1,0,1]
	v_cvt_scalef32_pk_f32_fp4 v[228:229], v219, 1.0 op_sel:[0,1,0]
	v_pk_fma_f32 v[50:51], v[224:225], v[122:123], v[50:51] op_sel_hi:[1,0,1]
	v_cvt_scalef32_pk_f32_fp4 v[230:231], v219, 1.0 op_sel:[1,1,0]
	v_pk_fma_f32 v[116:117], v[226:227], v[122:123], v[116:117] op_sel_hi:[1,0,1]
	v_pk_fma_f32 v[112:113], v[228:229], v[122:123], v[112:113] op_sel_hi:[1,0,1]
	v_pk_fma_f32 v[104:105], v[230:231], v[122:123], v[104:105] op_sel_hi:[1,0,1]
	s_waitcnt vmcnt(8)
	v_cvt_scalef32_pk_f32_fp4 v[224:225], v220, 1.0
	v_cvt_scalef32_pk_f32_fp4 v[226:227], v220, 1.0 op_sel:[1,0,0]
	v_cvt_scalef32_pk_f32_fp4 v[228:229], v220, 1.0 op_sel:[0,1,0]
	v_pk_fma_f32 v[114:115], v[224:225], v[124:125], v[114:115] op_sel_hi:[1,0,1]
	v_cvt_scalef32_pk_f32_fp4 v[230:231], v220, 1.0 op_sel:[1,1,0]
	v_pk_fma_f32 v[110:111], v[226:227], v[124:125], v[110:111] op_sel_hi:[1,0,1]
	v_cvt_scalef32_pk_f32_fp4 v[224:225], v221, 1.0
	v_pk_fma_f32 v[102:103], v[228:229], v[124:125], v[102:103] op_sel_hi:[1,0,1]
	v_cvt_scalef32_pk_f32_fp4 v[226:227], v221, 1.0 op_sel:[1,0,0]
	v_pk_fma_f32 v[100:101], v[230:231], v[124:125], v[100:101] op_sel_hi:[1,0,1]
	v_cvt_scalef32_pk_f32_fp4 v[228:229], v221, 1.0 op_sel:[0,1,0]
	v_pk_fma_f32 v[54:55], v[224:225], v[124:125], v[54:55] op_sel_hi:[1,0,1]
	v_cvt_scalef32_pk_f32_fp4 v[230:231], v221, 1.0 op_sel:[1,1,0]
	v_pk_fma_f32 v[58:59], v[226:227], v[124:125], v[58:59] op_sel_hi:[1,0,1]
	v_cvt_scalef32_pk_f32_fp4 v[224:225], v222, 1.0
	v_pk_fma_f32 v[52:53], v[228:229], v[124:125], v[52:53] op_sel_hi:[1,0,1]
	v_cvt_scalef32_pk_f32_fp4 v[226:227], v222, 1.0 op_sel:[1,0,0]
	v_pk_fma_f32 v[48:49], v[230:231], v[124:125], v[48:49] op_sel_hi:[1,0,1]
	v_cvt_scalef32_pk_f32_fp4 v[228:229], v222, 1.0 op_sel:[0,1,0]
	v_pk_fma_f32 v[108:109], v[224:225], v[124:125], v[108:109] op_sel_hi:[1,0,1]
	v_cvt_scalef32_pk_f32_fp4 v[230:231], v222, 1.0 op_sel:[1,1,0]
	v_pk_fma_f32 v[106:107], v[226:227], v[124:125], v[106:107] op_sel_hi:[1,0,1]
	v_cvt_scalef32_pk_f32_fp4 v[224:225], v223, 1.0
	v_pk_fma_f32 v[98:99], v[228:229], v[124:125], v[98:99] op_sel_hi:[1,0,1]
	v_cvt_scalef32_pk_f32_fp4 v[226:227], v223, 1.0 op_sel:[1,0,0]
	v_pk_fma_f32 v[56:57], v[230:231], v[124:125], v[56:57] op_sel_hi:[1,0,1]
	v_cvt_scalef32_pk_f32_fp4 v[228:229], v223, 1.0 op_sel:[0,1,0]
	v_pk_fma_f32 v[50:51], v[224:225], v[124:125], v[50:51] op_sel_hi:[1,0,1]
	v_cvt_scalef32_pk_f32_fp4 v[230:231], v223, 1.0 op_sel:[1,1,0]
	v_pk_fma_f32 v[116:117], v[226:227], v[124:125], v[116:117] op_sel_hi:[1,0,1]
	v_pk_fma_f32 v[112:113], v[228:229], v[124:125], v[112:113] op_sel_hi:[1,0,1]
	v_pk_fma_f32 v[104:105], v[230:231], v[124:125], v[104:105] op_sel_hi:[1,0,1]
	s_add_u32 s22, s22, 2
	s_cmp_lt_u32 s22, 14
	s_cbranch_scc1 .Lxg_loop_p6
	s_waitcnt lgkmcnt(0)
	v_lshl_add_u32 v250, v240, 9, v241
	v_lshl_add_u32 v251, v242, 9, v241
	v_lshl_add_u32 v252, v246, 9, v241
	v_lshl_add_u32 v253, v248, 9, v241
	global_load_dwordx4 v[192:195], v250, s[98:99]
	global_load_dwordx4 v[196:199], v251, s[98:99]
	global_load_dwordx4 v[200:203], v252, s[98:99]
	global_load_dwordx4 v[204:207], v253, s[98:99]
	global_load_dwordx4 v[208:211], v250, s[100:101]
	global_load_dwordx4 v[212:215], v251, s[100:101]
	global_load_dwordx4 v[216:219], v252, s[100:101]
	global_load_dwordx4 v[220:223], v253, s[100:101]
	s_movk_i32 s23, 0xc0
	v_lshl_add_u32 v130, v140, 2, s23
	ds_bpermute_b32 v156, v130, v150
	ds_bpermute_b32 v157, v130, v152
	s_waitcnt vmcnt(14)
	v_cvt_scalef32_pk_f32_fp4 v[224:225], v160, 1.0
	v_cvt_scalef32_pk_f32_fp4 v[226:227], v164, 1.0
	v_cvt_scalef32_pk_f32_fp4 v[228:229], v160, 1.0 op_sel:[1,0,0]
	v_cvt_scalef32_pk_f32_fp4 v[230:231], v164, 1.0 op_sel:[1,0,0]
	v_pk_fma_f32 v[232:233], v[24:25], v[224:225], 0 op_sel_hi:[1,1,0]
	v_pk_fma_f32 v[234:235], v[24:25], v[226:227], 0 op_sel_hi:[1,1,0]
	v_cvt_scalef32_pk_f32_fp4 v[224:225], v160, 1.0 op_sel:[0,1,0]
	v_cvt_scalef32_pk_f32_fp4 v[226:227], v164, 1.0 op_sel:[0,1,0]
	v_pk_fma_f32 v[232:233], v[26:27], v[228:229], v[232:233]
	v_pk_fma_f32 v[234:235], v[26:27], v[230:231], v[234:235]
	v_cvt_scalef32_pk_f32_fp4 v[228:229], v160, 1.0 op_sel:[1,1,0]
	v_cvt_scalef32_pk_f32_fp4 v[230:231], v164, 1.0 op_sel:[1,1,0]
	v_pk_fma_f32 v[232:233], v[12:13], v[224:225], v[232:233]
	v_pk_fma_f32 v[234:235], v[12:13], v[226:227], v[234:235]
	v_cvt_scalef32_pk_f32_fp4 v[224:225], v161, 1.0
	v_cvt_scalef32_pk_f32_fp4 v[226:227], v165, 1.0
	v_pk_fma_f32 v[232:233], v[14:15], v[228:229], v[232:233]
	v_pk_fma_f32 v[234:235], v[14:15], v[230:231], v[234:235]
	v_cvt_scalef32_pk_f32_fp4 v[228:229], v161, 1.0 op_sel:[1,0,0]
	v_cvt_scalef32_pk_f32_fp4 v[230:231], v165, 1.0 op_sel:[1,0,0]
	v_pk_fma_f32 v[232:233], v[4:5], v[224:225], v[232:233]
	v_pk_fma_f32 v[234:235], v[4:5], v[226:227], v[234:235]
	v_cvt_scalef32_pk_f32_fp4 v[224:225], v161, 1.0 op_sel:[0,1,0]
	v_cvt_scalef32_pk_f32_fp4 v[226:227], v165, 1.0 op_sel:[0,1,0]
	v_pk_fma_f32 v[232:233], v[6:7], v[228:229], v[232:233]
	v_pk_fma_f32 v[234:235], v[6:7], v[230:231], v[234:235]
	v_cvt_scalef32_pk_f32_fp4 v[228:229], v161, 1.0 op_sel:[1,1,0]
	v_cvt_scalef32_pk_f32_fp4 v[230:231], v165, 1.0 op_sel:[1,1,0]
	v_pk_fma_f32 v[232:233], v[0:1], v[224:225], v[232:233]
	v_pk_fma_f32 v[234:235], v[0:1], v[226:227], v[234:235]
	v_cvt_scalef32_pk_f32_fp4 v[224:225], v162, 1.0
	v_cvt_scalef32_pk_f32_fp4 v[226:227], v166, 1.0
	v_pk_fma_f32 v[232:233], v[2:3], v[228:229], v[232:233]
	v_pk_fma_f32 v[234:235], v[2:3], v[230:231], v[234:235]
	v_cvt_scalef32_pk_f32_fp4 v[228:229], v162, 1.0 op_sel:[1,0,0]
	v_cvt_scalef32_pk_f32_fp4 v[230:231], v166, 1.0 op_sel:[1,0,0]
	v_pk_fma_f32 v[232:233], v[28:29], v[224:225], v[232:233]
	v_pk_fma_f32 v[234:235], v[28:29], v[226:227], v[234:235]
	v_cvt_scalef32_pk_f32_fp4 v[224:225], v162, 1.0 op_sel:[0,1,0]
	v_cvt_scalef32_pk_f32_fp4 v[226:227], v166, 1.0 op_sel:[0,1,0]
	v_pk_fma_f32 v[232:233], v[30:31], v[228:229], v[232:233]
	v_pk_fma_f32 v[234:235], v[30:31], v[230:231], v[234:235]
	v_cvt_scalef32_pk_f32_fp4 v[228:229], v162, 1.0 op_sel:[1,1,0]
	v_cvt_scalef32_pk_f32_fp4 v[230:231], v166, 1.0 op_sel:[1,1,0]
	v_pk_fma_f32 v[232:233], v[16:17], v[224:225], v[232:233]
	v_pk_fma_f32 v[234:235], v[16:17], v[226:227], v[234:235]
	v_cvt_scalef32_pk_f32_fp4 v[224:225], v163, 1.0
	v_cvt_scalef32_pk_f32_fp4 v[226:227], v167, 1.0
	v_pk_fma_f32 v[232:233], v[18:19], v[228:229], v[232:233]
	v_pk_fma_f32 v[234:235], v[18:19], v[230:231], v[234:235]
	v_cvt_scalef32_pk_f32_fp4 v[228:229], v163, 1.0 op_sel:[1,0,0]
	v_cvt_scalef32_pk_f32_fp4 v[230:231], v167, 1.0 op_sel:[1,0,0]
	v_pk_fma_f32 v[232:233], v[8:9], v[224:225], v[232:233]
	v_pk_fma_f32 v[234:235], v[8:9], v[226:227], v[234:235]
	v_cvt_scalef32_pk_f32_fp4 v[224:225], v163, 1.0 op_sel:[0,1,0]
	v_cvt_scalef32_pk_f32_fp4 v[226:227], v167, 1.0 op_sel:[0,1,0]
	v_pk_fma_f32 v[232:233], v[10:11], v[228:229], v[232:233]
	v_pk_fma_f32 v[234:235], v[10:11], v[230:231], v[234:235]
	v_cvt_scalef32_pk_f32_fp4 v[228:229], v163, 1.0 op_sel:[1,1,0]
	v_cvt_scalef32_pk_f32_fp4 v[230:231], v167, 1.0 op_sel:[1,1,0]
	v_pk_fma_f32 v[232:233], v[20:21], v[224:225], v[232:233]
	v_pk_fma_f32 v[234:235], v[20:21], v[226:227], v[234:235]
	v_pk_fma_f32 v[232:233], v[22:23], v[228:229], v[232:233]
	v_pk_fma_f32 v[234:235], v[22:23], v[230:231], v[234:235]
	v_add_f32_e32 v32, v232, v233
	v_add_f32_e32 v33, v234, v235
	s_waitcnt vmcnt(12)
	v_cvt_scalef32_pk_f32_fp4 v[224:225], v168, 1.0
	v_cvt_scalef32_pk_f32_fp4 v[226:227], v172, 1.0
	v_cvt_scalef32_pk_f32_fp4 v[228:229], v168, 1.0 op_sel:[1,0,0]
	v_cvt_scalef32_pk_f32_fp4 v[230:231], v172, 1.0 op_sel:[1,0,0]
	v_pk_fma_f32 v[236:237], v[24:25], v[224:225], 0 op_sel_hi:[1,1,0]
	v_pk_fma_f32 v[238:239], v[24:25], v[226:227], 0 op_sel_hi:[1,1,0]
	v_cvt_scalef32_pk_f32_fp4 v[224:225], v168, 1.0 op_sel:[0,1,0]
	v_cvt_scalef32_pk_f32_fp4 v[226:227], v172, 1.0 op_sel:[0,1,0]
	v_pk_fma_f32 v[236:237], v[26:27], v[228:229], v[236:237]
	v_pk_fma_f32 v[238:239], v[26:27], v[230:231], v[238:239]
	v_cvt_scalef32_pk_f32_fp4 v[228:229], v168, 1.0 op_sel:[1,1,0]
	v_cvt_scalef32_pk_f32_fp4 v[230:231], v172, 1.0 op_sel:[1,1,0]
	v_pk_fma_f32 v[236:237], v[12:13], v[224:225], v[236:237]
	v_pk_fma_f32 v[238:239], v[12:13], v[226:227], v[238:239]
	v_cvt_scalef32_pk_f32_fp4 v[224:225], v169, 1.0
	v_cvt_scalef32_pk_f32_fp4 v[226:227], v173, 1.0
	v_pk_fma_f32 v[236:237], v[14:15], v[228:229], v[236:237]
	v_pk_fma_f32 v[238:239], v[14:15], v[230:231], v[238:239]
	v_cvt_scalef32_pk_f32_fp4 v[228:229], v169, 1.0 op_sel:[1,0,0]
	v_cvt_scalef32_pk_f32_fp4 v[230:231], v173, 1.0 op_sel:[1,0,0]
	v_pk_fma_f32 v[236:237], v[4:5], v[224:225], v[236:237]
	v_pk_fma_f32 v[238:239], v[4:5], v[226:227], v[238:239]
	v_cvt_scalef32_pk_f32_fp4 v[224:225], v169, 1.0 op_sel:[0,1,0]
	v_cvt_scalef32_pk_f32_fp4 v[226:227], v173, 1.0 op_sel:[0,1,0]
	v_pk_fma_f32 v[236:237], v[6:7], v[228:229], v[236:237]
	v_pk_fma_f32 v[238:239], v[6:7], v[230:231], v[238:239]
	v_cvt_scalef32_pk_f32_fp4 v[228:229], v169, 1.0 op_sel:[1,1,0]
	v_cvt_scalef32_pk_f32_fp4 v[230:231], v173, 1.0 op_sel:[1,1,0]
	v_pk_fma_f32 v[236:237], v[0:1], v[224:225], v[236:237]
	v_pk_fma_f32 v[238:239], v[0:1], v[226:227], v[238:239]
	v_cvt_scalef32_pk_f32_fp4 v[224:225], v170, 1.0
	v_cvt_scalef32_pk_f32_fp4 v[226:227], v174, 1.0
	v_pk_fma_f32 v[236:237], v[2:3], v[228:229], v[236:237]
	v_pk_fma_f32 v[238:239], v[2:3], v[230:231], v[238:239]
	v_cvt_scalef32_pk_f32_fp4 v[228:229], v170, 1.0 op_sel:[1,0,0]
	v_cvt_scalef32_pk_f32_fp4 v[230:231], v174, 1.0 op_sel:[1,0,0]
	v_pk_fma_f32 v[236:237], v[28:29], v[224:225], v[236:237]
	v_pk_fma_f32 v[238:239], v[28:29], v[226:227], v[238:239]
	v_cvt_scalef32_pk_f32_fp4 v[224:225], v170, 1.0 op_sel:[0,1,0]
	v_cvt_scalef32_pk_f32_fp4 v[226:227], v174, 1.0 op_sel:[0,1,0]
	v_pk_fma_f32 v[236:237], v[30:31], v[228:229], v[236:237]
	v_pk_fma_f32 v[238:239], v[30:31], v[230:231], v[238:239]
	v_cvt_scalef32_pk_f32_fp4 v[228:229], v170, 1.0 op_sel:[1,1,0]
	v_cvt_scalef32_pk_f32_fp4 v[230:231], v174, 1.0 op_sel:[1,1,0]
	v_pk_fma_f32 v[236:237], v[16:17], v[224:225], v[236:237]
	v_pk_fma_f32 v[238:239], v[16:17], v[226:227], v[238:239]
	v_cvt_scalef32_pk_f32_fp4 v[224:225], v171, 1.0
	v_cvt_scalef32_pk_f32_fp4 v[226:227], v175, 1.0
	v_pk_fma_f32 v[236:237], v[18:19], v[228:229], v[236:237]
	v_pk_fma_f32 v[238:239], v[18:19], v[230:231], v[238:239]
	v_cvt_scalef32_pk_f32_fp4 v[228:229], v171, 1.0 op_sel:[1,0,0]
	v_cvt_scalef32_pk_f32_fp4 v[230:231], v175, 1.0 op_sel:[1,0,0]
	v_pk_fma_f32 v[236:237], v[8:9], v[224:225], v[236:237]
	v_pk_fma_f32 v[238:239], v[8:9], v[226:227], v[238:239]
	v_cvt_scalef32_pk_f32_fp4 v[224:225], v171, 1.0 op_sel:[0,1,0]
	v_cvt_scalef32_pk_f32_fp4 v[226:227], v175, 1.0 op_sel:[0,1,0]
	v_pk_fma_f32 v[236:237], v[10:11], v[228:229], v[236:237]
	v_pk_fma_f32 v[238:239], v[10:11], v[230:231], v[238:239]
	v_cvt_scalef32_pk_f32_fp4 v[228:229], v171, 1.0 op_sel:[1,1,0]
	v_cvt_scalef32_pk_f32_fp4 v[230:231], v175, 1.0 op_sel:[1,1,0]
	v_pk_fma_f32 v[236:237], v[20:21], v[224:225], v[236:237]
	v_pk_fma_f32 v[238:239], v[20:21], v[226:227], v[238:239]
	v_pk_fma_f32 v[236:237], v[22:23], v[228:229], v[236:237]
	v_pk_fma_f32 v[238:239], v[22:23], v[230:231], v[238:239]
	v_add_f32_e32 v34, v236, v237
	v_add_f32_e32 v35, v238, v239
	s_nop 1
	v_permlane16_swap_b32_e32 v32, v34
	v_permlane16_swap_b32_e32 v33, v35
	v_add_f32_e32 v36, v32, v34
	v_add_f32_e32 v38, v33, v35
	s_waitcnt lgkmcnt(0)
	v_cndmask_b32_e64 v40, v38, v36, s[4:5]
	v_cndmask_b32_e64 v41, v36, v38, s[4:5]
	s_nop 1
	v_add_f32_dpp v40, v41, v40 row_ror:8 row_mask:0xf bank_mask:0xf
	s_nop 1
	v_add_f32_dpp v40, v40, v40 quad_perm:[1,0,3,2] row_mask:0xf bank_mask:0xf
	s_nop 1
	v_add_f32_dpp v40, v40, v40 quad_perm:[2,3,0,1] row_mask:0xf bank_mask:0xf
	s_nop 1
	v_add_f32_dpp v40, v40, v40 row_half_mirror row_mask:0xf bank_mask:0xf
	v_mul_f32_e32 v42, v40, v156
	v_fma_f32 v43, |v42|, s19, 1.0
	v_rcp_f32_e32 v43, v43
	v_cmp_gt_f32_e64 s[8:9], 0, v42
	v_mul_f32_e32 v45, v42, v42
	v_fmamk_f32 v44, v43, 0x3f07dc22, v145
	v_fmaak_f32 v44, v43, v44, 0x3f35f0e3
	v_fmaak_f32 v44, v43, v44, 0xbe11a98e
	v_fmaak_f32 v44, v43, v44, 0x3e027906
	v_mul_f32_e32 v45, 0xbf38aa3b, v45
	v_exp_f32_e32 v45, v45
	v_mul_f32_e32 v43, v43, v44
	v_mul_f32_e32 v43, v45, v43
	v_mul_f32_e32 v44, v42, v43
	v_fma_f32 v42, -v42, v43, v42
	v_cndmask_b32_e64 v42, v42, v44, s[8:9]
	v_mul_f32_e32 v158, v42, v157
	ds_bpermute_b32 v118, v141, v158
	ds_bpermute_b32 v120, v142, v158
	ds_bpermute_b32 v122, v143, v158
	ds_bpermute_b32 v124, v144, v158
	s_waitcnt vmcnt(11)
	v_cvt_scalef32_pk_f32_fp4 v[224:225], v176, 1.0
	v_cvt_scalef32_pk_f32_fp4 v[226:227], v176, 1.0 op_sel:[1,0,0]
	s_waitcnt lgkmcnt(0)
	v_cvt_scalef32_pk_f32_fp4 v[228:229], v176, 1.0 op_sel:[0,1,0]
	v_pk_fma_f32 v[114:115], v[224:225], v[118:119], v[114:115] op_sel_hi:[1,0,1]
	v_cvt_scalef32_pk_f32_fp4 v[230:231], v176, 1.0 op_sel:[1,1,0]
	v_pk_fma_f32 v[110:111], v[226:227], v[118:119], v[110:111] op_sel_hi:[1,0,1]
	v_cvt_scalef32_pk_f32_fp4 v[224:225], v177, 1.0
	v_pk_fma_f32 v[102:103], v[228:229], v[118:119], v[102:103] op_sel_hi:[1,0,1]
	v_cvt_scalef32_pk_f32_fp4 v[226:227], v177, 1.0 op_sel:[1,0,0]
	v_pk_fma_f32 v[100:101], v[230:231], v[118:119], v[100:101] op_sel_hi:[1,0,1]
	v_cvt_scalef32_pk_f32_fp4 v[228:229], v177, 1.0 op_sel:[0,1,0]
	v_pk_fma_f32 v[54:55], v[224:225], v[118:119], v[54:55] op_sel_hi:[1,0,1]
	v_cvt_scalef32_pk_f32_fp4 v[230:231], v177, 1.0 op_sel:[1,1,0]
	v_pk_fma_f32 v[58:59], v[226:227], v[118:119], v[58:59] op_sel_hi:[1,0,1]
	v_cvt_scalef32_pk_f32_fp4 v[224:225], v178, 1.0
	v_pk_fma_f32 v[52:53], v[228:229], v[118:119], v[52:53] op_sel_hi:[1,0,1]
	v_cvt_scalef32_pk_f32_fp4 v[226:227], v178, 1.0 op_sel:[1,0,0]
	v_pk_fma_f32 v[48:49], v[230:231], v[118:119], v[48:49] op_sel_hi:[1,0,1]
	v_cvt_scalef32_pk_f32_fp4 v[228:229], v178, 1.0 op_sel:[0,1,0]
	v_pk_fma_f32 v[108:109], v[224:225], v[118:119], v[108:109] op_sel_hi:[1,0,1]
	v_cvt_scalef32_pk_f32_fp4 v[230:231], v178, 1.0 op_sel:[1,1,0]
	v_pk_fma_f32 v[106:107], v[226:227], v[118:119], v[106:107] op_sel_hi:[1,0,1]
	v_cvt_scalef32_pk_f32_fp4 v[224:225], v179, 1.0
	v_pk_fma_f32 v[98:99], v[228:229], v[118:119], v[98:99] op_sel_hi:[1,0,1]
	v_cvt_scalef32_pk_f32_fp4 v[226:227], v179, 1.0 op_sel:[1,0,0]
	v_pk_fma_f32 v[56:57], v[230:231], v[118:119], v[56:57] op_sel_hi:[1,0,1]
	v_cvt_scalef32_pk_f32_fp4 v[228:229], v179, 1.0 op_sel:[0,1,0]
	v_pk_fma_f32 v[50:51], v[224:225], v[118:119], v[50:51] op_sel_hi:[1,0,1]
	v_cvt_scalef32_pk_f32_fp4 v[230:231], v179, 1.0 op_sel:[1,1,0]
	v_pk_fma_f32 v[116:117], v[226:227], v[118:119], v[116:117] op_sel_hi:[1,0,1]
	v_pk_fma_f32 v[112:113], v[228:229], v[118:119], v[112:113] op_sel_hi:[1,0,1]
	v_pk_fma_f32 v[104:105], v[230:231], v[118:119], v[104:105] op_sel_hi:[1,0,1]
	s_waitcnt vmcnt(10)
	v_cvt_scalef32_pk_f32_fp4 v[224:225], v180, 1.0
	v_cvt_scalef32_pk_f32_fp4 v[226:227], v180, 1.0 op_sel:[1,0,0]
	v_cvt_scalef32_pk_f32_fp4 v[228:229], v180, 1.0 op_sel:[0,1,0]
	v_pk_fma_f32 v[114:115], v[224:225], v[120:121], v[114:115] op_sel_hi:[1,0,1]
	v_cvt_scalef32_pk_f32_fp4 v[230:231], v180, 1.0 op_sel:[1,1,0]
	v_pk_fma_f32 v[110:111], v[226:227], v[120:121], v[110:111] op_sel_hi:[1,0,1]
	v_cvt_scalef32_pk_f32_fp4 v[224:225], v181, 1.0
	v_pk_fma_f32 v[102:103], v[228:229], v[120:121], v[102:103] op_sel_hi:[1,0,1]
	v_cvt_scalef32_pk_f32_fp4 v[226:227], v181, 1.0 op_sel:[1,0,0]
	v_pk_fma_f32 v[100:101], v[230:231], v[120:121], v[100:101] op_sel_hi:[1,0,1]
	v_cvt_scalef32_pk_f32_fp4 v[228:229], v181, 1.0 op_sel:[0,1,0]
	v_pk_fma_f32 v[54:55], v[224:225], v[120:121], v[54:55] op_sel_hi:[1,0,1]
	v_cvt_scalef32_pk_f32_fp4 v[230:231], v181, 1.0 op_sel:[1,1,0]
	v_pk_fma_f32 v[58:59], v[226:227], v[120:121], v[58:59] op_sel_hi:[1,0,1]
	v_cvt_scalef32_pk_f32_fp4 v[224:225], v182, 1.0
	v_pk_fma_f32 v[52:53], v[228:229], v[120:121], v[52:53] op_sel_hi:[1,0,1]
	v_cvt_scalef32_pk_f32_fp4 v[226:227], v182, 1.0 op_sel:[1,0,0]
	v_pk_fma_f32 v[48:49], v[230:231], v[120:121], v[48:49] op_sel_hi:[1,0,1]
	v_cvt_scalef32_pk_f32_fp4 v[228:229], v182, 1.0 op_sel:[0,1,0]
	v_pk_fma_f32 v[108:109], v[224:225], v[120:121], v[108:109] op_sel_hi:[1,0,1]
	v_cvt_scalef32_pk_f32_fp4 v[230:231], v182, 1.0 op_sel:[1,1,0]
	v_pk_fma_f32 v[106:107], v[226:227], v[120:121], v[106:107] op_sel_hi:[1,0,1]
	v_cvt_scalef32_pk_f32_fp4 v[224:225], v183, 1.0
	v_pk_fma_f32 v[98:99], v[228:229], v[120:121], v[98:99] op_sel_hi:[1,0,1]
	v_cvt_scalef32_pk_f32_fp4 v[226:227], v183, 1.0 op_sel:[1,0,0]
	v_pk_fma_f32 v[56:57], v[230:231], v[120:121], v[56:57] op_sel_hi:[1,0,1]
	v_cvt_scalef32_pk_f32_fp4 v[228:229], v183, 1.0 op_sel:[0,1,0]
	v_pk_fma_f32 v[50:51], v[224:225], v[120:121], v[50:51] op_sel_hi:[1,0,1]
	v_cvt_scalef32_pk_f32_fp4 v[230:231], v183, 1.0 op_sel:[1,1,0]
	v_pk_fma_f32 v[116:117], v[226:227], v[120:121], v[116:117] op_sel_hi:[1,0,1]
	v_pk_fma_f32 v[112:113], v[228:229], v[120:121], v[112:113] op_sel_hi:[1,0,1]
	v_pk_fma_f32 v[104:105], v[230:231], v[120:121], v[104:105] op_sel_hi:[1,0,1]
	s_waitcnt vmcnt(9)
	v_cvt_scalef32_pk_f32_fp4 v[224:225], v184, 1.0
	v_cvt_scalef32_pk_f32_fp4 v[226:227], v184, 1.0 op_sel:[1,0,0]
	v_cvt_scalef32_pk_f32_fp4 v[228:229], v184, 1.0 op_sel:[0,1,0]
	v_pk_fma_f32 v[114:115], v[224:225], v[122:123], v[114:115] op_sel_hi:[1,0,1]
	v_cvt_scalef32_pk_f32_fp4 v[230:231], v184, 1.0 op_sel:[1,1,0]
	v_pk_fma_f32 v[110:111], v[226:227], v[122:123], v[110:111] op_sel_hi:[1,0,1]
	v_cvt_scalef32_pk_f32_fp4 v[224:225], v185, 1.0
	v_pk_fma_f32 v[102:103], v[228:229], v[122:123], v[102:103] op_sel_hi:[1,0,1]
	v_cvt_scalef32_pk_f32_fp4 v[226:227], v185, 1.0 op_sel:[1,0,0]
	v_pk_fma_f32 v[100:101], v[230:231], v[122:123], v[100:101] op_sel_hi:[1,0,1]
	v_cvt_scalef32_pk_f32_fp4 v[228:229], v185, 1.0 op_sel:[0,1,0]
	v_pk_fma_f32 v[54:55], v[224:225], v[122:123], v[54:55] op_sel_hi:[1,0,1]
	v_cvt_scalef32_pk_f32_fp4 v[230:231], v185, 1.0 op_sel:[1,1,0]
	v_pk_fma_f32 v[58:59], v[226:227], v[122:123], v[58:59] op_sel_hi:[1,0,1]
	v_cvt_scalef32_pk_f32_fp4 v[224:225], v186, 1.0
	v_pk_fma_f32 v[52:53], v[228:229], v[122:123], v[52:53] op_sel_hi:[1,0,1]
	v_cvt_scalef32_pk_f32_fp4 v[226:227], v186, 1.0 op_sel:[1,0,0]
	v_pk_fma_f32 v[48:49], v[230:231], v[122:123], v[48:49] op_sel_hi:[1,0,1]
	v_cvt_scalef32_pk_f32_fp4 v[228:229], v186, 1.0 op_sel:[0,1,0]
	v_pk_fma_f32 v[108:109], v[224:225], v[122:123], v[108:109] op_sel_hi:[1,0,1]
	v_cvt_scalef32_pk_f32_fp4 v[230:231], v186, 1.0 op_sel:[1,1,0]
	v_pk_fma_f32 v[106:107], v[226:227], v[122:123], v[106:107] op_sel_hi:[1,0,1]
	v_cvt_scalef32_pk_f32_fp4 v[224:225], v187, 1.0
	v_pk_fma_f32 v[98:99], v[228:229], v[122:123], v[98:99] op_sel_hi:[1,0,1]
	v_cvt_scalef32_pk_f32_fp4 v[226:227], v187, 1.0 op_sel:[1,0,0]
	v_pk_fma_f32 v[56:57], v[230:231], v[122:123], v[56:57] op_sel_hi:[1,0,1]
	v_cvt_scalef32_pk_f32_fp4 v[228:229], v187, 1.0 op_sel:[0,1,0]
	v_pk_fma_f32 v[50:51], v[224:225], v[122:123], v[50:51] op_sel_hi:[1,0,1]
	v_cvt_scalef32_pk_f32_fp4 v[230:231], v187, 1.0 op_sel:[1,1,0]
	v_pk_fma_f32 v[116:117], v[226:227], v[122:123], v[116:117] op_sel_hi:[1,0,1]
	v_pk_fma_f32 v[112:113], v[228:229], v[122:123], v[112:113] op_sel_hi:[1,0,1]
	v_pk_fma_f32 v[104:105], v[230:231], v[122:123], v[104:105] op_sel_hi:[1,0,1]
	s_waitcnt vmcnt(8)
	v_cvt_scalef32_pk_f32_fp4 v[224:225], v188, 1.0
	v_cvt_scalef32_pk_f32_fp4 v[226:227], v188, 1.0 op_sel:[1,0,0]
	v_cvt_scalef32_pk_f32_fp4 v[228:229], v188, 1.0 op_sel:[0,1,0]
	v_pk_fma_f32 v[114:115], v[224:225], v[124:125], v[114:115] op_sel_hi:[1,0,1]
	v_cvt_scalef32_pk_f32_fp4 v[230:231], v188, 1.0 op_sel:[1,1,0]
	v_pk_fma_f32 v[110:111], v[226:227], v[124:125], v[110:111] op_sel_hi:[1,0,1]
	v_cvt_scalef32_pk_f32_fp4 v[224:225], v189, 1.0
	v_pk_fma_f32 v[102:103], v[228:229], v[124:125], v[102:103] op_sel_hi:[1,0,1]
	v_cvt_scalef32_pk_f32_fp4 v[226:227], v189, 1.0 op_sel:[1,0,0]
	v_pk_fma_f32 v[100:101], v[230:231], v[124:125], v[100:101] op_sel_hi:[1,0,1]
	v_cvt_scalef32_pk_f32_fp4 v[228:229], v189, 1.0 op_sel:[0,1,0]
	v_pk_fma_f32 v[54:55], v[224:225], v[124:125], v[54:55] op_sel_hi:[1,0,1]
	v_cvt_scalef32_pk_f32_fp4 v[230:231], v189, 1.0 op_sel:[1,1,0]
	v_pk_fma_f32 v[58:59], v[226:227], v[124:125], v[58:59] op_sel_hi:[1,0,1]
	v_cvt_scalef32_pk_f32_fp4 v[224:225], v190, 1.0
	v_pk_fma_f32 v[52:53], v[228:229], v[124:125], v[52:53] op_sel_hi:[1,0,1]
	v_cvt_scalef32_pk_f32_fp4 v[226:227], v190, 1.0 op_sel:[1,0,0]
	v_pk_fma_f32 v[48:49], v[230:231], v[124:125], v[48:49] op_sel_hi:[1,0,1]
	v_cvt_scalef32_pk_f32_fp4 v[228:229], v190, 1.0 op_sel:[0,1,0]
	v_pk_fma_f32 v[108:109], v[224:225], v[124:125], v[108:109] op_sel_hi:[1,0,1]
	v_cvt_scalef32_pk_f32_fp4 v[230:231], v190, 1.0 op_sel:[1,1,0]
	v_pk_fma_f32 v[106:107], v[226:227], v[124:125], v[106:107] op_sel_hi:[1,0,1]
	v_cvt_scalef32_pk_f32_fp4 v[224:225], v191, 1.0
	v_pk_fma_f32 v[98:99], v[228:229], v[124:125], v[98:99] op_sel_hi:[1,0,1]
	v_cvt_scalef32_pk_f32_fp4 v[226:227], v191, 1.0 op_sel:[1,0,0]
	v_pk_fma_f32 v[56:57], v[230:231], v[124:125], v[56:57] op_sel_hi:[1,0,1]
	v_cvt_scalef32_pk_f32_fp4 v[228:229], v191, 1.0 op_sel:[0,1,0]
	v_pk_fma_f32 v[50:51], v[224:225], v[124:125], v[50:51] op_sel_hi:[1,0,1]
	v_cvt_scalef32_pk_f32_fp4 v[230:231], v191, 1.0 op_sel:[1,1,0]
	v_pk_fma_f32 v[116:117], v[226:227], v[124:125], v[116:117] op_sel_hi:[1,0,1]
	v_pk_fma_f32 v[112:113], v[228:229], v[124:125], v[112:113] op_sel_hi:[1,0,1]
	v_pk_fma_f32 v[104:105], v[230:231], v[124:125], v[104:105] op_sel_hi:[1,0,1]
	s_waitcnt lgkmcnt(0)
	s_movk_i32 s23, 0xe0
	v_lshl_add_u32 v130, v140, 2, s23
	ds_bpermute_b32 v156, v130, v150
	ds_bpermute_b32 v157, v130, v152
	s_waitcnt vmcnt(6)
	v_cvt_scalef32_pk_f32_fp4 v[224:225], v192, 1.0
	v_cvt_scalef32_pk_f32_fp4 v[226:227], v196, 1.0
	v_cvt_scalef32_pk_f32_fp4 v[228:229], v192, 1.0 op_sel:[1,0,0]
	v_cvt_scalef32_pk_f32_fp4 v[230:231], v196, 1.0 op_sel:[1,0,0]
	v_pk_fma_f32 v[232:233], v[24:25], v[224:225], 0 op_sel_hi:[1,1,0]
	v_pk_fma_f32 v[234:235], v[24:25], v[226:227], 0 op_sel_hi:[1,1,0]
	v_cvt_scalef32_pk_f32_fp4 v[224:225], v192, 1.0 op_sel:[0,1,0]
	v_cvt_scalef32_pk_f32_fp4 v[226:227], v196, 1.0 op_sel:[0,1,0]
	v_pk_fma_f32 v[232:233], v[26:27], v[228:229], v[232:233]
	v_pk_fma_f32 v[234:235], v[26:27], v[230:231], v[234:235]
	v_cvt_scalef32_pk_f32_fp4 v[228:229], v192, 1.0 op_sel:[1,1,0]
	v_cvt_scalef32_pk_f32_fp4 v[230:231], v196, 1.0 op_sel:[1,1,0]
	v_pk_fma_f32 v[232:233], v[12:13], v[224:225], v[232:233]
	v_pk_fma_f32 v[234:235], v[12:13], v[226:227], v[234:235]
	v_cvt_scalef32_pk_f32_fp4 v[224:225], v193, 1.0
	v_cvt_scalef32_pk_f32_fp4 v[226:227], v197, 1.0
	v_pk_fma_f32 v[232:233], v[14:15], v[228:229], v[232:233]
	v_pk_fma_f32 v[234:235], v[14:15], v[230:231], v[234:235]
	v_cvt_scalef32_pk_f32_fp4 v[228:229], v193, 1.0 op_sel:[1,0,0]
	v_cvt_scalef32_pk_f32_fp4 v[230:231], v197, 1.0 op_sel:[1,0,0]
	v_pk_fma_f32 v[232:233], v[4:5], v[224:225], v[232:233]
	v_pk_fma_f32 v[234:235], v[4:5], v[226:227], v[234:235]
	v_cvt_scalef32_pk_f32_fp4 v[224:225], v193, 1.0 op_sel:[0,1,0]
	v_cvt_scalef32_pk_f32_fp4 v[226:227], v197, 1.0 op_sel:[0,1,0]
	v_pk_fma_f32 v[232:233], v[6:7], v[228:229], v[232:233]
	v_pk_fma_f32 v[234:235], v[6:7], v[230:231], v[234:235]
	v_cvt_scalef32_pk_f32_fp4 v[228:229], v193, 1.0 op_sel:[1,1,0]
	v_cvt_scalef32_pk_f32_fp4 v[230:231], v197, 1.0 op_sel:[1,1,0]
	v_pk_fma_f32 v[232:233], v[0:1], v[224:225], v[232:233]
	v_pk_fma_f32 v[234:235], v[0:1], v[226:227], v[234:235]
	v_cvt_scalef32_pk_f32_fp4 v[224:225], v194, 1.0
	v_cvt_scalef32_pk_f32_fp4 v[226:227], v198, 1.0
	v_pk_fma_f32 v[232:233], v[2:3], v[228:229], v[232:233]
	v_pk_fma_f32 v[234:235], v[2:3], v[230:231], v[234:235]
	v_cvt_scalef32_pk_f32_fp4 v[228:229], v194, 1.0 op_sel:[1,0,0]
	v_cvt_scalef32_pk_f32_fp4 v[230:231], v198, 1.0 op_sel:[1,0,0]
	v_pk_fma_f32 v[232:233], v[28:29], v[224:225], v[232:233]
	v_pk_fma_f32 v[234:235], v[28:29], v[226:227], v[234:235]
	v_cvt_scalef32_pk_f32_fp4 v[224:225], v194, 1.0 op_sel:[0,1,0]
	v_cvt_scalef32_pk_f32_fp4 v[226:227], v198, 1.0 op_sel:[0,1,0]
	v_pk_fma_f32 v[232:233], v[30:31], v[228:229], v[232:233]
	v_pk_fma_f32 v[234:235], v[30:31], v[230:231], v[234:235]
	v_cvt_scalef32_pk_f32_fp4 v[228:229], v194, 1.0 op_sel:[1,1,0]
	v_cvt_scalef32_pk_f32_fp4 v[230:231], v198, 1.0 op_sel:[1,1,0]
	v_pk_fma_f32 v[232:233], v[16:17], v[224:225], v[232:233]
	v_pk_fma_f32 v[234:235], v[16:17], v[226:227], v[234:235]
	v_cvt_scalef32_pk_f32_fp4 v[224:225], v195, 1.0
	v_cvt_scalef32_pk_f32_fp4 v[226:227], v199, 1.0
	v_pk_fma_f32 v[232:233], v[18:19], v[228:229], v[232:233]
	v_pk_fma_f32 v[234:235], v[18:19], v[230:231], v[234:235]
	v_cvt_scalef32_pk_f32_fp4 v[228:229], v195, 1.0 op_sel:[1,0,0]
	v_cvt_scalef32_pk_f32_fp4 v[230:231], v199, 1.0 op_sel:[1,0,0]
	v_pk_fma_f32 v[232:233], v[8:9], v[224:225], v[232:233]
	v_pk_fma_f32 v[234:235], v[8:9], v[226:227], v[234:235]
	v_cvt_scalef32_pk_f32_fp4 v[224:225], v195, 1.0 op_sel:[0,1,0]
	v_cvt_scalef32_pk_f32_fp4 v[226:227], v199, 1.0 op_sel:[0,1,0]
	v_pk_fma_f32 v[232:233], v[10:11], v[228:229], v[232:233]
	v_pk_fma_f32 v[234:235], v[10:11], v[230:231], v[234:235]
	v_cvt_scalef32_pk_f32_fp4 v[228:229], v195, 1.0 op_sel:[1,1,0]
	v_cvt_scalef32_pk_f32_fp4 v[230:231], v199, 1.0 op_sel:[1,1,0]
	v_pk_fma_f32 v[232:233], v[20:21], v[224:225], v[232:233]
	v_pk_fma_f32 v[234:235], v[20:21], v[226:227], v[234:235]
	v_pk_fma_f32 v[232:233], v[22:23], v[228:229], v[232:233]
	v_pk_fma_f32 v[234:235], v[22:23], v[230:231], v[234:235]
	v_add_f32_e32 v32, v232, v233
	v_add_f32_e32 v33, v234, v235
	s_waitcnt vmcnt(4)
	v_cvt_scalef32_pk_f32_fp4 v[224:225], v200, 1.0
	v_cvt_scalef32_pk_f32_fp4 v[226:227], v204, 1.0
	v_cvt_scalef32_pk_f32_fp4 v[228:229], v200, 1.0 op_sel:[1,0,0]
	v_cvt_scalef32_pk_f32_fp4 v[230:231], v204, 1.0 op_sel:[1,0,0]
	v_pk_fma_f32 v[236:237], v[24:25], v[224:225], 0 op_sel_hi:[1,1,0]
	v_pk_fma_f32 v[238:239], v[24:25], v[226:227], 0 op_sel_hi:[1,1,0]
	v_cvt_scalef32_pk_f32_fp4 v[224:225], v200, 1.0 op_sel:[0,1,0]
	v_cvt_scalef32_pk_f32_fp4 v[226:227], v204, 1.0 op_sel:[0,1,0]
	v_pk_fma_f32 v[236:237], v[26:27], v[228:229], v[236:237]
	v_pk_fma_f32 v[238:239], v[26:27], v[230:231], v[238:239]
	v_cvt_scalef32_pk_f32_fp4 v[228:229], v200, 1.0 op_sel:[1,1,0]
	v_cvt_scalef32_pk_f32_fp4 v[230:231], v204, 1.0 op_sel:[1,1,0]
	v_pk_fma_f32 v[236:237], v[12:13], v[224:225], v[236:237]
	v_pk_fma_f32 v[238:239], v[12:13], v[226:227], v[238:239]
	v_cvt_scalef32_pk_f32_fp4 v[224:225], v201, 1.0
	v_cvt_scalef32_pk_f32_fp4 v[226:227], v205, 1.0
	v_pk_fma_f32 v[236:237], v[14:15], v[228:229], v[236:237]
	v_pk_fma_f32 v[238:239], v[14:15], v[230:231], v[238:239]
	v_cvt_scalef32_pk_f32_fp4 v[228:229], v201, 1.0 op_sel:[1,0,0]
	v_cvt_scalef32_pk_f32_fp4 v[230:231], v205, 1.0 op_sel:[1,0,0]
	v_pk_fma_f32 v[236:237], v[4:5], v[224:225], v[236:237]
	v_pk_fma_f32 v[238:239], v[4:5], v[226:227], v[238:239]
	v_cvt_scalef32_pk_f32_fp4 v[224:225], v201, 1.0 op_sel:[0,1,0]
	v_cvt_scalef32_pk_f32_fp4 v[226:227], v205, 1.0 op_sel:[0,1,0]
	v_pk_fma_f32 v[236:237], v[6:7], v[228:229], v[236:237]
	v_pk_fma_f32 v[238:239], v[6:7], v[230:231], v[238:239]
	v_cvt_scalef32_pk_f32_fp4 v[228:229], v201, 1.0 op_sel:[1,1,0]
	v_cvt_scalef32_pk_f32_fp4 v[230:231], v205, 1.0 op_sel:[1,1,0]
	v_pk_fma_f32 v[236:237], v[0:1], v[224:225], v[236:237]
	v_pk_fma_f32 v[238:239], v[0:1], v[226:227], v[238:239]
	v_cvt_scalef32_pk_f32_fp4 v[224:225], v202, 1.0
	v_cvt_scalef32_pk_f32_fp4 v[226:227], v206, 1.0
	v_pk_fma_f32 v[236:237], v[2:3], v[228:229], v[236:237]
	v_pk_fma_f32 v[238:239], v[2:3], v[230:231], v[238:239]
	v_cvt_scalef32_pk_f32_fp4 v[228:229], v202, 1.0 op_sel:[1,0,0]
	v_cvt_scalef32_pk_f32_fp4 v[230:231], v206, 1.0 op_sel:[1,0,0]
	v_pk_fma_f32 v[236:237], v[28:29], v[224:225], v[236:237]
	v_pk_fma_f32 v[238:239], v[28:29], v[226:227], v[238:239]
	v_cvt_scalef32_pk_f32_fp4 v[224:225], v202, 1.0 op_sel:[0,1,0]
	v_cvt_scalef32_pk_f32_fp4 v[226:227], v206, 1.0 op_sel:[0,1,0]
	v_pk_fma_f32 v[236:237], v[30:31], v[228:229], v[236:237]
	v_pk_fma_f32 v[238:239], v[30:31], v[230:231], v[238:239]
	v_cvt_scalef32_pk_f32_fp4 v[228:229], v202, 1.0 op_sel:[1,1,0]
	v_cvt_scalef32_pk_f32_fp4 v[230:231], v206, 1.0 op_sel:[1,1,0]
	v_pk_fma_f32 v[236:237], v[16:17], v[224:225], v[236:237]
	v_pk_fma_f32 v[238:239], v[16:17], v[226:227], v[238:239]
	v_cvt_scalef32_pk_f32_fp4 v[224:225], v203, 1.0
	v_cvt_scalef32_pk_f32_fp4 v[226:227], v207, 1.0
	v_pk_fma_f32 v[236:237], v[18:19], v[228:229], v[236:237]
	v_pk_fma_f32 v[238:239], v[18:19], v[230:231], v[238:239]
	v_cvt_scalef32_pk_f32_fp4 v[228:229], v203, 1.0 op_sel:[1,0,0]
	v_cvt_scalef32_pk_f32_fp4 v[230:231], v207, 1.0 op_sel:[1,0,0]
	v_pk_fma_f32 v[236:237], v[8:9], v[224:225], v[236:237]
	v_pk_fma_f32 v[238:239], v[8:9], v[226:227], v[238:239]
	v_cvt_scalef32_pk_f32_fp4 v[224:225], v203, 1.0 op_sel:[0,1,0]
	v_cvt_scalef32_pk_f32_fp4 v[226:227], v207, 1.0 op_sel:[0,1,0]
	v_pk_fma_f32 v[236:237], v[10:11], v[228:229], v[236:237]
	v_pk_fma_f32 v[238:239], v[10:11], v[230:231], v[238:239]
	v_cvt_scalef32_pk_f32_fp4 v[228:229], v203, 1.0 op_sel:[1,1,0]
	v_cvt_scalef32_pk_f32_fp4 v[230:231], v207, 1.0 op_sel:[1,1,0]
	v_pk_fma_f32 v[236:237], v[20:21], v[224:225], v[236:237]
	v_pk_fma_f32 v[238:239], v[20:21], v[226:227], v[238:239]
	v_pk_fma_f32 v[236:237], v[22:23], v[228:229], v[236:237]
	v_pk_fma_f32 v[238:239], v[22:23], v[230:231], v[238:239]
	v_add_f32_e32 v34, v236, v237
	v_add_f32_e32 v35, v238, v239
	s_nop 1
	v_permlane16_swap_b32_e32 v32, v34
	v_permlane16_swap_b32_e32 v33, v35
	v_add_f32_e32 v36, v32, v34
	v_add_f32_e32 v38, v33, v35
	s_waitcnt lgkmcnt(0)
	v_cndmask_b32_e64 v40, v38, v36, s[4:5]
	v_cndmask_b32_e64 v41, v36, v38, s[4:5]
	s_nop 1
	v_add_f32_dpp v40, v41, v40 row_ror:8 row_mask:0xf bank_mask:0xf
	s_nop 1
	v_add_f32_dpp v40, v40, v40 quad_perm:[1,0,3,2] row_mask:0xf bank_mask:0xf
	s_nop 1
	v_add_f32_dpp v40, v40, v40 quad_perm:[2,3,0,1] row_mask:0xf bank_mask:0xf
	s_nop 1
	v_add_f32_dpp v40, v40, v40 row_half_mirror row_mask:0xf bank_mask:0xf
	v_mul_f32_e32 v42, v40, v156
	v_fma_f32 v43, |v42|, s19, 1.0
	v_rcp_f32_e32 v43, v43
	v_cmp_gt_f32_e64 s[8:9], 0, v42
	v_mul_f32_e32 v45, v42, v42
	v_fmamk_f32 v44, v43, 0x3f07dc22, v145
	v_fmaak_f32 v44, v43, v44, 0x3f35f0e3
	v_fmaak_f32 v44, v43, v44, 0xbe11a98e
	v_fmaak_f32 v44, v43, v44, 0x3e027906
	v_mul_f32_e32 v45, 0xbf38aa3b, v45
	v_exp_f32_e32 v45, v45
	v_mul_f32_e32 v43, v43, v44
	v_mul_f32_e32 v43, v45, v43
	v_mul_f32_e32 v44, v42, v43
	v_fma_f32 v42, -v42, v43, v42
	v_cndmask_b32_e64 v42, v42, v44, s[8:9]
	v_mul_f32_e32 v158, v42, v157
	ds_bpermute_b32 v118, v141, v158
	ds_bpermute_b32 v120, v142, v158
	ds_bpermute_b32 v122, v143, v158
	ds_bpermute_b32 v124, v144, v158
	s_waitcnt vmcnt(3)
	v_cvt_scalef32_pk_f32_fp4 v[224:225], v208, 1.0
	v_cvt_scalef32_pk_f32_fp4 v[226:227], v208, 1.0 op_sel:[1,0,0]
	s_waitcnt lgkmcnt(0)
	v_cvt_scalef32_pk_f32_fp4 v[228:229], v208, 1.0 op_sel:[0,1,0]
	v_pk_fma_f32 v[114:115], v[224:225], v[118:119], v[114:115] op_sel_hi:[1,0,1]
	v_cvt_scalef32_pk_f32_fp4 v[230:231], v208, 1.0 op_sel:[1,1,0]
	v_pk_fma_f32 v[110:111], v[226:227], v[118:119], v[110:111] op_sel_hi:[1,0,1]
	v_cvt_scalef32_pk_f32_fp4 v[224:225], v209, 1.0
	v_pk_fma_f32 v[102:103], v[228:229], v[118:119], v[102:103] op_sel_hi:[1,0,1]
	v_cvt_scalef32_pk_f32_fp4 v[226:227], v209, 1.0 op_sel:[1,0,0]
	v_pk_fma_f32 v[100:101], v[230:231], v[118:119], v[100:101] op_sel_hi:[1,0,1]
	v_cvt_scalef32_pk_f32_fp4 v[228:229], v209, 1.0 op_sel:[0,1,0]
	v_pk_fma_f32 v[54:55], v[224:225], v[118:119], v[54:55] op_sel_hi:[1,0,1]
	v_cvt_scalef32_pk_f32_fp4 v[230:231], v209, 1.0 op_sel:[1,1,0]
	v_pk_fma_f32 v[58:59], v[226:227], v[118:119], v[58:59] op_sel_hi:[1,0,1]
	v_cvt_scalef32_pk_f32_fp4 v[224:225], v210, 1.0
	v_pk_fma_f32 v[52:53], v[228:229], v[118:119], v[52:53] op_sel_hi:[1,0,1]
	v_cvt_scalef32_pk_f32_fp4 v[226:227], v210, 1.0 op_sel:[1,0,0]
	v_pk_fma_f32 v[48:49], v[230:231], v[118:119], v[48:49] op_sel_hi:[1,0,1]
	v_cvt_scalef32_pk_f32_fp4 v[228:229], v210, 1.0 op_sel:[0,1,0]
	v_pk_fma_f32 v[108:109], v[224:225], v[118:119], v[108:109] op_sel_hi:[1,0,1]
	v_cvt_scalef32_pk_f32_fp4 v[230:231], v210, 1.0 op_sel:[1,1,0]
	v_pk_fma_f32 v[106:107], v[226:227], v[118:119], v[106:107] op_sel_hi:[1,0,1]
	v_cvt_scalef32_pk_f32_fp4 v[224:225], v211, 1.0
	v_pk_fma_f32 v[98:99], v[228:229], v[118:119], v[98:99] op_sel_hi:[1,0,1]
	v_cvt_scalef32_pk_f32_fp4 v[226:227], v211, 1.0 op_sel:[1,0,0]
	v_pk_fma_f32 v[56:57], v[230:231], v[118:119], v[56:57] op_sel_hi:[1,0,1]
	v_cvt_scalef32_pk_f32_fp4 v[228:229], v211, 1.0 op_sel:[0,1,0]
	v_pk_fma_f32 v[50:51], v[224:225], v[118:119], v[50:51] op_sel_hi:[1,0,1]
	v_cvt_scalef32_pk_f32_fp4 v[230:231], v211, 1.0 op_sel:[1,1,0]
	v_pk_fma_f32 v[116:117], v[226:227], v[118:119], v[116:117] op_sel_hi:[1,0,1]
	v_pk_fma_f32 v[112:113], v[228:229], v[118:119], v[112:113] op_sel_hi:[1,0,1]
	v_pk_fma_f32 v[104:105], v[230:231], v[118:119], v[104:105] op_sel_hi:[1,0,1]
	s_waitcnt vmcnt(2)
	v_cvt_scalef32_pk_f32_fp4 v[224:225], v212, 1.0
	v_cvt_scalef32_pk_f32_fp4 v[226:227], v212, 1.0 op_sel:[1,0,0]
	v_cvt_scalef32_pk_f32_fp4 v[228:229], v212, 1.0 op_sel:[0,1,0]
	v_pk_fma_f32 v[114:115], v[224:225], v[120:121], v[114:115] op_sel_hi:[1,0,1]
	v_cvt_scalef32_pk_f32_fp4 v[230:231], v212, 1.0 op_sel:[1,1,0]
	v_pk_fma_f32 v[110:111], v[226:227], v[120:121], v[110:111] op_sel_hi:[1,0,1]
	v_cvt_scalef32_pk_f32_fp4 v[224:225], v213, 1.0
	v_pk_fma_f32 v[102:103], v[228:229], v[120:121], v[102:103] op_sel_hi:[1,0,1]
	v_cvt_scalef32_pk_f32_fp4 v[226:227], v213, 1.0 op_sel:[1,0,0]
	v_pk_fma_f32 v[100:101], v[230:231], v[120:121], v[100:101] op_sel_hi:[1,0,1]
	v_cvt_scalef32_pk_f32_fp4 v[228:229], v213, 1.0 op_sel:[0,1,0]
	v_pk_fma_f32 v[54:55], v[224:225], v[120:121], v[54:55] op_sel_hi:[1,0,1]
	v_cvt_scalef32_pk_f32_fp4 v[230:231], v213, 1.0 op_sel:[1,1,0]
	v_pk_fma_f32 v[58:59], v[226:227], v[120:121], v[58:59] op_sel_hi:[1,0,1]
	v_cvt_scalef32_pk_f32_fp4 v[224:225], v214, 1.0
	v_pk_fma_f32 v[52:53], v[228:229], v[120:121], v[52:53] op_sel_hi:[1,0,1]
	v_cvt_scalef32_pk_f32_fp4 v[226:227], v214, 1.0 op_sel:[1,0,0]
	v_pk_fma_f32 v[48:49], v[230:231], v[120:121], v[48:49] op_sel_hi:[1,0,1]
	v_cvt_scalef32_pk_f32_fp4 v[228:229], v214, 1.0 op_sel:[0,1,0]
	v_pk_fma_f32 v[108:109], v[224:225], v[120:121], v[108:109] op_sel_hi:[1,0,1]
	v_cvt_scalef32_pk_f32_fp4 v[230:231], v214, 1.0 op_sel:[1,1,0]
	v_pk_fma_f32 v[106:107], v[226:227], v[120:121], v[106:107] op_sel_hi:[1,0,1]
	v_cvt_scalef32_pk_f32_fp4 v[224:225], v215, 1.0
	v_pk_fma_f32 v[98:99], v[228:229], v[120:121], v[98:99] op_sel_hi:[1,0,1]
	v_cvt_scalef32_pk_f32_fp4 v[226:227], v215, 1.0 op_sel:[1,0,0]
	v_pk_fma_f32 v[56:57], v[230:231], v[120:121], v[56:57] op_sel_hi:[1,0,1]
	v_cvt_scalef32_pk_f32_fp4 v[228:229], v215, 1.0 op_sel:[0,1,0]
	v_pk_fma_f32 v[50:51], v[224:225], v[120:121], v[50:51] op_sel_hi:[1,0,1]
	v_cvt_scalef32_pk_f32_fp4 v[230:231], v215, 1.0 op_sel:[1,1,0]
	v_pk_fma_f32 v[116:117], v[226:227], v[120:121], v[116:117] op_sel_hi:[1,0,1]
	v_pk_fma_f32 v[112:113], v[228:229], v[120:121], v[112:113] op_sel_hi:[1,0,1]
	v_pk_fma_f32 v[104:105], v[230:231], v[120:121], v[104:105] op_sel_hi:[1,0,1]
	s_waitcnt vmcnt(1)
	v_cvt_scalef32_pk_f32_fp4 v[224:225], v216, 1.0
	v_cvt_scalef32_pk_f32_fp4 v[226:227], v216, 1.0 op_sel:[1,0,0]
	v_cvt_scalef32_pk_f32_fp4 v[228:229], v216, 1.0 op_sel:[0,1,0]
	v_pk_fma_f32 v[114:115], v[224:225], v[122:123], v[114:115] op_sel_hi:[1,0,1]
	v_cvt_scalef32_pk_f32_fp4 v[230:231], v216, 1.0 op_sel:[1,1,0]
	v_pk_fma_f32 v[110:111], v[226:227], v[122:123], v[110:111] op_sel_hi:[1,0,1]
	v_cvt_scalef32_pk_f32_fp4 v[224:225], v217, 1.0
	v_pk_fma_f32 v[102:103], v[228:229], v[122:123], v[102:103] op_sel_hi:[1,0,1]
	v_cvt_scalef32_pk_f32_fp4 v[226:227], v217, 1.0 op_sel:[1,0,0]
	v_pk_fma_f32 v[100:101], v[230:231], v[122:123], v[100:101] op_sel_hi:[1,0,1]
	v_cvt_scalef32_pk_f32_fp4 v[228:229], v217, 1.0 op_sel:[0,1,0]
	v_pk_fma_f32 v[54:55], v[224:225], v[122:123], v[54:55] op_sel_hi:[1,0,1]
	v_cvt_scalef32_pk_f32_fp4 v[230:231], v217, 1.0 op_sel:[1,1,0]
	v_pk_fma_f32 v[58:59], v[226:227], v[122:123], v[58:59] op_sel_hi:[1,0,1]
	v_cvt_scalef32_pk_f32_fp4 v[224:225], v218, 1.0
	v_pk_fma_f32 v[52:53], v[228:229], v[122:123], v[52:53] op_sel_hi:[1,0,1]
	v_cvt_scalef32_pk_f32_fp4 v[226:227], v218, 1.0 op_sel:[1,0,0]
	v_pk_fma_f32 v[48:49], v[230:231], v[122:123], v[48:49] op_sel_hi:[1,0,1]
	v_cvt_scalef32_pk_f32_fp4 v[228:229], v218, 1.0 op_sel:[0,1,0]
	v_pk_fma_f32 v[108:109], v[224:225], v[122:123], v[108:109] op_sel_hi:[1,0,1]
	v_cvt_scalef32_pk_f32_fp4 v[230:231], v218, 1.0 op_sel:[1,1,0]
	v_pk_fma_f32 v[106:107], v[226:227], v[122:123], v[106:107] op_sel_hi:[1,0,1]
	v_cvt_scalef32_pk_f32_fp4 v[224:225], v219, 1.0
	v_pk_fma_f32 v[98:99], v[228:229], v[122:123], v[98:99] op_sel_hi:[1,0,1]
	v_cvt_scalef32_pk_f32_fp4 v[226:227], v219, 1.0 op_sel:[1,0,0]
	v_pk_fma_f32 v[56:57], v[230:231], v[122:123], v[56:57] op_sel_hi:[1,0,1]
	v_cvt_scalef32_pk_f32_fp4 v[228:229], v219, 1.0 op_sel:[0,1,0]
	v_pk_fma_f32 v[50:51], v[224:225], v[122:123], v[50:51] op_sel_hi:[1,0,1]
	v_cvt_scalef32_pk_f32_fp4 v[230:231], v219, 1.0 op_sel:[1,1,0]
	v_pk_fma_f32 v[116:117], v[226:227], v[122:123], v[116:117] op_sel_hi:[1,0,1]
	v_pk_fma_f32 v[112:113], v[228:229], v[122:123], v[112:113] op_sel_hi:[1,0,1]
	v_pk_fma_f32 v[104:105], v[230:231], v[122:123], v[104:105] op_sel_hi:[1,0,1]
	s_waitcnt vmcnt(0)
	v_cvt_scalef32_pk_f32_fp4 v[224:225], v220, 1.0
	v_cvt_scalef32_pk_f32_fp4 v[226:227], v220, 1.0 op_sel:[1,0,0]
	v_cvt_scalef32_pk_f32_fp4 v[228:229], v220, 1.0 op_sel:[0,1,0]
	v_pk_fma_f32 v[114:115], v[224:225], v[124:125], v[114:115] op_sel_hi:[1,0,1]
	v_cvt_scalef32_pk_f32_fp4 v[230:231], v220, 1.0 op_sel:[1,1,0]
	v_pk_fma_f32 v[110:111], v[226:227], v[124:125], v[110:111] op_sel_hi:[1,0,1]
	v_cvt_scalef32_pk_f32_fp4 v[224:225], v221, 1.0
	v_pk_fma_f32 v[102:103], v[228:229], v[124:125], v[102:103] op_sel_hi:[1,0,1]
	v_cvt_scalef32_pk_f32_fp4 v[226:227], v221, 1.0 op_sel:[1,0,0]
	v_pk_fma_f32 v[100:101], v[230:231], v[124:125], v[100:101] op_sel_hi:[1,0,1]
	v_cvt_scalef32_pk_f32_fp4 v[228:229], v221, 1.0 op_sel:[0,1,0]
	v_pk_fma_f32 v[54:55], v[224:225], v[124:125], v[54:55] op_sel_hi:[1,0,1]
	v_cvt_scalef32_pk_f32_fp4 v[230:231], v221, 1.0 op_sel:[1,1,0]
	v_pk_fma_f32 v[58:59], v[226:227], v[124:125], v[58:59] op_sel_hi:[1,0,1]
	v_cvt_scalef32_pk_f32_fp4 v[224:225], v222, 1.0
	v_pk_fma_f32 v[52:53], v[228:229], v[124:125], v[52:53] op_sel_hi:[1,0,1]
	v_cvt_scalef32_pk_f32_fp4 v[226:227], v222, 1.0 op_sel:[1,0,0]
	v_pk_fma_f32 v[48:49], v[230:231], v[124:125], v[48:49] op_sel_hi:[1,0,1]
	v_cvt_scalef32_pk_f32_fp4 v[228:229], v222, 1.0 op_sel:[0,1,0]
	v_pk_fma_f32 v[108:109], v[224:225], v[124:125], v[108:109] op_sel_hi:[1,0,1]
	v_cvt_scalef32_pk_f32_fp4 v[230:231], v222, 1.0 op_sel:[1,1,0]
	v_pk_fma_f32 v[106:107], v[226:227], v[124:125], v[106:107] op_sel_hi:[1,0,1]
	v_cvt_scalef32_pk_f32_fp4 v[224:225], v223, 1.0
	v_pk_fma_f32 v[98:99], v[228:229], v[124:125], v[98:99] op_sel_hi:[1,0,1]
	v_cvt_scalef32_pk_f32_fp4 v[226:227], v223, 1.0 op_sel:[1,0,0]
	v_pk_fma_f32 v[56:57], v[230:231], v[124:125], v[56:57] op_sel_hi:[1,0,1]
	v_cvt_scalef32_pk_f32_fp4 v[228:229], v223, 1.0 op_sel:[0,1,0]
	v_pk_fma_f32 v[50:51], v[224:225], v[124:125], v[50:51] op_sel_hi:[1,0,1]
	v_cvt_scalef32_pk_f32_fp4 v[230:231], v223, 1.0 op_sel:[1,1,0]
	v_pk_fma_f32 v[116:117], v[226:227], v[124:125], v[116:117] op_sel_hi:[1,0,1]
	v_pk_fma_f32 v[112:113], v[228:229], v[124:125], v[112:113] op_sel_hi:[1,0,1]
	v_pk_fma_f32 v[104:105], v[230:231], v[124:125], v[104:105] op_sel_hi:[1,0,1]
	ds_bpermute_b32 v32, v138, v114
	ds_bpermute_b32 v33, v138, v115
	ds_bpermute_b32 v128, v138, v112
	ds_bpermute_b32 v129, v138, v113
	ds_bpermute_b32 v118, v138, v108
	ds_bpermute_b32 v119, v138, v109
	ds_bpermute_b32 v34, v138, v110
	ds_bpermute_b32 v35, v138, v111
	ds_bpermute_b32 v120, v138, v106
	ds_bpermute_b32 v121, v138, v107
	s_waitcnt lgkmcnt(8)
	v_pk_add_f32 v[32:33], v[114:115], v[32:33]
	s_waitcnt lgkmcnt(6)
	v_pk_add_f32 v[112:113], v[112:113], v[128:129]
	v_pk_fma_f32 v[24:25], v[24:25], s[18:19], v[32:33] op_sel_hi:[1,0,1]
	v_pk_fma_f32 v[20:21], v[20:21], s[18:19], v[112:113] op_sel_hi:[1,0,1]
	ds_bpermute_b32 v112, v138, v104
	ds_bpermute_b32 v113, v138, v105
	v_add_f32_e32 v32, 0, v24
	ds_bpermute_b32 v36, v138, v102
	ds_bpermute_b32 v37, v138, v103
	v_add_f32_e32 v94, v32, v25
	s_waitcnt lgkmcnt(8)
	v_pk_add_f32 v[32:33], v[108:109], v[118:119]
	ds_bpermute_b32 v122, v138, v98
	ds_bpermute_b32 v123, v138, v99
	v_pk_fma_f32 v[28:29], v[28:29], s[18:19], v[32:33] op_sel_hi:[1,0,1]
	s_waitcnt lgkmcnt(8)
	v_pk_add_f32 v[32:33], v[110:111], v[34:35]
	ds_bpermute_b32 v38, v138, v100
	v_pk_fma_f32 v[26:27], v[26:27], s[18:19], v[32:33] op_sel_hi:[1,0,1]
	s_waitcnt lgkmcnt(7)
	v_pk_add_f32 v[32:33], v[106:107], v[120:121]
	ds_bpermute_b32 v39, v138, v101
	v_pk_fma_f32 v[30:31], v[30:31], s[18:19], v[32:33] op_sel_hi:[1,0,1]
	v_add_f32_e32 v32, v94, v26
	ds_bpermute_b32 v124, v138, v56
	ds_bpermute_b32 v125, v138, v57
	v_add_f32_e32 v34, v32, v27
	s_waitcnt lgkmcnt(8)
	v_pk_add_f32 v[32:33], v[104:105], v[112:113]
	ds_bpermute_b32 v40, v138, v54
	v_pk_fma_f32 v[22:23], v[22:23], s[18:19], v[32:33] op_sel_hi:[1,0,1]
	s_waitcnt lgkmcnt(7)
	v_pk_add_f32 v[32:33], v[102:103], v[36:37]
	ds_bpermute_b32 v41, v138, v55
	v_pk_fma_f32 v[12:13], v[12:13], s[18:19], v[32:33] op_sel_hi:[1,0,1]
	s_waitcnt lgkmcnt(6)
	v_pk_add_f32 v[32:33], v[98:99], v[122:123]
	ds_bpermute_b32 v132, v138, v50
	ds_bpermute_b32 v133, v138, v51
	v_pk_fma_f32 v[16:17], v[16:17], s[18:19], v[32:33] op_sel_hi:[1,0,1]
	v_add_f32_e32 v32, v34, v12
	v_add_f32_e32 v34, v32, v13
	s_waitcnt lgkmcnt(6)
	v_pk_add_f32 v[32:33], v[100:101], v[38:39]
	ds_bpermute_b32 v42, v138, v58
	ds_bpermute_b32 v43, v138, v59
	v_pk_fma_f32 v[14:15], v[14:15], s[18:19], v[32:33] op_sel_hi:[1,0,1]
	s_waitcnt lgkmcnt(6)
	v_pk_add_f32 v[32:33], v[56:57], v[124:125]
	ds_bpermute_b32 v44, v138, v52
	v_pk_fma_f32 v[18:19], v[18:19], s[18:19], v[32:33] op_sel_hi:[1,0,1]
	v_add_f32_e32 v32, v34, v14
	v_add_f32_e32 v34, v32, v15
	s_waitcnt lgkmcnt(5)
	v_pk_add_f32 v[32:33], v[54:55], v[40:41]
	ds_bpermute_b32 v45, v138, v53
	v_pk_fma_f32 v[32:33], v[4:5], s[18:19], v[32:33] op_sel_hi:[1,0,1]
	s_waitcnt lgkmcnt(4)
	v_pk_add_f32 v[4:5], v[50:51], v[132:133]
	ds_bpermute_b32 v46, v138, v48
	v_pk_fma_f32 v[8:9], v[8:9], s[18:19], v[4:5] op_sel_hi:[1,0,1]
	v_add_f32_e32 v4, v34, v32
	v_add_f32_e32 v36, v4, v33
	s_waitcnt lgkmcnt(3)
	v_pk_add_f32 v[4:5], v[58:59], v[42:43]
	ds_bpermute_b32 v47, v138, v49
	v_pk_fma_f32 v[34:35], v[6:7], s[18:19], v[4:5] op_sel_hi:[1,0,1]
	ds_bpermute_b32 v126, v138, v116
	v_add_f32_e32 v4, v36, v34
	v_add_f32_e32 v6, v4, v35
	s_waitcnt lgkmcnt(3)
	v_pk_add_f32 v[4:5], v[52:53], v[44:45]
	ds_bpermute_b32 v127, v138, v117
	v_pk_fma_f32 v[36:37], v[0:1], s[18:19], v[4:5] op_sel_hi:[1,0,1]
	v_mov_b32_e32 v94, v147
	v_add_f32_e32 v0, v6, v36
	v_add_f32_e32 v4, v0, v37
	s_waitcnt lgkmcnt(2)
	v_pk_add_f32 v[0:1], v[48:49], v[46:47]
	s_waitcnt lgkmcnt(0)
	v_pk_add_f32 v[116:117], v[116:117], v[126:127]
	v_pk_fma_f32 v[38:39], v[2:3], s[18:19], v[0:1] op_sel_hi:[1,0,1]
	v_pk_fma_f32 v[10:11], v[10:11], s[18:19], v[116:117] op_sel_hi:[1,0,1]
	v_add_f32_e32 v0, v4, v38
	v_add_f32_e32 v0, v0, v39
	v_add_f32_e32 v0, v0, v28
	v_add_f32_e32 v0, v0, v29
	v_add_f32_e32 v0, v0, v30
	v_add_f32_e32 v0, v0, v31
	v_add_f32_e32 v0, v0, v16
	v_add_f32_e32 v0, v0, v17
	v_add_f32_e32 v0, v0, v18
	v_add_f32_e32 v0, v0, v19
	v_add_f32_e32 v0, v0, v8
	v_add_f32_e32 v0, v0, v9
	v_add_f32_e32 v0, v0, v10
	v_add_f32_e32 v0, v0, v11
	v_add_f32_e32 v0, v0, v20
	v_add_f32_e32 v0, v0, v21
	v_add_f32_e32 v0, v0, v22
	v_add_f32_e32 v0, v0, v23
	ds_bpermute_b32 v1, v61, v0
	v_mov_b32_e32 v96, v148
	s_waitcnt lgkmcnt(0)
	v_add_f32_e32 v0, v0, v1
	ds_bpermute_b32 v1, v63, v0
	s_waitcnt lgkmcnt(0)
	v_add_f32_e32 v0, v0, v1
	ds_bpermute_b32 v1, v131, v0
	s_waitcnt lgkmcnt(0)
	v_add_f32_e32 v0, v0, v1
	ds_bpermute_b32 v1, v136, v0
	s_waitcnt lgkmcnt(0)
	v_add_f32_e32 v40, v0, v1
	ds_bpermute_b32 v41, v137, v40
	global_load_dwordx4 v[0:3], v[70:71], off
	global_load_dwordx4 v[4:7], v[72:73], off
	s_waitcnt lgkmcnt(0)
	v_add_f32_e32 v40, v40, v41
	v_mul_f32_e32 v40, 0x3a800000, v40
	v_pk_add_f32 v[24:25], v[24:25], v[40:41] op_sel_hi:[1,0] neg_lo:[0,1] neg_hi:[0,1]
	v_pk_add_f32 v[26:27], v[26:27], v[40:41] op_sel_hi:[1,0] neg_lo:[0,1] neg_hi:[0,1]
	v_pk_mul_f32 v[42:43], v[24:25], v[24:25]
	v_pk_mul_f32 v[44:45], v[26:27], v[26:27]
	v_add_f32_e32 v42, v42, v43
	v_pk_add_f32 v[12:13], v[12:13], v[40:41] op_sel_hi:[1,0] neg_lo:[0,1] neg_hi:[0,1]
	v_add_f32_e32 v42, v44, v42
	v_pk_mul_f32 v[46:47], v[12:13], v[12:13]
	v_add_f32_e32 v42, v45, v42
	v_pk_add_f32 v[14:15], v[14:15], v[40:41] op_sel_hi:[1,0] neg_lo:[0,1] neg_hi:[0,1]
	v_add_f32_e32 v42, v46, v42
	v_pk_mul_f32 v[48:49], v[14:15], v[14:15]
	v_add_f32_e32 v42, v47, v42
	v_pk_add_f32 v[32:33], v[32:33], v[40:41] op_sel_hi:[1,0] neg_lo:[0,1] neg_hi:[0,1]
	v_add_f32_e32 v42, v48, v42
	v_pk_mul_f32 v[50:51], v[32:33], v[32:33]
	v_add_f32_e32 v42, v49, v42
	v_pk_add_f32 v[34:35], v[34:35], v[40:41] op_sel_hi:[1,0] neg_lo:[0,1] neg_hi:[0,1]
	v_add_f32_e32 v42, v50, v42
	v_pk_mul_f32 v[52:53], v[34:35], v[34:35]
	v_add_f32_e32 v42, v51, v42
	v_pk_add_f32 v[36:37], v[36:37], v[40:41] op_sel_hi:[1,0] neg_lo:[0,1] neg_hi:[0,1]
	v_add_f32_e32 v42, v52, v42
	v_pk_mul_f32 v[54:55], v[36:37], v[36:37]
	v_add_f32_e32 v42, v53, v42
	v_pk_add_f32 v[38:39], v[38:39], v[40:41] op_sel_hi:[1,0] neg_lo:[0,1] neg_hi:[0,1]
	v_add_f32_e32 v42, v54, v42
	v_pk_mul_f32 v[56:57], v[38:39], v[38:39]
	v_add_f32_e32 v42, v55, v42
	v_pk_add_f32 v[28:29], v[28:29], v[40:41] op_sel_hi:[1,0] neg_lo:[0,1] neg_hi:[0,1]
	v_add_f32_e32 v42, v56, v42
	v_pk_mul_f32 v[58:59], v[28:29], v[28:29]
	v_add_f32_e32 v42, v57, v42
	v_pk_add_f32 v[30:31], v[30:31], v[40:41] op_sel_hi:[1,0] neg_lo:[0,1] neg_hi:[0,1]
	v_add_f32_e32 v42, v58, v42
	v_pk_mul_f32 v[98:99], v[30:31], v[30:31]
	v_add_f32_e32 v42, v59, v42
	v_pk_add_f32 v[16:17], v[16:17], v[40:41] op_sel_hi:[1,0] neg_lo:[0,1] neg_hi:[0,1]
	v_add_f32_e32 v42, v98, v42
	v_pk_mul_f32 v[100:101], v[16:17], v[16:17]
	v_add_f32_e32 v42, v99, v42
	v_pk_add_f32 v[18:19], v[18:19], v[40:41] op_sel_hi:[1,0] neg_lo:[0,1] neg_hi:[0,1]
	v_add_f32_e32 v42, v100, v42
	v_pk_mul_f32 v[102:103], v[18:19], v[18:19]
	v_add_f32_e32 v42, v101, v42
	v_pk_add_f32 v[104:105], v[8:9], v[40:41] op_sel_hi:[1,0] neg_lo:[0,1] neg_hi:[0,1]
	v_add_f32_e32 v42, v102, v42
	v_pk_mul_f32 v[8:9], v[104:105], v[104:105]
	v_add_f32_e32 v42, v103, v42
	v_pk_add_f32 v[106:107], v[10:11], v[40:41] op_sel_hi:[1,0] neg_lo:[0,1] neg_hi:[0,1]
	v_add_f32_e32 v8, v8, v42
	v_pk_mul_f32 v[10:11], v[106:107], v[106:107]
	v_add_f32_e32 v8, v9, v8
	v_pk_add_f32 v[20:21], v[20:21], v[40:41] op_sel_hi:[1,0] neg_lo:[0,1] neg_hi:[0,1]
	v_add_f32_e32 v8, v10, v8
	v_pk_mul_f32 v[108:109], v[20:21], v[20:21]
	v_add_f32_e32 v8, v11, v8
	v_pk_add_f32 v[22:23], v[22:23], v[40:41] op_sel_hi:[1,0] neg_lo:[0,1] neg_hi:[0,1]
	v_add_f32_e32 v8, v108, v8
	v_pk_mul_f32 v[40:41], v[22:23], v[22:23]
	v_add_f32_e32 v8, v109, v8
	v_add_f32_e32 v8, v40, v8
	v_add_f32_e32 v8, v41, v8
	ds_bpermute_b32 v9, v61, v8
	v_lshl_add_u64 v[40:41], v[92:93], 0, v[64:65]
	v_cndmask_b32_e64 v13, v17, v13, s[6:7]
	v_cndmask_b32_e64 v12, v16, v12, s[6:7]
	v_cndmask_b32_e64 v15, v19, v15, s[6:7]
	s_waitcnt lgkmcnt(0)
	v_add_f32_e32 v8, v8, v9
	ds_bpermute_b32 v9, v63, v8
	v_cndmask_b32_e64 v14, v18, v14, s[6:7]
	v_cndmask_b32_e64 v17, v105, v33, s[6:7]
	v_cndmask_b32_e64 v16, v104, v32, s[6:7]
	v_cndmask_b32_e64 v19, v107, v35, s[6:7]
	s_waitcnt lgkmcnt(0)
	v_add_f32_e32 v8, v8, v9
	ds_bpermute_b32 v9, v131, v8
	v_cndmask_b32_e64 v18, v106, v34, s[6:7]
	v_cndmask_b32_e64 v21, v21, v37, s[6:7]
	v_cndmask_b32_e64 v20, v20, v36, s[6:7]
	v_cndmask_b32_e64 v23, v23, v39, s[6:7]
	s_waitcnt lgkmcnt(0)
	v_add_f32_e32 v8, v8, v9
	ds_bpermute_b32 v9, v136, v8
	v_cndmask_b32_e64 v22, v22, v38, s[6:7]
	v_mov_b32_e32 v32, v97
	s_waitcnt lgkmcnt(0)
	v_add_f32_e32 v8, v8, v9
	ds_bpermute_b32 v9, v137, v8
	s_waitcnt lgkmcnt(0)
	v_add_f32_e32 v8, v8, v9
	v_fmamk_f32 v8, v8, 0x3a800000, v146
	v_mul_f32_e32 v9, 0x4b800000, v8
	v_cmp_gt_f32_e64 s[0:1], s20, v8
	s_nop 1
	v_cndmask_b32_e64 v8, v8, v9, s[0:1]
	v_rsq_f32_e32 v8, v8
	s_nop 0
	v_mul_f32_e32 v9, 0x45800000, v8
	v_cndmask_b32_e64 v42, v8, v9, s[0:1]
	v_cndmask_b32_e64 v9, v29, v25, s[6:7]
	v_cndmask_b32_e64 v8, v28, v24, s[6:7]
	v_pk_mul_f32 v[8:9], v[8:9], v[42:43] op_sel_hi:[1,0]
	v_pk_mul_f32 v[12:13], v[12:13], v[42:43] op_sel_hi:[1,0]
	s_waitcnt vmcnt(0)
	v_pk_fma_f32 v[0:1], v[0:1], v[8:9], v[4:5]
	v_cndmask_b32_e64 v5, v31, v27, s[6:7]
	v_cndmask_b32_e64 v4, v30, v26, s[6:7]
	v_pk_mul_f32 v[4:5], v[4:5], v[42:43] op_sel_hi:[1,0]
	v_pk_mul_f32 v[14:15], v[14:15], v[42:43] op_sel_hi:[1,0]
	v_pk_fma_f32 v[2:3], v[2:3], v[4:5], v[6:7]
	global_store_dwordx4 v[40:41], v[0:3], off
	global_load_dwordx4 v[4:7], v[74:75], off
	global_load_dwordx4 v[8:11], v[76:77], off
	v_pk_mul_f32 v[16:17], v[16:17], v[42:43] op_sel_hi:[1,0]
	v_pk_mul_f32 v[18:19], v[18:19], v[42:43] op_sel_hi:[1,0]
	v_lshlrev_b64 v[24:25], 11, v[90:91]
	v_pk_mul_f32 v[20:21], v[20:21], v[42:43] op_sel_hi:[1,0]
	v_pk_mul_f32 v[22:23], v[22:23], v[42:43] op_sel_hi:[1,0]
	v_lshl_add_u64 v[24:25], v[86:87], 0, v[24:25]
	v_cvt_pk_bf16_f32 v0, v0, v1
	v_cvt_pk_bf16_f32 v1, v2, v3
	s_waitcnt vmcnt(0)
	v_pk_fma_f32 v[4:5], v[4:5], v[12:13], v[8:9]
	v_pk_fma_f32 v[6:7], v[6:7], v[14:15], v[10:11]
	global_store_dwordx4 v[40:41], v[4:7], off offset:16
	global_load_dwordx4 v[8:11], v[78:79], off
	global_load_dwordx4 v[12:15], v[80:81], off
	v_cvt_pk_bf16_f32 v2, v4, v5
	v_cvt_pk_bf16_f32 v3, v6, v7
	s_waitcnt vmcnt(0)
	v_pk_fma_f32 v[8:9], v[8:9], v[16:17], v[12:13]
	v_pk_fma_f32 v[10:11], v[10:11], v[18:19], v[14:15]
	global_store_dwordx4 v[40:41], v[8:11], off offset:32
	global_load_dwordx4 v[12:15], v[82:83], off
	global_load_dwordx4 v[16:19], v[84:85], off
	v_cvt_pk_bf16_f32 v4, v8, v9
	v_cvt_pk_bf16_f32 v5, v10, v11
	s_waitcnt vmcnt(0)
	v_pk_fma_f32 v[6:7], v[12:13], v[20:21], v[16:17]
	v_pk_fma_f32 v[8:9], v[14:15], v[22:23], v[18:19]
	global_store_dwordx4 v[40:41], v[6:9], off offset:48
	s_nop 1
	v_cvt_pk_bf16_f32 v6, v6, v7
	v_cvt_pk_bf16_f32 v7, v8, v9
	global_store_dwordx4 v[24:25], v[0:3], off
	global_store_dwordx4 v[24:25], v[4:7], off offset:16
	s_andn2_b64 exec, exec, s[16:17]
	s_cbranch_execnz .LBB0_389

.Lxg_loop_p12:
	s_waitcnt lgkmcnt(0)
	v_lshl_add_u32 v250, v240, 9, v241
	v_lshl_add_u32 v251, v242, 9, v241
	v_lshl_add_u32 v252, v246, 9, v241
	v_lshl_add_u32 v253, v248, 9, v241
	global_load_dwordx4 v[192:195], v250, s[98:99]
	global_load_dwordx4 v[196:199], v251, s[98:99]
	global_load_dwordx4 v[200:203], v252, s[98:99]
	global_load_dwordx4 v[204:207], v253, s[98:99]
	global_load_dwordx4 v[208:211], v250, s[100:101]
	global_load_dwordx4 v[212:215], v251, s[100:101]
	global_load_dwordx4 v[216:219], v252, s[100:101]
	global_load_dwordx4 v[220:223], v253, s[100:101]
	s_add_u32 s20, s19, 2
	s_cmp_lt_u32 s20, 8
	s_cselect_b64 s[4:5], -1, 0
	s_and_b32 s20, s20, 7
	s_lshl_b32 s20, s20, 5
	v_cndmask_b32_e64 v126, v94, v92, s[4:5]
	v_lshl_add_u32 v129, v136, 2, s20
	ds_bpermute_b32 v240, v129, v126
	ds_bpermute_b32 v242, v129, v126 offset:8
	ds_bpermute_b32 v246, v129, v126 offset:16
	ds_bpermute_b32 v248, v129, v126 offset:24
	s_add_u32 s20, s19, 0
	s_cmp_lt_u32 s20, 8
	s_cselect_b64 s[4:5], -1, 0
	s_and_b32 s20, s20, 7
	s_lshl_b32 s20, s20, 5
	v_cndmask_b32_e64 v127, v147, v146, s[4:5]
	v_cndmask_b32_e64 v128, v149, v148, s[4:5]
	v_lshl_add_u32 v130, v137, 2, s20
	ds_bpermute_b32 v156, v130, v127
	ds_bpermute_b32 v157, v130, v128
	s_waitcnt vmcnt(14)
	v_cvt_scalef32_pk_f32_fp4 v[224:225], v160, 1.0
	v_cvt_scalef32_pk_f32_fp4 v[226:227], v164, 1.0
	v_cvt_scalef32_pk_f32_fp4 v[228:229], v160, 1.0 op_sel:[1,0,0]
	v_cvt_scalef32_pk_f32_fp4 v[230:231], v164, 1.0 op_sel:[1,0,0]
	v_pk_fma_f32 v[232:233], v[24:25], v[224:225], 0 op_sel_hi:[1,1,0]
	v_pk_fma_f32 v[234:235], v[24:25], v[226:227], 0 op_sel_hi:[1,1,0]
	v_cvt_scalef32_pk_f32_fp4 v[224:225], v160, 1.0 op_sel:[0,1,0]
	v_cvt_scalef32_pk_f32_fp4 v[226:227], v164, 1.0 op_sel:[0,1,0]
	v_pk_fma_f32 v[232:233], v[26:27], v[228:229], v[232:233]
	v_pk_fma_f32 v[234:235], v[26:27], v[230:231], v[234:235]
	v_cvt_scalef32_pk_f32_fp4 v[228:229], v160, 1.0 op_sel:[1,1,0]
	v_cvt_scalef32_pk_f32_fp4 v[230:231], v164, 1.0 op_sel:[1,1,0]
	v_pk_fma_f32 v[232:233], v[12:13], v[224:225], v[232:233]
	v_pk_fma_f32 v[234:235], v[12:13], v[226:227], v[234:235]
	v_cvt_scalef32_pk_f32_fp4 v[224:225], v161, 1.0
	v_cvt_scalef32_pk_f32_fp4 v[226:227], v165, 1.0
	v_pk_fma_f32 v[232:233], v[14:15], v[228:229], v[232:233]
	v_pk_fma_f32 v[234:235], v[14:15], v[230:231], v[234:235]
	v_cvt_scalef32_pk_f32_fp4 v[228:229], v161, 1.0 op_sel:[1,0,0]
	v_cvt_scalef32_pk_f32_fp4 v[230:231], v165, 1.0 op_sel:[1,0,0]
	v_pk_fma_f32 v[232:233], v[4:5], v[224:225], v[232:233]
	v_pk_fma_f32 v[234:235], v[4:5], v[226:227], v[234:235]
	v_cvt_scalef32_pk_f32_fp4 v[224:225], v161, 1.0 op_sel:[0,1,0]
	v_cvt_scalef32_pk_f32_fp4 v[226:227], v165, 1.0 op_sel:[0,1,0]
	v_pk_fma_f32 v[232:233], v[6:7], v[228:229], v[232:233]
	v_pk_fma_f32 v[234:235], v[6:7], v[230:231], v[234:235]
	v_cvt_scalef32_pk_f32_fp4 v[228:229], v161, 1.0 op_sel:[1,1,0]
	v_cvt_scalef32_pk_f32_fp4 v[230:231], v165, 1.0 op_sel:[1,1,0]
	v_pk_fma_f32 v[232:233], v[0:1], v[224:225], v[232:233]
	v_pk_fma_f32 v[234:235], v[0:1], v[226:227], v[234:235]
	v_cvt_scalef32_pk_f32_fp4 v[224:225], v162, 1.0
	v_cvt_scalef32_pk_f32_fp4 v[226:227], v166, 1.0
	v_pk_fma_f32 v[232:233], v[2:3], v[228:229], v[232:233]
	v_pk_fma_f32 v[234:235], v[2:3], v[230:231], v[234:235]
	v_cvt_scalef32_pk_f32_fp4 v[228:229], v162, 1.0 op_sel:[1,0,0]
	v_cvt_scalef32_pk_f32_fp4 v[230:231], v166, 1.0 op_sel:[1,0,0]
	v_pk_fma_f32 v[232:233], v[28:29], v[224:225], v[232:233]
	v_pk_fma_f32 v[234:235], v[28:29], v[226:227], v[234:235]
	v_cvt_scalef32_pk_f32_fp4 v[224:225], v162, 1.0 op_sel:[0,1,0]
	v_cvt_scalef32_pk_f32_fp4 v[226:227], v166, 1.0 op_sel:[0,1,0]
	v_pk_fma_f32 v[232:233], v[30:31], v[228:229], v[232:233]
	v_pk_fma_f32 v[234:235], v[30:31], v[230:231], v[234:235]
	v_cvt_scalef32_pk_f32_fp4 v[228:229], v162, 1.0 op_sel:[1,1,0]
	v_cvt_scalef32_pk_f32_fp4 v[230:231], v166, 1.0 op_sel:[1,1,0]
	v_pk_fma_f32 v[232:233], v[16:17], v[224:225], v[232:233]
	v_pk_fma_f32 v[234:235], v[16:17], v[226:227], v[234:235]
	v_cvt_scalef32_pk_f32_fp4 v[224:225], v163, 1.0
	v_cvt_scalef32_pk_f32_fp4 v[226:227], v167, 1.0
	v_pk_fma_f32 v[232:233], v[18:19], v[228:229], v[232:233]
	v_pk_fma_f32 v[234:235], v[18:19], v[230:231], v[234:235]
	v_cvt_scalef32_pk_f32_fp4 v[228:229], v163, 1.0 op_sel:[1,0,0]
	v_cvt_scalef32_pk_f32_fp4 v[230:231], v167, 1.0 op_sel:[1,0,0]
	v_pk_fma_f32 v[232:233], v[8:9], v[224:225], v[232:233]
	v_pk_fma_f32 v[234:235], v[8:9], v[226:227], v[234:235]
	v_cvt_scalef32_pk_f32_fp4 v[224:225], v163, 1.0 op_sel:[0,1,0]
	v_cvt_scalef32_pk_f32_fp4 v[226:227], v167, 1.0 op_sel:[0,1,0]
	v_pk_fma_f32 v[232:233], v[10:11], v[228:229], v[232:233]
	v_pk_fma_f32 v[234:235], v[10:11], v[230:231], v[234:235]
	v_cvt_scalef32_pk_f32_fp4 v[228:229], v163, 1.0 op_sel:[1,1,0]
	v_cvt_scalef32_pk_f32_fp4 v[230:231], v167, 1.0 op_sel:[1,1,0]
	v_pk_fma_f32 v[232:233], v[20:21], v[224:225], v[232:233]
	v_pk_fma_f32 v[234:235], v[20:21], v[226:227], v[234:235]
	v_pk_fma_f32 v[232:233], v[22:23], v[228:229], v[232:233]
	v_pk_fma_f32 v[234:235], v[22:23], v[230:231], v[234:235]
	v_add_f32_e32 v32, v232, v233
	v_add_f32_e32 v33, v234, v235
	s_waitcnt vmcnt(12)
	v_cvt_scalef32_pk_f32_fp4 v[224:225], v168, 1.0
	v_cvt_scalef32_pk_f32_fp4 v[226:227], v172, 1.0
	v_cvt_scalef32_pk_f32_fp4 v[228:229], v168, 1.0 op_sel:[1,0,0]
	v_cvt_scalef32_pk_f32_fp4 v[230:231], v172, 1.0 op_sel:[1,0,0]
	v_pk_fma_f32 v[236:237], v[24:25], v[224:225], 0 op_sel_hi:[1,1,0]
	v_pk_fma_f32 v[238:239], v[24:25], v[226:227], 0 op_sel_hi:[1,1,0]
	v_cvt_scalef32_pk_f32_fp4 v[224:225], v168, 1.0 op_sel:[0,1,0]
	v_cvt_scalef32_pk_f32_fp4 v[226:227], v172, 1.0 op_sel:[0,1,0]
	v_pk_fma_f32 v[236:237], v[26:27], v[228:229], v[236:237]
	v_pk_fma_f32 v[238:239], v[26:27], v[230:231], v[238:239]
	v_cvt_scalef32_pk_f32_fp4 v[228:229], v168, 1.0 op_sel:[1,1,0]
	v_cvt_scalef32_pk_f32_fp4 v[230:231], v172, 1.0 op_sel:[1,1,0]
	v_pk_fma_f32 v[236:237], v[12:13], v[224:225], v[236:237]
	v_pk_fma_f32 v[238:239], v[12:13], v[226:227], v[238:239]
	v_cvt_scalef32_pk_f32_fp4 v[224:225], v169, 1.0
	v_cvt_scalef32_pk_f32_fp4 v[226:227], v173, 1.0
	v_pk_fma_f32 v[236:237], v[14:15], v[228:229], v[236:237]
	v_pk_fma_f32 v[238:239], v[14:15], v[230:231], v[238:239]
	v_cvt_scalef32_pk_f32_fp4 v[228:229], v169, 1.0 op_sel:[1,0,0]
	v_cvt_scalef32_pk_f32_fp4 v[230:231], v173, 1.0 op_sel:[1,0,0]
	v_pk_fma_f32 v[236:237], v[4:5], v[224:225], v[236:237]
	v_pk_fma_f32 v[238:239], v[4:5], v[226:227], v[238:239]
	v_cvt_scalef32_pk_f32_fp4 v[224:225], v169, 1.0 op_sel:[0,1,0]
	v_cvt_scalef32_pk_f32_fp4 v[226:227], v173, 1.0 op_sel:[0,1,0]
	v_pk_fma_f32 v[236:237], v[6:7], v[228:229], v[236:237]
	v_pk_fma_f32 v[238:239], v[6:7], v[230:231], v[238:239]
	v_cvt_scalef32_pk_f32_fp4 v[228:229], v169, 1.0 op_sel:[1,1,0]
	v_cvt_scalef32_pk_f32_fp4 v[230:231], v173, 1.0 op_sel:[1,1,0]
	v_pk_fma_f32 v[236:237], v[0:1], v[224:225], v[236:237]
	v_pk_fma_f32 v[238:239], v[0:1], v[226:227], v[238:239]
	v_cvt_scalef32_pk_f32_fp4 v[224:225], v170, 1.0
	v_cvt_scalef32_pk_f32_fp4 v[226:227], v174, 1.0
	v_pk_fma_f32 v[236:237], v[2:3], v[228:229], v[236:237]
	v_pk_fma_f32 v[238:239], v[2:3], v[230:231], v[238:239]
	v_cvt_scalef32_pk_f32_fp4 v[228:229], v170, 1.0 op_sel:[1,0,0]
	v_cvt_scalef32_pk_f32_fp4 v[230:231], v174, 1.0 op_sel:[1,0,0]
	v_pk_fma_f32 v[236:237], v[28:29], v[224:225], v[236:237]
	v_pk_fma_f32 v[238:239], v[28:29], v[226:227], v[238:239]
	v_cvt_scalef32_pk_f32_fp4 v[224:225], v170, 1.0 op_sel:[0,1,0]
	v_cvt_scalef32_pk_f32_fp4 v[226:227], v174, 1.0 op_sel:[0,1,0]
	v_pk_fma_f32 v[236:237], v[30:31], v[228:229], v[236:237]
	v_pk_fma_f32 v[238:239], v[30:31], v[230:231], v[238:239]
	v_cvt_scalef32_pk_f32_fp4 v[228:229], v170, 1.0 op_sel:[1,1,0]
	v_cvt_scalef32_pk_f32_fp4 v[230:231], v174, 1.0 op_sel:[1,1,0]
	v_pk_fma_f32 v[236:237], v[16:17], v[224:225], v[236:237]
	v_pk_fma_f32 v[238:239], v[16:17], v[226:227], v[238:239]
	v_cvt_scalef32_pk_f32_fp4 v[224:225], v171, 1.0
	v_cvt_scalef32_pk_f32_fp4 v[226:227], v175, 1.0
	v_pk_fma_f32 v[236:237], v[18:19], v[228:229], v[236:237]
	v_pk_fma_f32 v[238:239], v[18:19], v[230:231], v[238:239]
	v_cvt_scalef32_pk_f32_fp4 v[228:229], v171, 1.0 op_sel:[1,0,0]
	v_cvt_scalef32_pk_f32_fp4 v[230:231], v175, 1.0 op_sel:[1,0,0]
	v_pk_fma_f32 v[236:237], v[8:9], v[224:225], v[236:237]
	v_pk_fma_f32 v[238:239], v[8:9], v[226:227], v[238:239]
	v_cvt_scalef32_pk_f32_fp4 v[224:225], v171, 1.0 op_sel:[0,1,0]
	v_cvt_scalef32_pk_f32_fp4 v[226:227], v175, 1.0 op_sel:[0,1,0]
	v_pk_fma_f32 v[236:237], v[10:11], v[228:229], v[236:237]
	v_pk_fma_f32 v[238:239], v[10:11], v[230:231], v[238:239]
	v_cvt_scalef32_pk_f32_fp4 v[228:229], v171, 1.0 op_sel:[1,1,0]
	v_cvt_scalef32_pk_f32_fp4 v[230:231], v175, 1.0 op_sel:[1,1,0]
	v_pk_fma_f32 v[236:237], v[20:21], v[224:225], v[236:237]
	v_pk_fma_f32 v[238:239], v[20:21], v[226:227], v[238:239]
	v_pk_fma_f32 v[236:237], v[22:23], v[228:229], v[236:237]
	v_pk_fma_f32 v[238:239], v[22:23], v[230:231], v[238:239]
	v_add_f32_e32 v34, v236, v237
	v_add_f32_e32 v35, v238, v239
	s_nop 1
	v_permlane16_swap_b32_e32 v32, v34
	v_permlane16_swap_b32_e32 v33, v35
	v_add_f32_e32 v36, v32, v34
	v_add_f32_e32 v38, v33, v35
	s_waitcnt lgkmcnt(0)
	v_cndmask_b32_e64 v40, v38, v36, s[0:1]
	v_cndmask_b32_e64 v41, v36, v38, s[0:1]
	s_nop 1
	v_add_f32_dpp v40, v41, v40 row_ror:8 row_mask:0xf bank_mask:0xf
	s_nop 1
	v_add_f32_dpp v40, v40, v40 quad_perm:[1,0,3,2] row_mask:0xf bank_mask:0xf
	s_nop 1
	v_add_f32_dpp v40, v40, v40 quad_perm:[2,3,0,1] row_mask:0xf bank_mask:0xf
	s_nop 1
	v_add_f32_dpp v40, v40, v40 row_half_mirror row_mask:0xf bank_mask:0xf
	v_mul_f32_e32 v42, v40, v156
	v_fma_f32 v43, |v42|, s16, 1.0
	v_rcp_f32_e32 v43, v43
	v_cmp_gt_f32_e64 s[4:5], 0, v42
	v_mul_f32_e32 v45, v42, v42
	v_fmamk_f32 v44, v43, 0x3f07dc22, v142
	v_fmaak_f32 v44, v43, v44, 0x3f35f0e3
	v_fmaak_f32 v44, v43, v44, 0xbe11a98e
	v_fmaak_f32 v44, v43, v44, 0x3e027906
	v_mul_f32_e32 v45, 0xbf38aa3b, v45
	v_exp_f32_e32 v45, v45
	v_mul_f32_e32 v43, v43, v44
	v_mul_f32_e32 v43, v45, v43
	v_mul_f32_e32 v44, v42, v43
	v_fma_f32 v42, -v42, v43, v42
	v_cndmask_b32_e64 v42, v42, v44, s[4:5]
	v_mul_f32_e32 v158, v42, v157
	ds_bpermute_b32 v118, v138, v158
	ds_bpermute_b32 v120, v139, v158
	ds_bpermute_b32 v122, v140, v158
	ds_bpermute_b32 v124, v141, v158
	s_waitcnt vmcnt(11)
	v_cvt_scalef32_pk_f32_fp4 v[224:225], v176, 1.0
	v_cvt_scalef32_pk_f32_fp4 v[226:227], v176, 1.0 op_sel:[1,0,0]
	s_waitcnt lgkmcnt(0)
	v_cvt_scalef32_pk_f32_fp4 v[228:229], v176, 1.0 op_sel:[0,1,0]
	v_pk_fma_f32 v[112:113], v[224:225], v[118:119], v[112:113] op_sel_hi:[1,0,1]
	v_cvt_scalef32_pk_f32_fp4 v[230:231], v176, 1.0 op_sel:[1,1,0]
	v_pk_fma_f32 v[108:109], v[226:227], v[118:119], v[108:109] op_sel_hi:[1,0,1]
	v_cvt_scalef32_pk_f32_fp4 v[224:225], v177, 1.0
	v_pk_fma_f32 v[104:105], v[228:229], v[118:119], v[104:105] op_sel_hi:[1,0,1]
	v_cvt_scalef32_pk_f32_fp4 v[226:227], v177, 1.0 op_sel:[1,0,0]
	v_pk_fma_f32 v[98:99], v[230:231], v[118:119], v[98:99] op_sel_hi:[1,0,1]
	v_cvt_scalef32_pk_f32_fp4 v[228:229], v177, 1.0 op_sel:[0,1,0]
	v_pk_fma_f32 v[54:55], v[224:225], v[118:119], v[54:55] op_sel_hi:[1,0,1]
	v_cvt_scalef32_pk_f32_fp4 v[230:231], v177, 1.0 op_sel:[1,1,0]
	v_pk_fma_f32 v[58:59], v[226:227], v[118:119], v[58:59] op_sel_hi:[1,0,1]
	v_cvt_scalef32_pk_f32_fp4 v[224:225], v178, 1.0
	v_pk_fma_f32 v[52:53], v[228:229], v[118:119], v[52:53] op_sel_hi:[1,0,1]
	v_cvt_scalef32_pk_f32_fp4 v[226:227], v178, 1.0 op_sel:[1,0,0]
	v_pk_fma_f32 v[48:49], v[230:231], v[118:119], v[48:49] op_sel_hi:[1,0,1]
	v_cvt_scalef32_pk_f32_fp4 v[228:229], v178, 1.0 op_sel:[0,1,0]
	v_pk_fma_f32 v[106:107], v[224:225], v[118:119], v[106:107] op_sel_hi:[1,0,1]
	v_cvt_scalef32_pk_f32_fp4 v[230:231], v178, 1.0 op_sel:[1,1,0]
	v_pk_fma_f32 v[102:103], v[226:227], v[118:119], v[102:103] op_sel_hi:[1,0,1]
	v_cvt_scalef32_pk_f32_fp4 v[224:225], v179, 1.0
	v_pk_fma_f32 v[96:97], v[228:229], v[118:119], v[96:97] op_sel_hi:[1,0,1]
	v_cvt_scalef32_pk_f32_fp4 v[226:227], v179, 1.0 op_sel:[1,0,0]
	v_pk_fma_f32 v[56:57], v[230:231], v[118:119], v[56:57] op_sel_hi:[1,0,1]
	v_cvt_scalef32_pk_f32_fp4 v[228:229], v179, 1.0 op_sel:[0,1,0]
	v_pk_fma_f32 v[50:51], v[224:225], v[118:119], v[50:51] op_sel_hi:[1,0,1]
	v_cvt_scalef32_pk_f32_fp4 v[230:231], v179, 1.0 op_sel:[1,1,0]
	v_pk_fma_f32 v[114:115], v[226:227], v[118:119], v[114:115] op_sel_hi:[1,0,1]
	v_pk_fma_f32 v[110:111], v[228:229], v[118:119], v[110:111] op_sel_hi:[1,0,1]
	v_pk_fma_f32 v[100:101], v[230:231], v[118:119], v[100:101] op_sel_hi:[1,0,1]
	s_waitcnt vmcnt(10)
	v_cvt_scalef32_pk_f32_fp4 v[224:225], v180, 1.0
	v_cvt_scalef32_pk_f32_fp4 v[226:227], v180, 1.0 op_sel:[1,0,0]
	v_cvt_scalef32_pk_f32_fp4 v[228:229], v180, 1.0 op_sel:[0,1,0]
	v_pk_fma_f32 v[112:113], v[224:225], v[120:121], v[112:113] op_sel_hi:[1,0,1]
	v_cvt_scalef32_pk_f32_fp4 v[230:231], v180, 1.0 op_sel:[1,1,0]
	v_pk_fma_f32 v[108:109], v[226:227], v[120:121], v[108:109] op_sel_hi:[1,0,1]
	v_cvt_scalef32_pk_f32_fp4 v[224:225], v181, 1.0
	v_pk_fma_f32 v[104:105], v[228:229], v[120:121], v[104:105] op_sel_hi:[1,0,1]
	v_cvt_scalef32_pk_f32_fp4 v[226:227], v181, 1.0 op_sel:[1,0,0]
	v_pk_fma_f32 v[98:99], v[230:231], v[120:121], v[98:99] op_sel_hi:[1,0,1]
	v_cvt_scalef32_pk_f32_fp4 v[228:229], v181, 1.0 op_sel:[0,1,0]
	v_pk_fma_f32 v[54:55], v[224:225], v[120:121], v[54:55] op_sel_hi:[1,0,1]
	v_cvt_scalef32_pk_f32_fp4 v[230:231], v181, 1.0 op_sel:[1,1,0]
	v_pk_fma_f32 v[58:59], v[226:227], v[120:121], v[58:59] op_sel_hi:[1,0,1]
	v_cvt_scalef32_pk_f32_fp4 v[224:225], v182, 1.0
	v_pk_fma_f32 v[52:53], v[228:229], v[120:121], v[52:53] op_sel_hi:[1,0,1]
	v_cvt_scalef32_pk_f32_fp4 v[226:227], v182, 1.0 op_sel:[1,0,0]
	v_pk_fma_f32 v[48:49], v[230:231], v[120:121], v[48:49] op_sel_hi:[1,0,1]
	v_cvt_scalef32_pk_f32_fp4 v[228:229], v182, 1.0 op_sel:[0,1,0]
	v_pk_fma_f32 v[106:107], v[224:225], v[120:121], v[106:107] op_sel_hi:[1,0,1]
	v_cvt_scalef32_pk_f32_fp4 v[230:231], v182, 1.0 op_sel:[1,1,0]
	v_pk_fma_f32 v[102:103], v[226:227], v[120:121], v[102:103] op_sel_hi:[1,0,1]
	v_cvt_scalef32_pk_f32_fp4 v[224:225], v183, 1.0
	v_pk_fma_f32 v[96:97], v[228:229], v[120:121], v[96:97] op_sel_hi:[1,0,1]
	v_cvt_scalef32_pk_f32_fp4 v[226:227], v183, 1.0 op_sel:[1,0,0]
	v_pk_fma_f32 v[56:57], v[230:231], v[120:121], v[56:57] op_sel_hi:[1,0,1]
	v_cvt_scalef32_pk_f32_fp4 v[228:229], v183, 1.0 op_sel:[0,1,0]
	v_pk_fma_f32 v[50:51], v[224:225], v[120:121], v[50:51] op_sel_hi:[1,0,1]
	v_cvt_scalef32_pk_f32_fp4 v[230:231], v183, 1.0 op_sel:[1,1,0]
	v_pk_fma_f32 v[114:115], v[226:227], v[120:121], v[114:115] op_sel_hi:[1,0,1]
	v_pk_fma_f32 v[110:111], v[228:229], v[120:121], v[110:111] op_sel_hi:[1,0,1]
	v_pk_fma_f32 v[100:101], v[230:231], v[120:121], v[100:101] op_sel_hi:[1,0,1]
	s_waitcnt vmcnt(9)
	v_cvt_scalef32_pk_f32_fp4 v[224:225], v184, 1.0
	v_cvt_scalef32_pk_f32_fp4 v[226:227], v184, 1.0 op_sel:[1,0,0]
	v_cvt_scalef32_pk_f32_fp4 v[228:229], v184, 1.0 op_sel:[0,1,0]
	v_pk_fma_f32 v[112:113], v[224:225], v[122:123], v[112:113] op_sel_hi:[1,0,1]
	v_cvt_scalef32_pk_f32_fp4 v[230:231], v184, 1.0 op_sel:[1,1,0]
	v_pk_fma_f32 v[108:109], v[226:227], v[122:123], v[108:109] op_sel_hi:[1,0,1]
	v_cvt_scalef32_pk_f32_fp4 v[224:225], v185, 1.0
	v_pk_fma_f32 v[104:105], v[228:229], v[122:123], v[104:105] op_sel_hi:[1,0,1]
	v_cvt_scalef32_pk_f32_fp4 v[226:227], v185, 1.0 op_sel:[1,0,0]
	v_pk_fma_f32 v[98:99], v[230:231], v[122:123], v[98:99] op_sel_hi:[1,0,1]
	v_cvt_scalef32_pk_f32_fp4 v[228:229], v185, 1.0 op_sel:[0,1,0]
	v_pk_fma_f32 v[54:55], v[224:225], v[122:123], v[54:55] op_sel_hi:[1,0,1]
	v_cvt_scalef32_pk_f32_fp4 v[230:231], v185, 1.0 op_sel:[1,1,0]
	v_pk_fma_f32 v[58:59], v[226:227], v[122:123], v[58:59] op_sel_hi:[1,0,1]
	v_cvt_scalef32_pk_f32_fp4 v[224:225], v186, 1.0
	v_pk_fma_f32 v[52:53], v[228:229], v[122:123], v[52:53] op_sel_hi:[1,0,1]
	v_cvt_scalef32_pk_f32_fp4 v[226:227], v186, 1.0 op_sel:[1,0,0]
	v_pk_fma_f32 v[48:49], v[230:231], v[122:123], v[48:49] op_sel_hi:[1,0,1]
	v_cvt_scalef32_pk_f32_fp4 v[228:229], v186, 1.0 op_sel:[0,1,0]
	v_pk_fma_f32 v[106:107], v[224:225], v[122:123], v[106:107] op_sel_hi:[1,0,1]
	v_cvt_scalef32_pk_f32_fp4 v[230:231], v186, 1.0 op_sel:[1,1,0]
	v_pk_fma_f32 v[102:103], v[226:227], v[122:123], v[102:103] op_sel_hi:[1,0,1]
	v_cvt_scalef32_pk_f32_fp4 v[224:225], v187, 1.0
	v_pk_fma_f32 v[96:97], v[228:229], v[122:123], v[96:97] op_sel_hi:[1,0,1]
	v_cvt_scalef32_pk_f32_fp4 v[226:227], v187, 1.0 op_sel:[1,0,0]
	v_pk_fma_f32 v[56:57], v[230:231], v[122:123], v[56:57] op_sel_hi:[1,0,1]
	v_cvt_scalef32_pk_f32_fp4 v[228:229], v187, 1.0 op_sel:[0,1,0]
	v_pk_fma_f32 v[50:51], v[224:225], v[122:123], v[50:51] op_sel_hi:[1,0,1]
	v_cvt_scalef32_pk_f32_fp4 v[230:231], v187, 1.0 op_sel:[1,1,0]
	v_pk_fma_f32 v[114:115], v[226:227], v[122:123], v[114:115] op_sel_hi:[1,0,1]
	v_pk_fma_f32 v[110:111], v[228:229], v[122:123], v[110:111] op_sel_hi:[1,0,1]
	v_pk_fma_f32 v[100:101], v[230:231], v[122:123], v[100:101] op_sel_hi:[1,0,1]
	s_waitcnt vmcnt(8)
	v_cvt_scalef32_pk_f32_fp4 v[224:225], v188, 1.0
	v_cvt_scalef32_pk_f32_fp4 v[226:227], v188, 1.0 op_sel:[1,0,0]
	v_cvt_scalef32_pk_f32_fp4 v[228:229], v188, 1.0 op_sel:[0,1,0]
	v_pk_fma_f32 v[112:113], v[224:225], v[124:125], v[112:113] op_sel_hi:[1,0,1]
	v_cvt_scalef32_pk_f32_fp4 v[230:231], v188, 1.0 op_sel:[1,1,0]
	v_pk_fma_f32 v[108:109], v[226:227], v[124:125], v[108:109] op_sel_hi:[1,0,1]
	v_cvt_scalef32_pk_f32_fp4 v[224:225], v189, 1.0
	v_pk_fma_f32 v[104:105], v[228:229], v[124:125], v[104:105] op_sel_hi:[1,0,1]
	v_cvt_scalef32_pk_f32_fp4 v[226:227], v189, 1.0 op_sel:[1,0,0]
	v_pk_fma_f32 v[98:99], v[230:231], v[124:125], v[98:99] op_sel_hi:[1,0,1]
	v_cvt_scalef32_pk_f32_fp4 v[228:229], v189, 1.0 op_sel:[0,1,0]
	v_pk_fma_f32 v[54:55], v[224:225], v[124:125], v[54:55] op_sel_hi:[1,0,1]
	v_cvt_scalef32_pk_f32_fp4 v[230:231], v189, 1.0 op_sel:[1,1,0]
	v_pk_fma_f32 v[58:59], v[226:227], v[124:125], v[58:59] op_sel_hi:[1,0,1]
	v_cvt_scalef32_pk_f32_fp4 v[224:225], v190, 1.0
	v_pk_fma_f32 v[52:53], v[228:229], v[124:125], v[52:53] op_sel_hi:[1,0,1]
	v_cvt_scalef32_pk_f32_fp4 v[226:227], v190, 1.0 op_sel:[1,0,0]
	v_pk_fma_f32 v[48:49], v[230:231], v[124:125], v[48:49] op_sel_hi:[1,0,1]
	v_cvt_scalef32_pk_f32_fp4 v[228:229], v190, 1.0 op_sel:[0,1,0]
	v_pk_fma_f32 v[106:107], v[224:225], v[124:125], v[106:107] op_sel_hi:[1,0,1]
	v_cvt_scalef32_pk_f32_fp4 v[230:231], v190, 1.0 op_sel:[1,1,0]
	v_pk_fma_f32 v[102:103], v[226:227], v[124:125], v[102:103] op_sel_hi:[1,0,1]
	v_cvt_scalef32_pk_f32_fp4 v[224:225], v191, 1.0
	v_pk_fma_f32 v[96:97], v[228:229], v[124:125], v[96:97] op_sel_hi:[1,0,1]
	v_cvt_scalef32_pk_f32_fp4 v[226:227], v191, 1.0 op_sel:[1,0,0]
	v_pk_fma_f32 v[56:57], v[230:231], v[124:125], v[56:57] op_sel_hi:[1,0,1]
	v_cvt_scalef32_pk_f32_fp4 v[228:229], v191, 1.0 op_sel:[0,1,0]
	v_pk_fma_f32 v[50:51], v[224:225], v[124:125], v[50:51] op_sel_hi:[1,0,1]
	v_cvt_scalef32_pk_f32_fp4 v[230:231], v191, 1.0 op_sel:[1,1,0]
	v_pk_fma_f32 v[114:115], v[226:227], v[124:125], v[114:115] op_sel_hi:[1,0,1]
	v_pk_fma_f32 v[110:111], v[228:229], v[124:125], v[110:111] op_sel_hi:[1,0,1]
	v_pk_fma_f32 v[100:101], v[230:231], v[124:125], v[100:101] op_sel_hi:[1,0,1]
	s_waitcnt lgkmcnt(0)
	v_lshl_add_u32 v250, v240, 9, v241
	v_lshl_add_u32 v251, v242, 9, v241
	v_lshl_add_u32 v252, v246, 9, v241
	v_lshl_add_u32 v253, v248, 9, v241
	global_load_dwordx4 v[160:163], v250, s[98:99]
	global_load_dwordx4 v[164:167], v251, s[98:99]
	global_load_dwordx4 v[168:171], v252, s[98:99]
	global_load_dwordx4 v[172:175], v253, s[98:99]
	global_load_dwordx4 v[176:179], v250, s[100:101]
	global_load_dwordx4 v[180:183], v251, s[100:101]
	global_load_dwordx4 v[184:187], v252, s[100:101]
	global_load_dwordx4 v[188:191], v253, s[100:101]
	s_add_u32 s20, s19, 3
	s_cmp_lt_u32 s20, 8
	s_cselect_b64 s[4:5], -1, 0
	s_and_b32 s20, s20, 7
	s_lshl_b32 s20, s20, 5
	v_cndmask_b32_e64 v126, v94, v92, s[4:5]
	v_lshl_add_u32 v129, v136, 2, s20
	ds_bpermute_b32 v240, v129, v126
	ds_bpermute_b32 v242, v129, v126 offset:8
	ds_bpermute_b32 v246, v129, v126 offset:16
	ds_bpermute_b32 v248, v129, v126 offset:24
	s_add_u32 s20, s19, 1
	s_cmp_lt_u32 s20, 8
	s_cselect_b64 s[4:5], -1, 0
	s_and_b32 s20, s20, 7
	s_lshl_b32 s20, s20, 5
	v_cndmask_b32_e64 v127, v147, v146, s[4:5]
	v_cndmask_b32_e64 v128, v149, v148, s[4:5]
	v_lshl_add_u32 v130, v137, 2, s20
	ds_bpermute_b32 v156, v130, v127
	ds_bpermute_b32 v157, v130, v128
	s_waitcnt vmcnt(14)
	v_cvt_scalef32_pk_f32_fp4 v[224:225], v192, 1.0
	v_cvt_scalef32_pk_f32_fp4 v[226:227], v196, 1.0
	v_cvt_scalef32_pk_f32_fp4 v[228:229], v192, 1.0 op_sel:[1,0,0]
	v_cvt_scalef32_pk_f32_fp4 v[230:231], v196, 1.0 op_sel:[1,0,0]
	v_pk_fma_f32 v[232:233], v[24:25], v[224:225], 0 op_sel_hi:[1,1,0]
	v_pk_fma_f32 v[234:235], v[24:25], v[226:227], 0 op_sel_hi:[1,1,0]
	v_cvt_scalef32_pk_f32_fp4 v[224:225], v192, 1.0 op_sel:[0,1,0]
	v_cvt_scalef32_pk_f32_fp4 v[226:227], v196, 1.0 op_sel:[0,1,0]
	v_pk_fma_f32 v[232:233], v[26:27], v[228:229], v[232:233]
	v_pk_fma_f32 v[234:235], v[26:27], v[230:231], v[234:235]
	v_cvt_scalef32_pk_f32_fp4 v[228:229], v192, 1.0 op_sel:[1,1,0]
	v_cvt_scalef32_pk_f32_fp4 v[230:231], v196, 1.0 op_sel:[1,1,0]
	v_pk_fma_f32 v[232:233], v[12:13], v[224:225], v[232:233]
	v_pk_fma_f32 v[234:235], v[12:13], v[226:227], v[234:235]
	v_cvt_scalef32_pk_f32_fp4 v[224:225], v193, 1.0
	v_cvt_scalef32_pk_f32_fp4 v[226:227], v197, 1.0
	v_pk_fma_f32 v[232:233], v[14:15], v[228:229], v[232:233]
	v_pk_fma_f32 v[234:235], v[14:15], v[230:231], v[234:235]
	v_cvt_scalef32_pk_f32_fp4 v[228:229], v193, 1.0 op_sel:[1,0,0]
	v_cvt_scalef32_pk_f32_fp4 v[230:231], v197, 1.0 op_sel:[1,0,0]
	v_pk_fma_f32 v[232:233], v[4:5], v[224:225], v[232:233]
	v_pk_fma_f32 v[234:235], v[4:5], v[226:227], v[234:235]
	v_cvt_scalef32_pk_f32_fp4 v[224:225], v193, 1.0 op_sel:[0,1,0]
	v_cvt_scalef32_pk_f32_fp4 v[226:227], v197, 1.0 op_sel:[0,1,0]
	v_pk_fma_f32 v[232:233], v[6:7], v[228:229], v[232:233]
	v_pk_fma_f32 v[234:235], v[6:7], v[230:231], v[234:235]
	v_cvt_scalef32_pk_f32_fp4 v[228:229], v193, 1.0 op_sel:[1,1,0]
	v_cvt_scalef32_pk_f32_fp4 v[230:231], v197, 1.0 op_sel:[1,1,0]
	v_pk_fma_f32 v[232:233], v[0:1], v[224:225], v[232:233]
	v_pk_fma_f32 v[234:235], v[0:1], v[226:227], v[234:235]
	v_cvt_scalef32_pk_f32_fp4 v[224:225], v194, 1.0
	v_cvt_scalef32_pk_f32_fp4 v[226:227], v198, 1.0
	v_pk_fma_f32 v[232:233], v[2:3], v[228:229], v[232:233]
	v_pk_fma_f32 v[234:235], v[2:3], v[230:231], v[234:235]
	v_cvt_scalef32_pk_f32_fp4 v[228:229], v194, 1.0 op_sel:[1,0,0]
	v_cvt_scalef32_pk_f32_fp4 v[230:231], v198, 1.0 op_sel:[1,0,0]
	v_pk_fma_f32 v[232:233], v[28:29], v[224:225], v[232:233]
	v_pk_fma_f32 v[234:235], v[28:29], v[226:227], v[234:235]
	v_cvt_scalef32_pk_f32_fp4 v[224:225], v194, 1.0 op_sel:[0,1,0]
	v_cvt_scalef32_pk_f32_fp4 v[226:227], v198, 1.0 op_sel:[0,1,0]
	v_pk_fma_f32 v[232:233], v[30:31], v[228:229], v[232:233]
	v_pk_fma_f32 v[234:235], v[30:31], v[230:231], v[234:235]
	v_cvt_scalef32_pk_f32_fp4 v[228:229], v194, 1.0 op_sel:[1,1,0]
	v_cvt_scalef32_pk_f32_fp4 v[230:231], v198, 1.0 op_sel:[1,1,0]
	v_pk_fma_f32 v[232:233], v[16:17], v[224:225], v[232:233]
	v_pk_fma_f32 v[234:235], v[16:17], v[226:227], v[234:235]
	v_cvt_scalef32_pk_f32_fp4 v[224:225], v195, 1.0
	v_cvt_scalef32_pk_f32_fp4 v[226:227], v199, 1.0
	v_pk_fma_f32 v[232:233], v[18:19], v[228:229], v[232:233]
	v_pk_fma_f32 v[234:235], v[18:19], v[230:231], v[234:235]
	v_cvt_scalef32_pk_f32_fp4 v[228:229], v195, 1.0 op_sel:[1,0,0]
	v_cvt_scalef32_pk_f32_fp4 v[230:231], v199, 1.0 op_sel:[1,0,0]
	v_pk_fma_f32 v[232:233], v[8:9], v[224:225], v[232:233]
	v_pk_fma_f32 v[234:235], v[8:9], v[226:227], v[234:235]
	v_cvt_scalef32_pk_f32_fp4 v[224:225], v195, 1.0 op_sel:[0,1,0]
	v_cvt_scalef32_pk_f32_fp4 v[226:227], v199, 1.0 op_sel:[0,1,0]
	v_pk_fma_f32 v[232:233], v[10:11], v[228:229], v[232:233]
	v_pk_fma_f32 v[234:235], v[10:11], v[230:231], v[234:235]
	v_cvt_scalef32_pk_f32_fp4 v[228:229], v195, 1.0 op_sel:[1,1,0]
	v_cvt_scalef32_pk_f32_fp4 v[230:231], v199, 1.0 op_sel:[1,1,0]
	v_pk_fma_f32 v[232:233], v[20:21], v[224:225], v[232:233]
	v_pk_fma_f32 v[234:235], v[20:21], v[226:227], v[234:235]
	v_pk_fma_f32 v[232:233], v[22:23], v[228:229], v[232:233]
	v_pk_fma_f32 v[234:235], v[22:23], v[230:231], v[234:235]
	v_add_f32_e32 v32, v232, v233
	v_add_f32_e32 v33, v234, v235
	s_waitcnt vmcnt(12)
	v_cvt_scalef32_pk_f32_fp4 v[224:225], v200, 1.0
	v_cvt_scalef32_pk_f32_fp4 v[226:227], v204, 1.0
	v_cvt_scalef32_pk_f32_fp4 v[228:229], v200, 1.0 op_sel:[1,0,0]
	v_cvt_scalef32_pk_f32_fp4 v[230:231], v204, 1.0 op_sel:[1,0,0]
	v_pk_fma_f32 v[236:237], v[24:25], v[224:225], 0 op_sel_hi:[1,1,0]
	v_pk_fma_f32 v[238:239], v[24:25], v[226:227], 0 op_sel_hi:[1,1,0]
	v_cvt_scalef32_pk_f32_fp4 v[224:225], v200, 1.0 op_sel:[0,1,0]
	v_cvt_scalef32_pk_f32_fp4 v[226:227], v204, 1.0 op_sel:[0,1,0]
	v_pk_fma_f32 v[236:237], v[26:27], v[228:229], v[236:237]
	v_pk_fma_f32 v[238:239], v[26:27], v[230:231], v[238:239]
	v_cvt_scalef32_pk_f32_fp4 v[228:229], v200, 1.0 op_sel:[1,1,0]
	v_cvt_scalef32_pk_f32_fp4 v[230:231], v204, 1.0 op_sel:[1,1,0]
	v_pk_fma_f32 v[236:237], v[12:13], v[224:225], v[236:237]
	v_pk_fma_f32 v[238:239], v[12:13], v[226:227], v[238:239]
	v_cvt_scalef32_pk_f32_fp4 v[224:225], v201, 1.0
	v_cvt_scalef32_pk_f32_fp4 v[226:227], v205, 1.0
	v_pk_fma_f32 v[236:237], v[14:15], v[228:229], v[236:237]
	v_pk_fma_f32 v[238:239], v[14:15], v[230:231], v[238:239]
	v_cvt_scalef32_pk_f32_fp4 v[228:229], v201, 1.0 op_sel:[1,0,0]
	v_cvt_scalef32_pk_f32_fp4 v[230:231], v205, 1.0 op_sel:[1,0,0]
	v_pk_fma_f32 v[236:237], v[4:5], v[224:225], v[236:237]
	v_pk_fma_f32 v[238:239], v[4:5], v[226:227], v[238:239]
	v_cvt_scalef32_pk_f32_fp4 v[224:225], v201, 1.0 op_sel:[0,1,0]
	v_cvt_scalef32_pk_f32_fp4 v[226:227], v205, 1.0 op_sel:[0,1,0]
	v_pk_fma_f32 v[236:237], v[6:7], v[228:229], v[236:237]
	v_pk_fma_f32 v[238:239], v[6:7], v[230:231], v[238:239]
	v_cvt_scalef32_pk_f32_fp4 v[228:229], v201, 1.0 op_sel:[1,1,0]
	v_cvt_scalef32_pk_f32_fp4 v[230:231], v205, 1.0 op_sel:[1,1,0]
	v_pk_fma_f32 v[236:237], v[0:1], v[224:225], v[236:237]
	v_pk_fma_f32 v[238:239], v[0:1], v[226:227], v[238:239]
	v_cvt_scalef32_pk_f32_fp4 v[224:225], v202, 1.0
	v_cvt_scalef32_pk_f32_fp4 v[226:227], v206, 1.0
	v_pk_fma_f32 v[236:237], v[2:3], v[228:229], v[236:237]
	v_pk_fma_f32 v[238:239], v[2:3], v[230:231], v[238:239]
	v_cvt_scalef32_pk_f32_fp4 v[228:229], v202, 1.0 op_sel:[1,0,0]
	v_cvt_scalef32_pk_f32_fp4 v[230:231], v206, 1.0 op_sel:[1,0,0]
	v_pk_fma_f32 v[236:237], v[28:29], v[224:225], v[236:237]
	v_pk_fma_f32 v[238:239], v[28:29], v[226:227], v[238:239]
	v_cvt_scalef32_pk_f32_fp4 v[224:225], v202, 1.0 op_sel:[0,1,0]
	v_cvt_scalef32_pk_f32_fp4 v[226:227], v206, 1.0 op_sel:[0,1,0]
	v_pk_fma_f32 v[236:237], v[30:31], v[228:229], v[236:237]
	v_pk_fma_f32 v[238:239], v[30:31], v[230:231], v[238:239]
	v_cvt_scalef32_pk_f32_fp4 v[228:229], v202, 1.0 op_sel:[1,1,0]
	v_cvt_scalef32_pk_f32_fp4 v[230:231], v206, 1.0 op_sel:[1,1,0]
	v_pk_fma_f32 v[236:237], v[16:17], v[224:225], v[236:237]
	v_pk_fma_f32 v[238:239], v[16:17], v[226:227], v[238:239]
	v_cvt_scalef32_pk_f32_fp4 v[224:225], v203, 1.0
	v_cvt_scalef32_pk_f32_fp4 v[226:227], v207, 1.0
	v_pk_fma_f32 v[236:237], v[18:19], v[228:229], v[236:237]
	v_pk_fma_f32 v[238:239], v[18:19], v[230:231], v[238:239]
	v_cvt_scalef32_pk_f32_fp4 v[228:229], v203, 1.0 op_sel:[1,0,0]
	v_cvt_scalef32_pk_f32_fp4 v[230:231], v207, 1.0 op_sel:[1,0,0]
	v_pk_fma_f32 v[236:237], v[8:9], v[224:225], v[236:237]
	v_pk_fma_f32 v[238:239], v[8:9], v[226:227], v[238:239]
	v_cvt_scalef32_pk_f32_fp4 v[224:225], v203, 1.0 op_sel:[0,1,0]
	v_cvt_scalef32_pk_f32_fp4 v[226:227], v207, 1.0 op_sel:[0,1,0]
	v_pk_fma_f32 v[236:237], v[10:11], v[228:229], v[236:237]
	v_pk_fma_f32 v[238:239], v[10:11], v[230:231], v[238:239]
	v_cvt_scalef32_pk_f32_fp4 v[228:229], v203, 1.0 op_sel:[1,1,0]
	v_cvt_scalef32_pk_f32_fp4 v[230:231], v207, 1.0 op_sel:[1,1,0]
	v_pk_fma_f32 v[236:237], v[20:21], v[224:225], v[236:237]
	v_pk_fma_f32 v[238:239], v[20:21], v[226:227], v[238:239]
	v_pk_fma_f32 v[236:237], v[22:23], v[228:229], v[236:237]
	v_pk_fma_f32 v[238:239], v[22:23], v[230:231], v[238:239]
	v_add_f32_e32 v34, v236, v237
	v_add_f32_e32 v35, v238, v239
	s_nop 1
	v_permlane16_swap_b32_e32 v32, v34
	v_permlane16_swap_b32_e32 v33, v35
	v_add_f32_e32 v36, v32, v34
	v_add_f32_e32 v38, v33, v35
	s_waitcnt lgkmcnt(0)
	v_cndmask_b32_e64 v40, v38, v36, s[0:1]
	v_cndmask_b32_e64 v41, v36, v38, s[0:1]
	s_nop 1
	v_add_f32_dpp v40, v41, v40 row_ror:8 row_mask:0xf bank_mask:0xf
	s_nop 1
	v_add_f32_dpp v40, v40, v40 quad_perm:[1,0,3,2] row_mask:0xf bank_mask:0xf
	s_nop 1
	v_add_f32_dpp v40, v40, v40 quad_perm:[2,3,0,1] row_mask:0xf bank_mask:0xf
	s_nop 1
	v_add_f32_dpp v40, v40, v40 row_half_mirror row_mask:0xf bank_mask:0xf
	v_mul_f32_e32 v42, v40, v156
	v_fma_f32 v43, |v42|, s16, 1.0
	v_rcp_f32_e32 v43, v43
	v_cmp_gt_f32_e64 s[4:5], 0, v42
	v_mul_f32_e32 v45, v42, v42
	v_fmamk_f32 v44, v43, 0x3f07dc22, v142
	v_fmaak_f32 v44, v43, v44, 0x3f35f0e3
	v_fmaak_f32 v44, v43, v44, 0xbe11a98e
	v_fmaak_f32 v44, v43, v44, 0x3e027906
	v_mul_f32_e32 v45, 0xbf38aa3b, v45
	v_exp_f32_e32 v45, v45
	v_mul_f32_e32 v43, v43, v44
	v_mul_f32_e32 v43, v45, v43
	v_mul_f32_e32 v44, v42, v43
	v_fma_f32 v42, -v42, v43, v42
	v_cndmask_b32_e64 v42, v42, v44, s[4:5]
	v_mul_f32_e32 v158, v42, v157
	ds_bpermute_b32 v118, v138, v158
	ds_bpermute_b32 v120, v139, v158
	ds_bpermute_b32 v122, v140, v158
	ds_bpermute_b32 v124, v141, v158
	s_waitcnt vmcnt(11)
	v_cvt_scalef32_pk_f32_fp4 v[224:225], v208, 1.0
	v_cvt_scalef32_pk_f32_fp4 v[226:227], v208, 1.0 op_sel:[1,0,0]
	s_waitcnt lgkmcnt(0)
	v_cvt_scalef32_pk_f32_fp4 v[228:229], v208, 1.0 op_sel:[0,1,0]
	v_pk_fma_f32 v[112:113], v[224:225], v[118:119], v[112:113] op_sel_hi:[1,0,1]
	v_cvt_scalef32_pk_f32_fp4 v[230:231], v208, 1.0 op_sel:[1,1,0]
	v_pk_fma_f32 v[108:109], v[226:227], v[118:119], v[108:109] op_sel_hi:[1,0,1]
	v_cvt_scalef32_pk_f32_fp4 v[224:225], v209, 1.0
	v_pk_fma_f32 v[104:105], v[228:229], v[118:119], v[104:105] op_sel_hi:[1,0,1]
	v_cvt_scalef32_pk_f32_fp4 v[226:227], v209, 1.0 op_sel:[1,0,0]
	v_pk_fma_f32 v[98:99], v[230:231], v[118:119], v[98:99] op_sel_hi:[1,0,1]
	v_cvt_scalef32_pk_f32_fp4 v[228:229], v209, 1.0 op_sel:[0,1,0]
	v_pk_fma_f32 v[54:55], v[224:225], v[118:119], v[54:55] op_sel_hi:[1,0,1]
	v_cvt_scalef32_pk_f32_fp4 v[230:231], v209, 1.0 op_sel:[1,1,0]
	v_pk_fma_f32 v[58:59], v[226:227], v[118:119], v[58:59] op_sel_hi:[1,0,1]
	v_cvt_scalef32_pk_f32_fp4 v[224:225], v210, 1.0
	v_pk_fma_f32 v[52:53], v[228:229], v[118:119], v[52:53] op_sel_hi:[1,0,1]
	v_cvt_scalef32_pk_f32_fp4 v[226:227], v210, 1.0 op_sel:[1,0,0]
	v_pk_fma_f32 v[48:49], v[230:231], v[118:119], v[48:49] op_sel_hi:[1,0,1]
	v_cvt_scalef32_pk_f32_fp4 v[228:229], v210, 1.0 op_sel:[0,1,0]
	v_pk_fma_f32 v[106:107], v[224:225], v[118:119], v[106:107] op_sel_hi:[1,0,1]
	v_cvt_scalef32_pk_f32_fp4 v[230:231], v210, 1.0 op_sel:[1,1,0]
	v_pk_fma_f32 v[102:103], v[226:227], v[118:119], v[102:103] op_sel_hi:[1,0,1]
	v_cvt_scalef32_pk_f32_fp4 v[224:225], v211, 1.0
	v_pk_fma_f32 v[96:97], v[228:229], v[118:119], v[96:97] op_sel_hi:[1,0,1]
	v_cvt_scalef32_pk_f32_fp4 v[226:227], v211, 1.0 op_sel:[1,0,0]
	v_pk_fma_f32 v[56:57], v[230:231], v[118:119], v[56:57] op_sel_hi:[1,0,1]
	v_cvt_scalef32_pk_f32_fp4 v[228:229], v211, 1.0 op_sel:[0,1,0]
	v_pk_fma_f32 v[50:51], v[224:225], v[118:119], v[50:51] op_sel_hi:[1,0,1]
	v_cvt_scalef32_pk_f32_fp4 v[230:231], v211, 1.0 op_sel:[1,1,0]
	v_pk_fma_f32 v[114:115], v[226:227], v[118:119], v[114:115] op_sel_hi:[1,0,1]
	v_pk_fma_f32 v[110:111], v[228:229], v[118:119], v[110:111] op_sel_hi:[1,0,1]
	v_pk_fma_f32 v[100:101], v[230:231], v[118:119], v[100:101] op_sel_hi:[1,0,1]
	s_waitcnt vmcnt(10)
	v_cvt_scalef32_pk_f32_fp4 v[224:225], v212, 1.0
	v_cvt_scalef32_pk_f32_fp4 v[226:227], v212, 1.0 op_sel:[1,0,0]
	v_cvt_scalef32_pk_f32_fp4 v[228:229], v212, 1.0 op_sel:[0,1,0]
	v_pk_fma_f32 v[112:113], v[224:225], v[120:121], v[112:113] op_sel_hi:[1,0,1]
	v_cvt_scalef32_pk_f32_fp4 v[230:231], v212, 1.0 op_sel:[1,1,0]
	v_pk_fma_f32 v[108:109], v[226:227], v[120:121], v[108:109] op_sel_hi:[1,0,1]
	v_cvt_scalef32_pk_f32_fp4 v[224:225], v213, 1.0
	v_pk_fma_f32 v[104:105], v[228:229], v[120:121], v[104:105] op_sel_hi:[1,0,1]
	v_cvt_scalef32_pk_f32_fp4 v[226:227], v213, 1.0 op_sel:[1,0,0]
	v_pk_fma_f32 v[98:99], v[230:231], v[120:121], v[98:99] op_sel_hi:[1,0,1]
	v_cvt_scalef32_pk_f32_fp4 v[228:229], v213, 1.0 op_sel:[0,1,0]
	v_pk_fma_f32 v[54:55], v[224:225], v[120:121], v[54:55] op_sel_hi:[1,0,1]
	v_cvt_scalef32_pk_f32_fp4 v[230:231], v213, 1.0 op_sel:[1,1,0]
	v_pk_fma_f32 v[58:59], v[226:227], v[120:121], v[58:59] op_sel_hi:[1,0,1]
	v_cvt_scalef32_pk_f32_fp4 v[224:225], v214, 1.0
	v_pk_fma_f32 v[52:53], v[228:229], v[120:121], v[52:53] op_sel_hi:[1,0,1]
	v_cvt_scalef32_pk_f32_fp4 v[226:227], v214, 1.0 op_sel:[1,0,0]
	v_pk_fma_f32 v[48:49], v[230:231], v[120:121], v[48:49] op_sel_hi:[1,0,1]
	v_cvt_scalef32_pk_f32_fp4 v[228:229], v214, 1.0 op_sel:[0,1,0]
	v_pk_fma_f32 v[106:107], v[224:225], v[120:121], v[106:107] op_sel_hi:[1,0,1]
	v_cvt_scalef32_pk_f32_fp4 v[230:231], v214, 1.0 op_sel:[1,1,0]
	v_pk_fma_f32 v[102:103], v[226:227], v[120:121], v[102:103] op_sel_hi:[1,0,1]
	v_cvt_scalef32_pk_f32_fp4 v[224:225], v215, 1.0
	v_pk_fma_f32 v[96:97], v[228:229], v[120:121], v[96:97] op_sel_hi:[1,0,1]
	v_cvt_scalef32_pk_f32_fp4 v[226:227], v215, 1.0 op_sel:[1,0,0]
	v_pk_fma_f32 v[56:57], v[230:231], v[120:121], v[56:57] op_sel_hi:[1,0,1]
	v_cvt_scalef32_pk_f32_fp4 v[228:229], v215, 1.0 op_sel:[0,1,0]
	v_pk_fma_f32 v[50:51], v[224:225], v[120:121], v[50:51] op_sel_hi:[1,0,1]
	v_cvt_scalef32_pk_f32_fp4 v[230:231], v215, 1.0 op_sel:[1,1,0]
	v_pk_fma_f32 v[114:115], v[226:227], v[120:121], v[114:115] op_sel_hi:[1,0,1]
	v_pk_fma_f32 v[110:111], v[228:229], v[120:121], v[110:111] op_sel_hi:[1,0,1]
	v_pk_fma_f32 v[100:101], v[230:231], v[120:121], v[100:101] op_sel_hi:[1,0,1]
	s_waitcnt vmcnt(9)
	v_cvt_scalef32_pk_f32_fp4 v[224:225], v216, 1.0
	v_cvt_scalef32_pk_f32_fp4 v[226:227], v216, 1.0 op_sel:[1,0,0]
	v_cvt_scalef32_pk_f32_fp4 v[228:229], v216, 1.0 op_sel:[0,1,0]
	v_pk_fma_f32 v[112:113], v[224:225], v[122:123], v[112:113] op_sel_hi:[1,0,1]
	v_cvt_scalef32_pk_f32_fp4 v[230:231], v216, 1.0 op_sel:[1,1,0]
	v_pk_fma_f32 v[108:109], v[226:227], v[122:123], v[108:109] op_sel_hi:[1,0,1]
	v_cvt_scalef32_pk_f32_fp4 v[224:225], v217, 1.0
	v_pk_fma_f32 v[104:105], v[228:229], v[122:123], v[104:105] op_sel_hi:[1,0,1]
	v_cvt_scalef32_pk_f32_fp4 v[226:227], v217, 1.0 op_sel:[1,0,0]
	v_pk_fma_f32 v[98:99], v[230:231], v[122:123], v[98:99] op_sel_hi:[1,0,1]
	v_cvt_scalef32_pk_f32_fp4 v[228:229], v217, 1.0 op_sel:[0,1,0]
	v_pk_fma_f32 v[54:55], v[224:225], v[122:123], v[54:55] op_sel_hi:[1,0,1]
	v_cvt_scalef32_pk_f32_fp4 v[230:231], v217, 1.0 op_sel:[1,1,0]
	v_pk_fma_f32 v[58:59], v[226:227], v[122:123], v[58:59] op_sel_hi:[1,0,1]
	v_cvt_scalef32_pk_f32_fp4 v[224:225], v218, 1.0
	v_pk_fma_f32 v[52:53], v[228:229], v[122:123], v[52:53] op_sel_hi:[1,0,1]
	v_cvt_scalef32_pk_f32_fp4 v[226:227], v218, 1.0 op_sel:[1,0,0]
	v_pk_fma_f32 v[48:49], v[230:231], v[122:123], v[48:49] op_sel_hi:[1,0,1]
	v_cvt_scalef32_pk_f32_fp4 v[228:229], v218, 1.0 op_sel:[0,1,0]
	v_pk_fma_f32 v[106:107], v[224:225], v[122:123], v[106:107] op_sel_hi:[1,0,1]
	v_cvt_scalef32_pk_f32_fp4 v[230:231], v218, 1.0 op_sel:[1,1,0]
	v_pk_fma_f32 v[102:103], v[226:227], v[122:123], v[102:103] op_sel_hi:[1,0,1]
	v_cvt_scalef32_pk_f32_fp4 v[224:225], v219, 1.0
	v_pk_fma_f32 v[96:97], v[228:229], v[122:123], v[96:97] op_sel_hi:[1,0,1]
	v_cvt_scalef32_pk_f32_fp4 v[226:227], v219, 1.0 op_sel:[1,0,0]
	v_pk_fma_f32 v[56:57], v[230:231], v[122:123], v[56:57] op_sel_hi:[1,0,1]
	v_cvt_scalef32_pk_f32_fp4 v[228:229], v219, 1.0 op_sel:[0,1,0]
	v_pk_fma_f32 v[50:51], v[224:225], v[122:123], v[50:51] op_sel_hi:[1,0,1]
	v_cvt_scalef32_pk_f32_fp4 v[230:231], v219, 1.0 op_sel:[1,1,0]
	v_pk_fma_f32 v[114:115], v[226:227], v[122:123], v[114:115] op_sel_hi:[1,0,1]
	v_pk_fma_f32 v[110:111], v[228:229], v[122:123], v[110:111] op_sel_hi:[1,0,1]
	v_pk_fma_f32 v[100:101], v[230:231], v[122:123], v[100:101] op_sel_hi:[1,0,1]
	s_waitcnt vmcnt(8)
	v_cvt_scalef32_pk_f32_fp4 v[224:225], v220, 1.0
	v_cvt_scalef32_pk_f32_fp4 v[226:227], v220, 1.0 op_sel:[1,0,0]
	v_cvt_scalef32_pk_f32_fp4 v[228:229], v220, 1.0 op_sel:[0,1,0]
	v_pk_fma_f32 v[112:113], v[224:225], v[124:125], v[112:113] op_sel_hi:[1,0,1]
	v_cvt_scalef32_pk_f32_fp4 v[230:231], v220, 1.0 op_sel:[1,1,0]
	v_pk_fma_f32 v[108:109], v[226:227], v[124:125], v[108:109] op_sel_hi:[1,0,1]
	v_cvt_scalef32_pk_f32_fp4 v[224:225], v221, 1.0
	v_pk_fma_f32 v[104:105], v[228:229], v[124:125], v[104:105] op_sel_hi:[1,0,1]
	v_cvt_scalef32_pk_f32_fp4 v[226:227], v221, 1.0 op_sel:[1,0,0]
	v_pk_fma_f32 v[98:99], v[230:231], v[124:125], v[98:99] op_sel_hi:[1,0,1]
	v_cvt_scalef32_pk_f32_fp4 v[228:229], v221, 1.0 op_sel:[0,1,0]
	v_pk_fma_f32 v[54:55], v[224:225], v[124:125], v[54:55] op_sel_hi:[1,0,1]
	v_cvt_scalef32_pk_f32_fp4 v[230:231], v221, 1.0 op_sel:[1,1,0]
	v_pk_fma_f32 v[58:59], v[226:227], v[124:125], v[58:59] op_sel_hi:[1,0,1]
	v_cvt_scalef32_pk_f32_fp4 v[224:225], v222, 1.0
	v_pk_fma_f32 v[52:53], v[228:229], v[124:125], v[52:53] op_sel_hi:[1,0,1]
	v_cvt_scalef32_pk_f32_fp4 v[226:227], v222, 1.0 op_sel:[1,0,0]
	v_pk_fma_f32 v[48:49], v[230:231], v[124:125], v[48:49] op_sel_hi:[1,0,1]
	v_cvt_scalef32_pk_f32_fp4 v[228:229], v222, 1.0 op_sel:[0,1,0]
	v_pk_fma_f32 v[106:107], v[224:225], v[124:125], v[106:107] op_sel_hi:[1,0,1]
	v_cvt_scalef32_pk_f32_fp4 v[230:231], v222, 1.0 op_sel:[1,1,0]
	v_pk_fma_f32 v[102:103], v[226:227], v[124:125], v[102:103] op_sel_hi:[1,0,1]
	v_cvt_scalef32_pk_f32_fp4 v[224:225], v223, 1.0
	v_pk_fma_f32 v[96:97], v[228:229], v[124:125], v[96:97] op_sel_hi:[1,0,1]
	v_cvt_scalef32_pk_f32_fp4 v[226:227], v223, 1.0 op_sel:[1,0,0]
	v_pk_fma_f32 v[56:57], v[230:231], v[124:125], v[56:57] op_sel_hi:[1,0,1]
	v_cvt_scalef32_pk_f32_fp4 v[228:229], v223, 1.0 op_sel:[0,1,0]
	v_pk_fma_f32 v[50:51], v[224:225], v[124:125], v[50:51] op_sel_hi:[1,0,1]
	v_cvt_scalef32_pk_f32_fp4 v[230:231], v223, 1.0 op_sel:[1,1,0]
	v_pk_fma_f32 v[114:115], v[226:227], v[124:125], v[114:115] op_sel_hi:[1,0,1]
	v_pk_fma_f32 v[110:111], v[228:229], v[124:125], v[110:111] op_sel_hi:[1,0,1]
	v_pk_fma_f32 v[100:101], v[230:231], v[124:125], v[100:101] op_sel_hi:[1,0,1]
	s_add_u32 s19, s19, 2
	s_cmp_lt_u32 s19, 14
	s_cbranch_scc1 .Lxg_loop_p12
	s_waitcnt lgkmcnt(0)
	v_lshl_add_u32 v250, v240, 9, v241
	v_lshl_add_u32 v251, v242, 9, v241
	v_lshl_add_u32 v252, v246, 9, v241
	v_lshl_add_u32 v253, v248, 9, v241
	global_load_dwordx4 v[192:195], v250, s[98:99]
	global_load_dwordx4 v[196:199], v251, s[98:99]
	global_load_dwordx4 v[200:203], v252, s[98:99]
	global_load_dwordx4 v[204:207], v253, s[98:99]
	global_load_dwordx4 v[208:211], v250, s[100:101]
	global_load_dwordx4 v[212:215], v251, s[100:101]
	global_load_dwordx4 v[216:219], v252, s[100:101]
	global_load_dwordx4 v[220:223], v253, s[100:101]
	s_movk_i32 s20, 0xc0
	v_lshl_add_u32 v130, v137, 2, s20
	ds_bpermute_b32 v156, v130, v147
	ds_bpermute_b32 v157, v130, v149
	s_waitcnt vmcnt(14)
	v_cvt_scalef32_pk_f32_fp4 v[224:225], v160, 1.0
	v_cvt_scalef32_pk_f32_fp4 v[226:227], v164, 1.0
	v_cvt_scalef32_pk_f32_fp4 v[228:229], v160, 1.0 op_sel:[1,0,0]
	v_cvt_scalef32_pk_f32_fp4 v[230:231], v164, 1.0 op_sel:[1,0,0]
	v_pk_fma_f32 v[232:233], v[24:25], v[224:225], 0 op_sel_hi:[1,1,0]
	v_pk_fma_f32 v[234:235], v[24:25], v[226:227], 0 op_sel_hi:[1,1,0]
	v_cvt_scalef32_pk_f32_fp4 v[224:225], v160, 1.0 op_sel:[0,1,0]
	v_cvt_scalef32_pk_f32_fp4 v[226:227], v164, 1.0 op_sel:[0,1,0]
	v_pk_fma_f32 v[232:233], v[26:27], v[228:229], v[232:233]
	v_pk_fma_f32 v[234:235], v[26:27], v[230:231], v[234:235]
	v_cvt_scalef32_pk_f32_fp4 v[228:229], v160, 1.0 op_sel:[1,1,0]
	v_cvt_scalef32_pk_f32_fp4 v[230:231], v164, 1.0 op_sel:[1,1,0]
	v_pk_fma_f32 v[232:233], v[12:13], v[224:225], v[232:233]
	v_pk_fma_f32 v[234:235], v[12:13], v[226:227], v[234:235]
	v_cvt_scalef32_pk_f32_fp4 v[224:225], v161, 1.0
	v_cvt_scalef32_pk_f32_fp4 v[226:227], v165, 1.0
	v_pk_fma_f32 v[232:233], v[14:15], v[228:229], v[232:233]
	v_pk_fma_f32 v[234:235], v[14:15], v[230:231], v[234:235]
	v_cvt_scalef32_pk_f32_fp4 v[228:229], v161, 1.0 op_sel:[1,0,0]
	v_cvt_scalef32_pk_f32_fp4 v[230:231], v165, 1.0 op_sel:[1,0,0]
	v_pk_fma_f32 v[232:233], v[4:5], v[224:225], v[232:233]
	v_pk_fma_f32 v[234:235], v[4:5], v[226:227], v[234:235]
	v_cvt_scalef32_pk_f32_fp4 v[224:225], v161, 1.0 op_sel:[0,1,0]
	v_cvt_scalef32_pk_f32_fp4 v[226:227], v165, 1.0 op_sel:[0,1,0]
	v_pk_fma_f32 v[232:233], v[6:7], v[228:229], v[232:233]
	v_pk_fma_f32 v[234:235], v[6:7], v[230:231], v[234:235]
	v_cvt_scalef32_pk_f32_fp4 v[228:229], v161, 1.0 op_sel:[1,1,0]
	v_cvt_scalef32_pk_f32_fp4 v[230:231], v165, 1.0 op_sel:[1,1,0]
	v_pk_fma_f32 v[232:233], v[0:1], v[224:225], v[232:233]
	v_pk_fma_f32 v[234:235], v[0:1], v[226:227], v[234:235]
	v_cvt_scalef32_pk_f32_fp4 v[224:225], v162, 1.0
	v_cvt_scalef32_pk_f32_fp4 v[226:227], v166, 1.0
	v_pk_fma_f32 v[232:233], v[2:3], v[228:229], v[232:233]
	v_pk_fma_f32 v[234:235], v[2:3], v[230:231], v[234:235]
	v_cvt_scalef32_pk_f32_fp4 v[228:229], v162, 1.0 op_sel:[1,0,0]
	v_cvt_scalef32_pk_f32_fp4 v[230:231], v166, 1.0 op_sel:[1,0,0]
	v_pk_fma_f32 v[232:233], v[28:29], v[224:225], v[232:233]
	v_pk_fma_f32 v[234:235], v[28:29], v[226:227], v[234:235]
	v_cvt_scalef32_pk_f32_fp4 v[224:225], v162, 1.0 op_sel:[0,1,0]
	v_cvt_scalef32_pk_f32_fp4 v[226:227], v166, 1.0 op_sel:[0,1,0]
	v_pk_fma_f32 v[232:233], v[30:31], v[228:229], v[232:233]
	v_pk_fma_f32 v[234:235], v[30:31], v[230:231], v[234:235]
	v_cvt_scalef32_pk_f32_fp4 v[228:229], v162, 1.0 op_sel:[1,1,0]
	v_cvt_scalef32_pk_f32_fp4 v[230:231], v166, 1.0 op_sel:[1,1,0]
	v_pk_fma_f32 v[232:233], v[16:17], v[224:225], v[232:233]
	v_pk_fma_f32 v[234:235], v[16:17], v[226:227], v[234:235]
	v_cvt_scalef32_pk_f32_fp4 v[224:225], v163, 1.0
	v_cvt_scalef32_pk_f32_fp4 v[226:227], v167, 1.0
	v_pk_fma_f32 v[232:233], v[18:19], v[228:229], v[232:233]
	v_pk_fma_f32 v[234:235], v[18:19], v[230:231], v[234:235]
	v_cvt_scalef32_pk_f32_fp4 v[228:229], v163, 1.0 op_sel:[1,0,0]
	v_cvt_scalef32_pk_f32_fp4 v[230:231], v167, 1.0 op_sel:[1,0,0]
	v_pk_fma_f32 v[232:233], v[8:9], v[224:225], v[232:233]
	v_pk_fma_f32 v[234:235], v[8:9], v[226:227], v[234:235]
	v_cvt_scalef32_pk_f32_fp4 v[224:225], v163, 1.0 op_sel:[0,1,0]
	v_cvt_scalef32_pk_f32_fp4 v[226:227], v167, 1.0 op_sel:[0,1,0]
	v_pk_fma_f32 v[232:233], v[10:11], v[228:229], v[232:233]
	v_pk_fma_f32 v[234:235], v[10:11], v[230:231], v[234:235]
	v_cvt_scalef32_pk_f32_fp4 v[228:229], v163, 1.0 op_sel:[1,1,0]
	v_cvt_scalef32_pk_f32_fp4 v[230:231], v167, 1.0 op_sel:[1,1,0]
	v_pk_fma_f32 v[232:233], v[20:21], v[224:225], v[232:233]
	v_pk_fma_f32 v[234:235], v[20:21], v[226:227], v[234:235]
	v_pk_fma_f32 v[232:233], v[22:23], v[228:229], v[232:233]
	v_pk_fma_f32 v[234:235], v[22:23], v[230:231], v[234:235]
	v_add_f32_e32 v32, v232, v233
	v_add_f32_e32 v33, v234, v235
	s_waitcnt vmcnt(12)
	v_cvt_scalef32_pk_f32_fp4 v[224:225], v168, 1.0
	v_cvt_scalef32_pk_f32_fp4 v[226:227], v172, 1.0
	v_cvt_scalef32_pk_f32_fp4 v[228:229], v168, 1.0 op_sel:[1,0,0]
	v_cvt_scalef32_pk_f32_fp4 v[230:231], v172, 1.0 op_sel:[1,0,0]
	v_pk_fma_f32 v[236:237], v[24:25], v[224:225], 0 op_sel_hi:[1,1,0]
	v_pk_fma_f32 v[238:239], v[24:25], v[226:227], 0 op_sel_hi:[1,1,0]
	v_cvt_scalef32_pk_f32_fp4 v[224:225], v168, 1.0 op_sel:[0,1,0]
	v_cvt_scalef32_pk_f32_fp4 v[226:227], v172, 1.0 op_sel:[0,1,0]
	v_pk_fma_f32 v[236:237], v[26:27], v[228:229], v[236:237]
	v_pk_fma_f32 v[238:239], v[26:27], v[230:231], v[238:239]
	v_cvt_scalef32_pk_f32_fp4 v[228:229], v168, 1.0 op_sel:[1,1,0]
	v_cvt_scalef32_pk_f32_fp4 v[230:231], v172, 1.0 op_sel:[1,1,0]
	v_pk_fma_f32 v[236:237], v[12:13], v[224:225], v[236:237]
	v_pk_fma_f32 v[238:239], v[12:13], v[226:227], v[238:239]
	v_cvt_scalef32_pk_f32_fp4 v[224:225], v169, 1.0
	v_cvt_scalef32_pk_f32_fp4 v[226:227], v173, 1.0
	v_pk_fma_f32 v[236:237], v[14:15], v[228:229], v[236:237]
	v_pk_fma_f32 v[238:239], v[14:15], v[230:231], v[238:239]
	v_cvt_scalef32_pk_f32_fp4 v[228:229], v169, 1.0 op_sel:[1,0,0]
	v_cvt_scalef32_pk_f32_fp4 v[230:231], v173, 1.0 op_sel:[1,0,0]
	v_pk_fma_f32 v[236:237], v[4:5], v[224:225], v[236:237]
	v_pk_fma_f32 v[238:239], v[4:5], v[226:227], v[238:239]
	v_cvt_scalef32_pk_f32_fp4 v[224:225], v169, 1.0 op_sel:[0,1,0]
	v_cvt_scalef32_pk_f32_fp4 v[226:227], v173, 1.0 op_sel:[0,1,0]
	v_pk_fma_f32 v[236:237], v[6:7], v[228:229], v[236:237]
	v_pk_fma_f32 v[238:239], v[6:7], v[230:231], v[238:239]
	v_cvt_scalef32_pk_f32_fp4 v[228:229], v169, 1.0 op_sel:[1,1,0]
	v_cvt_scalef32_pk_f32_fp4 v[230:231], v173, 1.0 op_sel:[1,1,0]
	v_pk_fma_f32 v[236:237], v[0:1], v[224:225], v[236:237]
	v_pk_fma_f32 v[238:239], v[0:1], v[226:227], v[238:239]
	v_cvt_scalef32_pk_f32_fp4 v[224:225], v170, 1.0
	v_cvt_scalef32_pk_f32_fp4 v[226:227], v174, 1.0
	v_pk_fma_f32 v[236:237], v[2:3], v[228:229], v[236:237]
	v_pk_fma_f32 v[238:239], v[2:3], v[230:231], v[238:239]
	v_cvt_scalef32_pk_f32_fp4 v[228:229], v170, 1.0 op_sel:[1,0,0]
	v_cvt_scalef32_pk_f32_fp4 v[230:231], v174, 1.0 op_sel:[1,0,0]
	v_pk_fma_f32 v[236:237], v[28:29], v[224:225], v[236:237]
	v_pk_fma_f32 v[238:239], v[28:29], v[226:227], v[238:239]
	v_cvt_scalef32_pk_f32_fp4 v[224:225], v170, 1.0 op_sel:[0,1,0]
	v_cvt_scalef32_pk_f32_fp4 v[226:227], v174, 1.0 op_sel:[0,1,0]
	v_pk_fma_f32 v[236:237], v[30:31], v[228:229], v[236:237]
	v_pk_fma_f32 v[238:239], v[30:31], v[230:231], v[238:239]
	v_cvt_scalef32_pk_f32_fp4 v[228:229], v170, 1.0 op_sel:[1,1,0]
	v_cvt_scalef32_pk_f32_fp4 v[230:231], v174, 1.0 op_sel:[1,1,0]
	v_pk_fma_f32 v[236:237], v[16:17], v[224:225], v[236:237]
	v_pk_fma_f32 v[238:239], v[16:17], v[226:227], v[238:239]
	v_cvt_scalef32_pk_f32_fp4 v[224:225], v171, 1.0
	v_cvt_scalef32_pk_f32_fp4 v[226:227], v175, 1.0
	v_pk_fma_f32 v[236:237], v[18:19], v[228:229], v[236:237]
	v_pk_fma_f32 v[238:239], v[18:19], v[230:231], v[238:239]
	v_cvt_scalef32_pk_f32_fp4 v[228:229], v171, 1.0 op_sel:[1,0,0]
	v_cvt_scalef32_pk_f32_fp4 v[230:231], v175, 1.0 op_sel:[1,0,0]
	v_pk_fma_f32 v[236:237], v[8:9], v[224:225], v[236:237]
	v_pk_fma_f32 v[238:239], v[8:9], v[226:227], v[238:239]
	v_cvt_scalef32_pk_f32_fp4 v[224:225], v171, 1.0 op_sel:[0,1,0]
	v_cvt_scalef32_pk_f32_fp4 v[226:227], v175, 1.0 op_sel:[0,1,0]
	v_pk_fma_f32 v[236:237], v[10:11], v[228:229], v[236:237]
	v_pk_fma_f32 v[238:239], v[10:11], v[230:231], v[238:239]
	v_cvt_scalef32_pk_f32_fp4 v[228:229], v171, 1.0 op_sel:[1,1,0]
	v_cvt_scalef32_pk_f32_fp4 v[230:231], v175, 1.0 op_sel:[1,1,0]
	v_pk_fma_f32 v[236:237], v[20:21], v[224:225], v[236:237]
	v_pk_fma_f32 v[238:239], v[20:21], v[226:227], v[238:239]
	v_pk_fma_f32 v[236:237], v[22:23], v[228:229], v[236:237]
	v_pk_fma_f32 v[238:239], v[22:23], v[230:231], v[238:239]
	v_add_f32_e32 v34, v236, v237
	v_add_f32_e32 v35, v238, v239
	s_nop 1
	v_permlane16_swap_b32_e32 v32, v34
	v_permlane16_swap_b32_e32 v33, v35
	v_add_f32_e32 v36, v32, v34
	v_add_f32_e32 v38, v33, v35
	s_waitcnt lgkmcnt(0)
	v_cndmask_b32_e64 v40, v38, v36, s[0:1]
	v_cndmask_b32_e64 v41, v36, v38, s[0:1]
	s_nop 1
	v_add_f32_dpp v40, v41, v40 row_ror:8 row_mask:0xf bank_mask:0xf
	s_nop 1
	v_add_f32_dpp v40, v40, v40 quad_perm:[1,0,3,2] row_mask:0xf bank_mask:0xf
	s_nop 1
	v_add_f32_dpp v40, v40, v40 quad_perm:[2,3,0,1] row_mask:0xf bank_mask:0xf
	s_nop 1
	v_add_f32_dpp v40, v40, v40 row_half_mirror row_mask:0xf bank_mask:0xf
	v_mul_f32_e32 v42, v40, v156
	v_fma_f32 v43, |v42|, s16, 1.0
	v_rcp_f32_e32 v43, v43
	v_cmp_gt_f32_e64 s[4:5], 0, v42
	v_mul_f32_e32 v45, v42, v42
	v_fmamk_f32 v44, v43, 0x3f07dc22, v142
	v_fmaak_f32 v44, v43, v44, 0x3f35f0e3
	v_fmaak_f32 v44, v43, v44, 0xbe11a98e
	v_fmaak_f32 v44, v43, v44, 0x3e027906
	v_mul_f32_e32 v45, 0xbf38aa3b, v45
	v_exp_f32_e32 v45, v45
	v_mul_f32_e32 v43, v43, v44
	v_mul_f32_e32 v43, v45, v43
	v_mul_f32_e32 v44, v42, v43
	v_fma_f32 v42, -v42, v43, v42
	v_cndmask_b32_e64 v42, v42, v44, s[4:5]
	v_mul_f32_e32 v158, v42, v157
	ds_bpermute_b32 v118, v138, v158
	ds_bpermute_b32 v120, v139, v158
	ds_bpermute_b32 v122, v140, v158
	ds_bpermute_b32 v124, v141, v158
	s_waitcnt vmcnt(11)
	v_cvt_scalef32_pk_f32_fp4 v[224:225], v176, 1.0
	v_cvt_scalef32_pk_f32_fp4 v[226:227], v176, 1.0 op_sel:[1,0,0]
	s_waitcnt lgkmcnt(0)
	v_cvt_scalef32_pk_f32_fp4 v[228:229], v176, 1.0 op_sel:[0,1,0]
	v_pk_fma_f32 v[112:113], v[224:225], v[118:119], v[112:113] op_sel_hi:[1,0,1]
	v_cvt_scalef32_pk_f32_fp4 v[230:231], v176, 1.0 op_sel:[1,1,0]
	v_pk_fma_f32 v[108:109], v[226:227], v[118:119], v[108:109] op_sel_hi:[1,0,1]
	v_cvt_scalef32_pk_f32_fp4 v[224:225], v177, 1.0
	v_pk_fma_f32 v[104:105], v[228:229], v[118:119], v[104:105] op_sel_hi:[1,0,1]
	v_cvt_scalef32_pk_f32_fp4 v[226:227], v177, 1.0 op_sel:[1,0,0]
	v_pk_fma_f32 v[98:99], v[230:231], v[118:119], v[98:99] op_sel_hi:[1,0,1]
	v_cvt_scalef32_pk_f32_fp4 v[228:229], v177, 1.0 op_sel:[0,1,0]
	v_pk_fma_f32 v[54:55], v[224:225], v[118:119], v[54:55] op_sel_hi:[1,0,1]
	v_cvt_scalef32_pk_f32_fp4 v[230:231], v177, 1.0 op_sel:[1,1,0]
	v_pk_fma_f32 v[58:59], v[226:227], v[118:119], v[58:59] op_sel_hi:[1,0,1]
	v_cvt_scalef32_pk_f32_fp4 v[224:225], v178, 1.0
	v_pk_fma_f32 v[52:53], v[228:229], v[118:119], v[52:53] op_sel_hi:[1,0,1]
	v_cvt_scalef32_pk_f32_fp4 v[226:227], v178, 1.0 op_sel:[1,0,0]
	v_pk_fma_f32 v[48:49], v[230:231], v[118:119], v[48:49] op_sel_hi:[1,0,1]
	v_cvt_scalef32_pk_f32_fp4 v[228:229], v178, 1.0 op_sel:[0,1,0]
	v_pk_fma_f32 v[106:107], v[224:225], v[118:119], v[106:107] op_sel_hi:[1,0,1]
	v_cvt_scalef32_pk_f32_fp4 v[230:231], v178, 1.0 op_sel:[1,1,0]
	v_pk_fma_f32 v[102:103], v[226:227], v[118:119], v[102:103] op_sel_hi:[1,0,1]
	v_cvt_scalef32_pk_f32_fp4 v[224:225], v179, 1.0
	v_pk_fma_f32 v[96:97], v[228:229], v[118:119], v[96:97] op_sel_hi:[1,0,1]
	v_cvt_scalef32_pk_f32_fp4 v[226:227], v179, 1.0 op_sel:[1,0,0]
	v_pk_fma_f32 v[56:57], v[230:231], v[118:119], v[56:57] op_sel_hi:[1,0,1]
	v_cvt_scalef32_pk_f32_fp4 v[228:229], v179, 1.0 op_sel:[0,1,0]
	v_pk_fma_f32 v[50:51], v[224:225], v[118:119], v[50:51] op_sel_hi:[1,0,1]
	v_cvt_scalef32_pk_f32_fp4 v[230:231], v179, 1.0 op_sel:[1,1,0]
	v_pk_fma_f32 v[114:115], v[226:227], v[118:119], v[114:115] op_sel_hi:[1,0,1]
	v_pk_fma_f32 v[110:111], v[228:229], v[118:119], v[110:111] op_sel_hi:[1,0,1]
	v_pk_fma_f32 v[100:101], v[230:231], v[118:119], v[100:101] op_sel_hi:[1,0,1]
	s_waitcnt vmcnt(10)
	v_cvt_scalef32_pk_f32_fp4 v[224:225], v180, 1.0
	v_cvt_scalef32_pk_f32_fp4 v[226:227], v180, 1.0 op_sel:[1,0,0]
	v_cvt_scalef32_pk_f32_fp4 v[228:229], v180, 1.0 op_sel:[0,1,0]
	v_pk_fma_f32 v[112:113], v[224:225], v[120:121], v[112:113] op_sel_hi:[1,0,1]
	v_cvt_scalef32_pk_f32_fp4 v[230:231], v180, 1.0 op_sel:[1,1,0]
	v_pk_fma_f32 v[108:109], v[226:227], v[120:121], v[108:109] op_sel_hi:[1,0,1]
	v_cvt_scalef32_pk_f32_fp4 v[224:225], v181, 1.0
	v_pk_fma_f32 v[104:105], v[228:229], v[120:121], v[104:105] op_sel_hi:[1,0,1]
	v_cvt_scalef32_pk_f32_fp4 v[226:227], v181, 1.0 op_sel:[1,0,0]
	v_pk_fma_f32 v[98:99], v[230:231], v[120:121], v[98:99] op_sel_hi:[1,0,1]
	v_cvt_scalef32_pk_f32_fp4 v[228:229], v181, 1.0 op_sel:[0,1,0]
	v_pk_fma_f32 v[54:55], v[224:225], v[120:121], v[54:55] op_sel_hi:[1,0,1]
	v_cvt_scalef32_pk_f32_fp4 v[230:231], v181, 1.0 op_sel:[1,1,0]
	v_pk_fma_f32 v[58:59], v[226:227], v[120:121], v[58:59] op_sel_hi:[1,0,1]
	v_cvt_scalef32_pk_f32_fp4 v[224:225], v182, 1.0
	v_pk_fma_f32 v[52:53], v[228:229], v[120:121], v[52:53] op_sel_hi:[1,0,1]
	v_cvt_scalef32_pk_f32_fp4 v[226:227], v182, 1.0 op_sel:[1,0,0]
	v_pk_fma_f32 v[48:49], v[230:231], v[120:121], v[48:49] op_sel_hi:[1,0,1]
	v_cvt_scalef32_pk_f32_fp4 v[228:229], v182, 1.0 op_sel:[0,1,0]
	v_pk_fma_f32 v[106:107], v[224:225], v[120:121], v[106:107] op_sel_hi:[1,0,1]
	v_cvt_scalef32_pk_f32_fp4 v[230:231], v182, 1.0 op_sel:[1,1,0]
	v_pk_fma_f32 v[102:103], v[226:227], v[120:121], v[102:103] op_sel_hi:[1,0,1]
	v_cvt_scalef32_pk_f32_fp4 v[224:225], v183, 1.0
	v_pk_fma_f32 v[96:97], v[228:229], v[120:121], v[96:97] op_sel_hi:[1,0,1]
	v_cvt_scalef32_pk_f32_fp4 v[226:227], v183, 1.0 op_sel:[1,0,0]
	v_pk_fma_f32 v[56:57], v[230:231], v[120:121], v[56:57] op_sel_hi:[1,0,1]
	v_cvt_scalef32_pk_f32_fp4 v[228:229], v183, 1.0 op_sel:[0,1,0]
	v_pk_fma_f32 v[50:51], v[224:225], v[120:121], v[50:51] op_sel_hi:[1,0,1]
	v_cvt_scalef32_pk_f32_fp4 v[230:231], v183, 1.0 op_sel:[1,1,0]
	v_pk_fma_f32 v[114:115], v[226:227], v[120:121], v[114:115] op_sel_hi:[1,0,1]
	v_pk_fma_f32 v[110:111], v[228:229], v[120:121], v[110:111] op_sel_hi:[1,0,1]
	v_pk_fma_f32 v[100:101], v[230:231], v[120:121], v[100:101] op_sel_hi:[1,0,1]
	s_waitcnt vmcnt(9)
	v_cvt_scalef32_pk_f32_fp4 v[224:225], v184, 1.0
	v_cvt_scalef32_pk_f32_fp4 v[226:227], v184, 1.0 op_sel:[1,0,0]
	v_cvt_scalef32_pk_f32_fp4 v[228:229], v184, 1.0 op_sel:[0,1,0]
	v_pk_fma_f32 v[112:113], v[224:225], v[122:123], v[112:113] op_sel_hi:[1,0,1]
	v_cvt_scalef32_pk_f32_fp4 v[230:231], v184, 1.0 op_sel:[1,1,0]
	v_pk_fma_f32 v[108:109], v[226:227], v[122:123], v[108:109] op_sel_hi:[1,0,1]
	v_cvt_scalef32_pk_f32_fp4 v[224:225], v185, 1.0
	v_pk_fma_f32 v[104:105], v[228:229], v[122:123], v[104:105] op_sel_hi:[1,0,1]
	v_cvt_scalef32_pk_f32_fp4 v[226:227], v185, 1.0 op_sel:[1,0,0]
	v_pk_fma_f32 v[98:99], v[230:231], v[122:123], v[98:99] op_sel_hi:[1,0,1]
	v_cvt_scalef32_pk_f32_fp4 v[228:229], v185, 1.0 op_sel:[0,1,0]
	v_pk_fma_f32 v[54:55], v[224:225], v[122:123], v[54:55] op_sel_hi:[1,0,1]
	v_cvt_scalef32_pk_f32_fp4 v[230:231], v185, 1.0 op_sel:[1,1,0]
	v_pk_fma_f32 v[58:59], v[226:227], v[122:123], v[58:59] op_sel_hi:[1,0,1]
	v_cvt_scalef32_pk_f32_fp4 v[224:225], v186, 1.0
	v_pk_fma_f32 v[52:53], v[228:229], v[122:123], v[52:53] op_sel_hi:[1,0,1]
	v_cvt_scalef32_pk_f32_fp4 v[226:227], v186, 1.0 op_sel:[1,0,0]
	v_pk_fma_f32 v[48:49], v[230:231], v[122:123], v[48:49] op_sel_hi:[1,0,1]
	v_cvt_scalef32_pk_f32_fp4 v[228:229], v186, 1.0 op_sel:[0,1,0]
	v_pk_fma_f32 v[106:107], v[224:225], v[122:123], v[106:107] op_sel_hi:[1,0,1]
	v_cvt_scalef32_pk_f32_fp4 v[230:231], v186, 1.0 op_sel:[1,1,0]
	v_pk_fma_f32 v[102:103], v[226:227], v[122:123], v[102:103] op_sel_hi:[1,0,1]
	v_cvt_scalef32_pk_f32_fp4 v[224:225], v187, 1.0
	v_pk_fma_f32 v[96:97], v[228:229], v[122:123], v[96:97] op_sel_hi:[1,0,1]
	v_cvt_scalef32_pk_f32_fp4 v[226:227], v187, 1.0 op_sel:[1,0,0]
	v_pk_fma_f32 v[56:57], v[230:231], v[122:123], v[56:57] op_sel_hi:[1,0,1]
	v_cvt_scalef32_pk_f32_fp4 v[228:229], v187, 1.0 op_sel:[0,1,0]
	v_pk_fma_f32 v[50:51], v[224:225], v[122:123], v[50:51] op_sel_hi:[1,0,1]
	v_cvt_scalef32_pk_f32_fp4 v[230:231], v187, 1.0 op_sel:[1,1,0]
	v_pk_fma_f32 v[114:115], v[226:227], v[122:123], v[114:115] op_sel_hi:[1,0,1]
	v_pk_fma_f32 v[110:111], v[228:229], v[122:123], v[110:111] op_sel_hi:[1,0,1]
	v_pk_fma_f32 v[100:101], v[230:231], v[122:123], v[100:101] op_sel_hi:[1,0,1]
	s_waitcnt vmcnt(8)
	v_cvt_scalef32_pk_f32_fp4 v[224:225], v188, 1.0
	v_cvt_scalef32_pk_f32_fp4 v[226:227], v188, 1.0 op_sel:[1,0,0]
	v_cvt_scalef32_pk_f32_fp4 v[228:229], v188, 1.0 op_sel:[0,1,0]
	v_pk_fma_f32 v[112:113], v[224:225], v[124:125], v[112:113] op_sel_hi:[1,0,1]
	v_cvt_scalef32_pk_f32_fp4 v[230:231], v188, 1.0 op_sel:[1,1,0]
	v_pk_fma_f32 v[108:109], v[226:227], v[124:125], v[108:109] op_sel_hi:[1,0,1]
	v_cvt_scalef32_pk_f32_fp4 v[224:225], v189, 1.0
	v_pk_fma_f32 v[104:105], v[228:229], v[124:125], v[104:105] op_sel_hi:[1,0,1]
	v_cvt_scalef32_pk_f32_fp4 v[226:227], v189, 1.0 op_sel:[1,0,0]
	v_pk_fma_f32 v[98:99], v[230:231], v[124:125], v[98:99] op_sel_hi:[1,0,1]
	v_cvt_scalef32_pk_f32_fp4 v[228:229], v189, 1.0 op_sel:[0,1,0]
	v_pk_fma_f32 v[54:55], v[224:225], v[124:125], v[54:55] op_sel_hi:[1,0,1]
	v_cvt_scalef32_pk_f32_fp4 v[230:231], v189, 1.0 op_sel:[1,1,0]
	v_pk_fma_f32 v[58:59], v[226:227], v[124:125], v[58:59] op_sel_hi:[1,0,1]
	v_cvt_scalef32_pk_f32_fp4 v[224:225], v190, 1.0
	v_pk_fma_f32 v[52:53], v[228:229], v[124:125], v[52:53] op_sel_hi:[1,0,1]
	v_cvt_scalef32_pk_f32_fp4 v[226:227], v190, 1.0 op_sel:[1,0,0]
	v_pk_fma_f32 v[48:49], v[230:231], v[124:125], v[48:49] op_sel_hi:[1,0,1]
	v_cvt_scalef32_pk_f32_fp4 v[228:229], v190, 1.0 op_sel:[0,1,0]
	v_pk_fma_f32 v[106:107], v[224:225], v[124:125], v[106:107] op_sel_hi:[1,0,1]
	v_cvt_scalef32_pk_f32_fp4 v[230:231], v190, 1.0 op_sel:[1,1,0]
	v_pk_fma_f32 v[102:103], v[226:227], v[124:125], v[102:103] op_sel_hi:[1,0,1]
	v_cvt_scalef32_pk_f32_fp4 v[224:225], v191, 1.0
	v_pk_fma_f32 v[96:97], v[228:229], v[124:125], v[96:97] op_sel_hi:[1,0,1]
	v_cvt_scalef32_pk_f32_fp4 v[226:227], v191, 1.0 op_sel:[1,0,0]
	v_pk_fma_f32 v[56:57], v[230:231], v[124:125], v[56:57] op_sel_hi:[1,0,1]
	v_cvt_scalef32_pk_f32_fp4 v[228:229], v191, 1.0 op_sel:[0,1,0]
	v_pk_fma_f32 v[50:51], v[224:225], v[124:125], v[50:51] op_sel_hi:[1,0,1]
	v_cvt_scalef32_pk_f32_fp4 v[230:231], v191, 1.0 op_sel:[1,1,0]
	v_pk_fma_f32 v[114:115], v[226:227], v[124:125], v[114:115] op_sel_hi:[1,0,1]
	v_pk_fma_f32 v[110:111], v[228:229], v[124:125], v[110:111] op_sel_hi:[1,0,1]
	v_pk_fma_f32 v[100:101], v[230:231], v[124:125], v[100:101] op_sel_hi:[1,0,1]
	s_waitcnt lgkmcnt(0)
	s_movk_i32 s20, 0xe0
	v_lshl_add_u32 v130, v137, 2, s20
	ds_bpermute_b32 v156, v130, v147
	ds_bpermute_b32 v157, v130, v149
	s_waitcnt vmcnt(6)
	v_cvt_scalef32_pk_f32_fp4 v[224:225], v192, 1.0
	v_cvt_scalef32_pk_f32_fp4 v[226:227], v196, 1.0
	v_cvt_scalef32_pk_f32_fp4 v[228:229], v192, 1.0 op_sel:[1,0,0]
	v_cvt_scalef32_pk_f32_fp4 v[230:231], v196, 1.0 op_sel:[1,0,0]
	v_pk_fma_f32 v[232:233], v[24:25], v[224:225], 0 op_sel_hi:[1,1,0]
	v_pk_fma_f32 v[234:235], v[24:25], v[226:227], 0 op_sel_hi:[1,1,0]
	v_cvt_scalef32_pk_f32_fp4 v[224:225], v192, 1.0 op_sel:[0,1,0]
	v_cvt_scalef32_pk_f32_fp4 v[226:227], v196, 1.0 op_sel:[0,1,0]
	v_pk_fma_f32 v[232:233], v[26:27], v[228:229], v[232:233]
	v_pk_fma_f32 v[234:235], v[26:27], v[230:231], v[234:235]
	v_cvt_scalef32_pk_f32_fp4 v[228:229], v192, 1.0 op_sel:[1,1,0]
	v_cvt_scalef32_pk_f32_fp4 v[230:231], v196, 1.0 op_sel:[1,1,0]
	v_pk_fma_f32 v[232:233], v[12:13], v[224:225], v[232:233]
	v_pk_fma_f32 v[234:235], v[12:13], v[226:227], v[234:235]
	v_cvt_scalef32_pk_f32_fp4 v[224:225], v193, 1.0
	v_cvt_scalef32_pk_f32_fp4 v[226:227], v197, 1.0
	v_pk_fma_f32 v[232:233], v[14:15], v[228:229], v[232:233]
	v_pk_fma_f32 v[234:235], v[14:15], v[230:231], v[234:235]
	v_cvt_scalef32_pk_f32_fp4 v[228:229], v193, 1.0 op_sel:[1,0,0]
	v_cvt_scalef32_pk_f32_fp4 v[230:231], v197, 1.0 op_sel:[1,0,0]
	v_pk_fma_f32 v[232:233], v[4:5], v[224:225], v[232:233]
	v_pk_fma_f32 v[234:235], v[4:5], v[226:227], v[234:235]
	v_cvt_scalef32_pk_f32_fp4 v[224:225], v193, 1.0 op_sel:[0,1,0]
	v_cvt_scalef32_pk_f32_fp4 v[226:227], v197, 1.0 op_sel:[0,1,0]
	v_pk_fma_f32 v[232:233], v[6:7], v[228:229], v[232:233]
	v_pk_fma_f32 v[234:235], v[6:7], v[230:231], v[234:235]
	v_cvt_scalef32_pk_f32_fp4 v[228:229], v193, 1.0 op_sel:[1,1,0]
	v_cvt_scalef32_pk_f32_fp4 v[230:231], v197, 1.0 op_sel:[1,1,0]
	v_pk_fma_f32 v[232:233], v[0:1], v[224:225], v[232:233]
	v_pk_fma_f32 v[234:235], v[0:1], v[226:227], v[234:235]
	v_cvt_scalef32_pk_f32_fp4 v[224:225], v194, 1.0
	v_cvt_scalef32_pk_f32_fp4 v[226:227], v198, 1.0
	v_pk_fma_f32 v[232:233], v[2:3], v[228:229], v[232:233]
	v_pk_fma_f32 v[234:235], v[2:3], v[230:231], v[234:235]
	v_cvt_scalef32_pk_f32_fp4 v[228:229], v194, 1.0 op_sel:[1,0,0]
	v_cvt_scalef32_pk_f32_fp4 v[230:231], v198, 1.0 op_sel:[1,0,0]
	v_pk_fma_f32 v[232:233], v[28:29], v[224:225], v[232:233]
	v_pk_fma_f32 v[234:235], v[28:29], v[226:227], v[234:235]
	v_cvt_scalef32_pk_f32_fp4 v[224:225], v194, 1.0 op_sel:[0,1,0]
	v_cvt_scalef32_pk_f32_fp4 v[226:227], v198, 1.0 op_sel:[0,1,0]
	v_pk_fma_f32 v[232:233], v[30:31], v[228:229], v[232:233]
	v_pk_fma_f32 v[234:235], v[30:31], v[230:231], v[234:235]
	v_cvt_scalef32_pk_f32_fp4 v[228:229], v194, 1.0 op_sel:[1,1,0]
	v_cvt_scalef32_pk_f32_fp4 v[230:231], v198, 1.0 op_sel:[1,1,0]
	v_pk_fma_f32 v[232:233], v[16:17], v[224:225], v[232:233]
	v_pk_fma_f32 v[234:235], v[16:17], v[226:227], v[234:235]
	v_cvt_scalef32_pk_f32_fp4 v[224:225], v195, 1.0
	v_cvt_scalef32_pk_f32_fp4 v[226:227], v199, 1.0
	v_pk_fma_f32 v[232:233], v[18:19], v[228:229], v[232:233]
	v_pk_fma_f32 v[234:235], v[18:19], v[230:231], v[234:235]
	v_cvt_scalef32_pk_f32_fp4 v[228:229], v195, 1.0 op_sel:[1,0,0]
	v_cvt_scalef32_pk_f32_fp4 v[230:231], v199, 1.0 op_sel:[1,0,0]
	v_pk_fma_f32 v[232:233], v[8:9], v[224:225], v[232:233]
	v_pk_fma_f32 v[234:235], v[8:9], v[226:227], v[234:235]
	v_cvt_scalef32_pk_f32_fp4 v[224:225], v195, 1.0 op_sel:[0,1,0]
	v_cvt_scalef32_pk_f32_fp4 v[226:227], v199, 1.0 op_sel:[0,1,0]
	v_pk_fma_f32 v[232:233], v[10:11], v[228:229], v[232:233]
	v_pk_fma_f32 v[234:235], v[10:11], v[230:231], v[234:235]
	v_cvt_scalef32_pk_f32_fp4 v[228:229], v195, 1.0 op_sel:[1,1,0]
	v_cvt_scalef32_pk_f32_fp4 v[230:231], v199, 1.0 op_sel:[1,1,0]
	v_pk_fma_f32 v[232:233], v[20:21], v[224:225], v[232:233]
	v_pk_fma_f32 v[234:235], v[20:21], v[226:227], v[234:235]
	v_pk_fma_f32 v[232:233], v[22:23], v[228:229], v[232:233]
	v_pk_fma_f32 v[234:235], v[22:23], v[230:231], v[234:235]
	v_add_f32_e32 v32, v232, v233
	v_add_f32_e32 v33, v234, v235
	s_waitcnt vmcnt(4)
	v_cvt_scalef32_pk_f32_fp4 v[224:225], v200, 1.0
	v_cvt_scalef32_pk_f32_fp4 v[226:227], v204, 1.0
	v_cvt_scalef32_pk_f32_fp4 v[228:229], v200, 1.0 op_sel:[1,0,0]
	v_cvt_scalef32_pk_f32_fp4 v[230:231], v204, 1.0 op_sel:[1,0,0]
	v_pk_fma_f32 v[236:237], v[24:25], v[224:225], 0 op_sel_hi:[1,1,0]
	v_pk_fma_f32 v[238:239], v[24:25], v[226:227], 0 op_sel_hi:[1,1,0]
	v_cvt_scalef32_pk_f32_fp4 v[224:225], v200, 1.0 op_sel:[0,1,0]
	v_cvt_scalef32_pk_f32_fp4 v[226:227], v204, 1.0 op_sel:[0,1,0]
	v_pk_fma_f32 v[236:237], v[26:27], v[228:229], v[236:237]
	v_pk_fma_f32 v[238:239], v[26:27], v[230:231], v[238:239]
	v_cvt_scalef32_pk_f32_fp4 v[228:229], v200, 1.0 op_sel:[1,1,0]
	v_cvt_scalef32_pk_f32_fp4 v[230:231], v204, 1.0 op_sel:[1,1,0]
	v_pk_fma_f32 v[236:237], v[12:13], v[224:225], v[236:237]
	v_pk_fma_f32 v[238:239], v[12:13], v[226:227], v[238:239]
	v_cvt_scalef32_pk_f32_fp4 v[224:225], v201, 1.0
	v_cvt_scalef32_pk_f32_fp4 v[226:227], v205, 1.0
	v_pk_fma_f32 v[236:237], v[14:15], v[228:229], v[236:237]
	v_pk_fma_f32 v[238:239], v[14:15], v[230:231], v[238:239]
	v_cvt_scalef32_pk_f32_fp4 v[228:229], v201, 1.0 op_sel:[1,0,0]
	v_cvt_scalef32_pk_f32_fp4 v[230:231], v205, 1.0 op_sel:[1,0,0]
	v_pk_fma_f32 v[236:237], v[4:5], v[224:225], v[236:237]
	v_pk_fma_f32 v[238:239], v[4:5], v[226:227], v[238:239]
	v_cvt_scalef32_pk_f32_fp4 v[224:225], v201, 1.0 op_sel:[0,1,0]
	v_cvt_scalef32_pk_f32_fp4 v[226:227], v205, 1.0 op_sel:[0,1,0]
	v_pk_fma_f32 v[236:237], v[6:7], v[228:229], v[236:237]
	v_pk_fma_f32 v[238:239], v[6:7], v[230:231], v[238:239]
	v_cvt_scalef32_pk_f32_fp4 v[228:229], v201, 1.0 op_sel:[1,1,0]
	v_cvt_scalef32_pk_f32_fp4 v[230:231], v205, 1.0 op_sel:[1,1,0]
	v_pk_fma_f32 v[236:237], v[0:1], v[224:225], v[236:237]
	v_pk_fma_f32 v[238:239], v[0:1], v[226:227], v[238:239]
	v_cvt_scalef32_pk_f32_fp4 v[224:225], v202, 1.0
	v_cvt_scalef32_pk_f32_fp4 v[226:227], v206, 1.0
	v_pk_fma_f32 v[236:237], v[2:3], v[228:229], v[236:237]
	v_pk_fma_f32 v[238:239], v[2:3], v[230:231], v[238:239]
	v_cvt_scalef32_pk_f32_fp4 v[228:229], v202, 1.0 op_sel:[1,0,0]
	v_cvt_scalef32_pk_f32_fp4 v[230:231], v206, 1.0 op_sel:[1,0,0]
	v_pk_fma_f32 v[236:237], v[28:29], v[224:225], v[236:237]
	v_pk_fma_f32 v[238:239], v[28:29], v[226:227], v[238:239]
	v_cvt_scalef32_pk_f32_fp4 v[224:225], v202, 1.0 op_sel:[0,1,0]
	v_cvt_scalef32_pk_f32_fp4 v[226:227], v206, 1.0 op_sel:[0,1,0]
	v_pk_fma_f32 v[236:237], v[30:31], v[228:229], v[236:237]
	v_pk_fma_f32 v[238:239], v[30:31], v[230:231], v[238:239]
	v_cvt_scalef32_pk_f32_fp4 v[228:229], v202, 1.0 op_sel:[1,1,0]
	v_cvt_scalef32_pk_f32_fp4 v[230:231], v206, 1.0 op_sel:[1,1,0]
	v_pk_fma_f32 v[236:237], v[16:17], v[224:225], v[236:237]
	v_pk_fma_f32 v[238:239], v[16:17], v[226:227], v[238:239]
	v_cvt_scalef32_pk_f32_fp4 v[224:225], v203, 1.0
	v_cvt_scalef32_pk_f32_fp4 v[226:227], v207, 1.0
	v_pk_fma_f32 v[236:237], v[18:19], v[228:229], v[236:237]
	v_pk_fma_f32 v[238:239], v[18:19], v[230:231], v[238:239]
	v_cvt_scalef32_pk_f32_fp4 v[228:229], v203, 1.0 op_sel:[1,0,0]
	v_cvt_scalef32_pk_f32_fp4 v[230:231], v207, 1.0 op_sel:[1,0,0]
	v_pk_fma_f32 v[236:237], v[8:9], v[224:225], v[236:237]
	v_pk_fma_f32 v[238:239], v[8:9], v[226:227], v[238:239]
	v_cvt_scalef32_pk_f32_fp4 v[224:225], v203, 1.0 op_sel:[0,1,0]
	v_cvt_scalef32_pk_f32_fp4 v[226:227], v207, 1.0 op_sel:[0,1,0]
	v_pk_fma_f32 v[236:237], v[10:11], v[228:229], v[236:237]
	v_pk_fma_f32 v[238:239], v[10:11], v[230:231], v[238:239]
	v_cvt_scalef32_pk_f32_fp4 v[228:229], v203, 1.0 op_sel:[1,1,0]
	v_cvt_scalef32_pk_f32_fp4 v[230:231], v207, 1.0 op_sel:[1,1,0]
	v_pk_fma_f32 v[236:237], v[20:21], v[224:225], v[236:237]
	v_pk_fma_f32 v[238:239], v[20:21], v[226:227], v[238:239]
	v_pk_fma_f32 v[236:237], v[22:23], v[228:229], v[236:237]
	v_pk_fma_f32 v[238:239], v[22:23], v[230:231], v[238:239]
	v_add_f32_e32 v34, v236, v237
	v_add_f32_e32 v35, v238, v239
	s_nop 1
	v_permlane16_swap_b32_e32 v32, v34
	v_permlane16_swap_b32_e32 v33, v35
	v_add_f32_e32 v36, v32, v34
	v_add_f32_e32 v38, v33, v35
	s_waitcnt lgkmcnt(0)
	v_cndmask_b32_e64 v40, v38, v36, s[0:1]
	v_cndmask_b32_e64 v41, v36, v38, s[0:1]
	s_nop 1
	v_add_f32_dpp v40, v41, v40 row_ror:8 row_mask:0xf bank_mask:0xf
	s_nop 1
	v_add_f32_dpp v40, v40, v40 quad_perm:[1,0,3,2] row_mask:0xf bank_mask:0xf
	s_nop 1
	v_add_f32_dpp v40, v40, v40 quad_perm:[2,3,0,1] row_mask:0xf bank_mask:0xf
	s_nop 1
	v_add_f32_dpp v40, v40, v40 row_half_mirror row_mask:0xf bank_mask:0xf
	v_mul_f32_e32 v42, v40, v156
	v_fma_f32 v43, |v42|, s16, 1.0
	v_rcp_f32_e32 v43, v43
	v_cmp_gt_f32_e64 s[4:5], 0, v42
	v_mul_f32_e32 v45, v42, v42
	v_fmamk_f32 v44, v43, 0x3f07dc22, v142
	v_fmaak_f32 v44, v43, v44, 0x3f35f0e3
	v_fmaak_f32 v44, v43, v44, 0xbe11a98e
	v_fmaak_f32 v44, v43, v44, 0x3e027906
	v_mul_f32_e32 v45, 0xbf38aa3b, v45
	v_exp_f32_e32 v45, v45
	v_mul_f32_e32 v43, v43, v44
	v_mul_f32_e32 v43, v45, v43
	v_mul_f32_e32 v44, v42, v43
	v_fma_f32 v42, -v42, v43, v42
	v_cndmask_b32_e64 v42, v42, v44, s[4:5]
	v_mul_f32_e32 v158, v42, v157
	ds_bpermute_b32 v118, v138, v158
	ds_bpermute_b32 v120, v139, v158
	ds_bpermute_b32 v122, v140, v158
	ds_bpermute_b32 v124, v141, v158
	s_waitcnt vmcnt(3)
	v_cvt_scalef32_pk_f32_fp4 v[224:225], v208, 1.0
	v_cvt_scalef32_pk_f32_fp4 v[226:227], v208, 1.0 op_sel:[1,0,0]
	s_waitcnt lgkmcnt(0)
	v_cvt_scalef32_pk_f32_fp4 v[228:229], v208, 1.0 op_sel:[0,1,0]
	v_pk_fma_f32 v[112:113], v[224:225], v[118:119], v[112:113] op_sel_hi:[1,0,1]
	v_cvt_scalef32_pk_f32_fp4 v[230:231], v208, 1.0 op_sel:[1,1,0]
	v_pk_fma_f32 v[108:109], v[226:227], v[118:119], v[108:109] op_sel_hi:[1,0,1]
	v_cvt_scalef32_pk_f32_fp4 v[224:225], v209, 1.0
	v_pk_fma_f32 v[104:105], v[228:229], v[118:119], v[104:105] op_sel_hi:[1,0,1]
	v_cvt_scalef32_pk_f32_fp4 v[226:227], v209, 1.0 op_sel:[1,0,0]
	v_pk_fma_f32 v[98:99], v[230:231], v[118:119], v[98:99] op_sel_hi:[1,0,1]
	v_cvt_scalef32_pk_f32_fp4 v[228:229], v209, 1.0 op_sel:[0,1,0]
	v_pk_fma_f32 v[54:55], v[224:225], v[118:119], v[54:55] op_sel_hi:[1,0,1]
	v_cvt_scalef32_pk_f32_fp4 v[230:231], v209, 1.0 op_sel:[1,1,0]
	v_pk_fma_f32 v[58:59], v[226:227], v[118:119], v[58:59] op_sel_hi:[1,0,1]
	v_cvt_scalef32_pk_f32_fp4 v[224:225], v210, 1.0
	v_pk_fma_f32 v[52:53], v[228:229], v[118:119], v[52:53] op_sel_hi:[1,0,1]
	v_cvt_scalef32_pk_f32_fp4 v[226:227], v210, 1.0 op_sel:[1,0,0]
	v_pk_fma_f32 v[48:49], v[230:231], v[118:119], v[48:49] op_sel_hi:[1,0,1]
	v_cvt_scalef32_pk_f32_fp4 v[228:229], v210, 1.0 op_sel:[0,1,0]
	v_pk_fma_f32 v[106:107], v[224:225], v[118:119], v[106:107] op_sel_hi:[1,0,1]
	v_cvt_scalef32_pk_f32_fp4 v[230:231], v210, 1.0 op_sel:[1,1,0]
	v_pk_fma_f32 v[102:103], v[226:227], v[118:119], v[102:103] op_sel_hi:[1,0,1]
	v_cvt_scalef32_pk_f32_fp4 v[224:225], v211, 1.0
	v_pk_fma_f32 v[96:97], v[228:229], v[118:119], v[96:97] op_sel_hi:[1,0,1]
	v_cvt_scalef32_pk_f32_fp4 v[226:227], v211, 1.0 op_sel:[1,0,0]
	v_pk_fma_f32 v[56:57], v[230:231], v[118:119], v[56:57] op_sel_hi:[1,0,1]
	v_cvt_scalef32_pk_f32_fp4 v[228:229], v211, 1.0 op_sel:[0,1,0]
	v_pk_fma_f32 v[50:51], v[224:225], v[118:119], v[50:51] op_sel_hi:[1,0,1]
	v_cvt_scalef32_pk_f32_fp4 v[230:231], v211, 1.0 op_sel:[1,1,0]
	v_pk_fma_f32 v[114:115], v[226:227], v[118:119], v[114:115] op_sel_hi:[1,0,1]
	v_pk_fma_f32 v[110:111], v[228:229], v[118:119], v[110:111] op_sel_hi:[1,0,1]
	v_pk_fma_f32 v[100:101], v[230:231], v[118:119], v[100:101] op_sel_hi:[1,0,1]
	s_waitcnt vmcnt(2)
	v_cvt_scalef32_pk_f32_fp4 v[224:225], v212, 1.0
	v_cvt_scalef32_pk_f32_fp4 v[226:227], v212, 1.0 op_sel:[1,0,0]
	v_cvt_scalef32_pk_f32_fp4 v[228:229], v212, 1.0 op_sel:[0,1,0]
	v_pk_fma_f32 v[112:113], v[224:225], v[120:121], v[112:113] op_sel_hi:[1,0,1]
	v_cvt_scalef32_pk_f32_fp4 v[230:231], v212, 1.0 op_sel:[1,1,0]
	v_pk_fma_f32 v[108:109], v[226:227], v[120:121], v[108:109] op_sel_hi:[1,0,1]
	v_cvt_scalef32_pk_f32_fp4 v[224:225], v213, 1.0
	v_pk_fma_f32 v[104:105], v[228:229], v[120:121], v[104:105] op_sel_hi:[1,0,1]
	v_cvt_scalef32_pk_f32_fp4 v[226:227], v213, 1.0 op_sel:[1,0,0]
	v_pk_fma_f32 v[98:99], v[230:231], v[120:121], v[98:99] op_sel_hi:[1,0,1]
	v_cvt_scalef32_pk_f32_fp4 v[228:229], v213, 1.0 op_sel:[0,1,0]
	v_pk_fma_f32 v[54:55], v[224:225], v[120:121], v[54:55] op_sel_hi:[1,0,1]
	v_cvt_scalef32_pk_f32_fp4 v[230:231], v213, 1.0 op_sel:[1,1,0]
	v_pk_fma_f32 v[58:59], v[226:227], v[120:121], v[58:59] op_sel_hi:[1,0,1]
	v_cvt_scalef32_pk_f32_fp4 v[224:225], v214, 1.0
	v_pk_fma_f32 v[52:53], v[228:229], v[120:121], v[52:53] op_sel_hi:[1,0,1]
	v_cvt_scalef32_pk_f32_fp4 v[226:227], v214, 1.0 op_sel:[1,0,0]
	v_pk_fma_f32 v[48:49], v[230:231], v[120:121], v[48:49] op_sel_hi:[1,0,1]
	v_cvt_scalef32_pk_f32_fp4 v[228:229], v214, 1.0 op_sel:[0,1,0]
	v_pk_fma_f32 v[106:107], v[224:225], v[120:121], v[106:107] op_sel_hi:[1,0,1]
	v_cvt_scalef32_pk_f32_fp4 v[230:231], v214, 1.0 op_sel:[1,1,0]
	v_pk_fma_f32 v[102:103], v[226:227], v[120:121], v[102:103] op_sel_hi:[1,0,1]
	v_cvt_scalef32_pk_f32_fp4 v[224:225], v215, 1.0
	v_pk_fma_f32 v[96:97], v[228:229], v[120:121], v[96:97] op_sel_hi:[1,0,1]
	v_cvt_scalef32_pk_f32_fp4 v[226:227], v215, 1.0 op_sel:[1,0,0]
	v_pk_fma_f32 v[56:57], v[230:231], v[120:121], v[56:57] op_sel_hi:[1,0,1]
	v_cvt_scalef32_pk_f32_fp4 v[228:229], v215, 1.0 op_sel:[0,1,0]
	v_pk_fma_f32 v[50:51], v[224:225], v[120:121], v[50:51] op_sel_hi:[1,0,1]
	v_cvt_scalef32_pk_f32_fp4 v[230:231], v215, 1.0 op_sel:[1,1,0]
	v_pk_fma_f32 v[114:115], v[226:227], v[120:121], v[114:115] op_sel_hi:[1,0,1]
	v_pk_fma_f32 v[110:111], v[228:229], v[120:121], v[110:111] op_sel_hi:[1,0,1]
	v_pk_fma_f32 v[100:101], v[230:231], v[120:121], v[100:101] op_sel_hi:[1,0,1]
	s_waitcnt vmcnt(1)
	v_cvt_scalef32_pk_f32_fp4 v[224:225], v216, 1.0
	v_cvt_scalef32_pk_f32_fp4 v[226:227], v216, 1.0 op_sel:[1,0,0]
	v_cvt_scalef32_pk_f32_fp4 v[228:229], v216, 1.0 op_sel:[0,1,0]
	v_pk_fma_f32 v[112:113], v[224:225], v[122:123], v[112:113] op_sel_hi:[1,0,1]
	v_cvt_scalef32_pk_f32_fp4 v[230:231], v216, 1.0 op_sel:[1,1,0]
	v_pk_fma_f32 v[108:109], v[226:227], v[122:123], v[108:109] op_sel_hi:[1,0,1]
	v_cvt_scalef32_pk_f32_fp4 v[224:225], v217, 1.0
	v_pk_fma_f32 v[104:105], v[228:229], v[122:123], v[104:105] op_sel_hi:[1,0,1]
	v_cvt_scalef32_pk_f32_fp4 v[226:227], v217, 1.0 op_sel:[1,0,0]
	v_pk_fma_f32 v[98:99], v[230:231], v[122:123], v[98:99] op_sel_hi:[1,0,1]
	v_cvt_scalef32_pk_f32_fp4 v[228:229], v217, 1.0 op_sel:[0,1,0]
	v_pk_fma_f32 v[54:55], v[224:225], v[122:123], v[54:55] op_sel_hi:[1,0,1]
	v_cvt_scalef32_pk_f32_fp4 v[230:231], v217, 1.0 op_sel:[1,1,0]
	v_pk_fma_f32 v[58:59], v[226:227], v[122:123], v[58:59] op_sel_hi:[1,0,1]
	v_cvt_scalef32_pk_f32_fp4 v[224:225], v218, 1.0
	v_pk_fma_f32 v[52:53], v[228:229], v[122:123], v[52:53] op_sel_hi:[1,0,1]
	v_cvt_scalef32_pk_f32_fp4 v[226:227], v218, 1.0 op_sel:[1,0,0]
	v_pk_fma_f32 v[48:49], v[230:231], v[122:123], v[48:49] op_sel_hi:[1,0,1]
	v_cvt_scalef32_pk_f32_fp4 v[228:229], v218, 1.0 op_sel:[0,1,0]
	v_pk_fma_f32 v[106:107], v[224:225], v[122:123], v[106:107] op_sel_hi:[1,0,1]
	v_cvt_scalef32_pk_f32_fp4 v[230:231], v218, 1.0 op_sel:[1,1,0]
	v_pk_fma_f32 v[102:103], v[226:227], v[122:123], v[102:103] op_sel_hi:[1,0,1]
	v_cvt_scalef32_pk_f32_fp4 v[224:225], v219, 1.0
	v_pk_fma_f32 v[96:97], v[228:229], v[122:123], v[96:97] op_sel_hi:[1,0,1]
	v_cvt_scalef32_pk_f32_fp4 v[226:227], v219, 1.0 op_sel:[1,0,0]
	v_pk_fma_f32 v[56:57], v[230:231], v[122:123], v[56:57] op_sel_hi:[1,0,1]
	v_cvt_scalef32_pk_f32_fp4 v[228:229], v219, 1.0 op_sel:[0,1,0]
	v_pk_fma_f32 v[50:51], v[224:225], v[122:123], v[50:51] op_sel_hi:[1,0,1]
	v_cvt_scalef32_pk_f32_fp4 v[230:231], v219, 1.0 op_sel:[1,1,0]
	v_pk_fma_f32 v[114:115], v[226:227], v[122:123], v[114:115] op_sel_hi:[1,0,1]
	v_pk_fma_f32 v[110:111], v[228:229], v[122:123], v[110:111] op_sel_hi:[1,0,1]
	v_pk_fma_f32 v[100:101], v[230:231], v[122:123], v[100:101] op_sel_hi:[1,0,1]
	s_waitcnt vmcnt(0)
	v_cvt_scalef32_pk_f32_fp4 v[224:225], v220, 1.0
	v_cvt_scalef32_pk_f32_fp4 v[226:227], v220, 1.0 op_sel:[1,0,0]
	v_cvt_scalef32_pk_f32_fp4 v[228:229], v220, 1.0 op_sel:[0,1,0]
	v_pk_fma_f32 v[112:113], v[224:225], v[124:125], v[112:113] op_sel_hi:[1,0,1]
	v_cvt_scalef32_pk_f32_fp4 v[230:231], v220, 1.0 op_sel:[1,1,0]
	v_pk_fma_f32 v[108:109], v[226:227], v[124:125], v[108:109] op_sel_hi:[1,0,1]
	v_cvt_scalef32_pk_f32_fp4 v[224:225], v221, 1.0
	v_pk_fma_f32 v[104:105], v[228:229], v[124:125], v[104:105] op_sel_hi:[1,0,1]
	v_cvt_scalef32_pk_f32_fp4 v[226:227], v221, 1.0 op_sel:[1,0,0]
	v_pk_fma_f32 v[98:99], v[230:231], v[124:125], v[98:99] op_sel_hi:[1,0,1]
	v_cvt_scalef32_pk_f32_fp4 v[228:229], v221, 1.0 op_sel:[0,1,0]
	v_pk_fma_f32 v[54:55], v[224:225], v[124:125], v[54:55] op_sel_hi:[1,0,1]
	v_cvt_scalef32_pk_f32_fp4 v[230:231], v221, 1.0 op_sel:[1,1,0]
	v_pk_fma_f32 v[58:59], v[226:227], v[124:125], v[58:59] op_sel_hi:[1,0,1]
	v_cvt_scalef32_pk_f32_fp4 v[224:225], v222, 1.0
	v_pk_fma_f32 v[52:53], v[228:229], v[124:125], v[52:53] op_sel_hi:[1,0,1]
	v_cvt_scalef32_pk_f32_fp4 v[226:227], v222, 1.0 op_sel:[1,0,0]
	v_pk_fma_f32 v[48:49], v[230:231], v[124:125], v[48:49] op_sel_hi:[1,0,1]
	v_cvt_scalef32_pk_f32_fp4 v[228:229], v222, 1.0 op_sel:[0,1,0]
	v_pk_fma_f32 v[106:107], v[224:225], v[124:125], v[106:107] op_sel_hi:[1,0,1]
	v_cvt_scalef32_pk_f32_fp4 v[230:231], v222, 1.0 op_sel:[1,1,0]
	v_pk_fma_f32 v[102:103], v[226:227], v[124:125], v[102:103] op_sel_hi:[1,0,1]
	v_cvt_scalef32_pk_f32_fp4 v[224:225], v223, 1.0
	v_pk_fma_f32 v[96:97], v[228:229], v[124:125], v[96:97] op_sel_hi:[1,0,1]
	v_cvt_scalef32_pk_f32_fp4 v[226:227], v223, 1.0 op_sel:[1,0,0]
	v_pk_fma_f32 v[56:57], v[230:231], v[124:125], v[56:57] op_sel_hi:[1,0,1]
	v_cvt_scalef32_pk_f32_fp4 v[228:229], v223, 1.0 op_sel:[0,1,0]
	v_pk_fma_f32 v[50:51], v[224:225], v[124:125], v[50:51] op_sel_hi:[1,0,1]
	v_cvt_scalef32_pk_f32_fp4 v[230:231], v223, 1.0 op_sel:[1,1,0]
	v_pk_fma_f32 v[114:115], v[226:227], v[124:125], v[114:115] op_sel_hi:[1,0,1]
	v_pk_fma_f32 v[110:111], v[228:229], v[124:125], v[110:111] op_sel_hi:[1,0,1]
	v_pk_fma_f32 v[100:101], v[230:231], v[124:125], v[100:101] op_sel_hi:[1,0,1]
	ds_bpermute_b32 v32, v135, v112
	ds_bpermute_b32 v33, v135, v113
	ds_bpermute_b32 v126, v135, v110
	ds_bpermute_b32 v127, v135, v111
	ds_bpermute_b32 v116, v135, v106
	ds_bpermute_b32 v117, v135, v107
	ds_bpermute_b32 v34, v135, v108
	ds_bpermute_b32 v35, v135, v109
	ds_bpermute_b32 v118, v135, v102
	ds_bpermute_b32 v119, v135, v103
	s_waitcnt lgkmcnt(8)
	v_pk_add_f32 v[32:33], v[112:113], v[32:33]
	s_waitcnt lgkmcnt(6)
	v_pk_add_f32 v[110:111], v[110:111], v[126:127]
	v_pk_fma_f32 v[24:25], v[24:25], s[12:13], v[32:33] op_sel_hi:[1,0,1]
	v_pk_fma_f32 v[20:21], v[20:21], s[12:13], v[110:111] op_sel_hi:[1,0,1]
	ds_bpermute_b32 v110, v135, v100
	ds_bpermute_b32 v111, v135, v101
	v_add_f32_e32 v32, 0, v24
	ds_bpermute_b32 v36, v135, v104
	ds_bpermute_b32 v37, v135, v105
	v_add_f32_e32 v64, v32, v25
	s_waitcnt lgkmcnt(8)
	v_pk_add_f32 v[32:33], v[106:107], v[116:117]
	ds_bpermute_b32 v120, v135, v96
	ds_bpermute_b32 v121, v135, v97
	v_pk_fma_f32 v[28:29], v[28:29], s[12:13], v[32:33] op_sel_hi:[1,0,1]
	s_waitcnt lgkmcnt(8)
	v_pk_add_f32 v[32:33], v[108:109], v[34:35]
	ds_bpermute_b32 v38, v135, v98
	v_pk_fma_f32 v[26:27], v[26:27], s[12:13], v[32:33] op_sel_hi:[1,0,1]
	s_waitcnt lgkmcnt(7)
	v_pk_add_f32 v[32:33], v[102:103], v[118:119]
	ds_bpermute_b32 v39, v135, v99
	v_pk_fma_f32 v[30:31], v[30:31], s[12:13], v[32:33] op_sel_hi:[1,0,1]
	v_add_f32_e32 v32, v64, v26
	ds_bpermute_b32 v122, v135, v56
	ds_bpermute_b32 v123, v135, v57
	v_add_f32_e32 v34, v32, v27
	s_waitcnt lgkmcnt(8)
	v_pk_add_f32 v[32:33], v[100:101], v[110:111]
	ds_bpermute_b32 v40, v135, v54
	v_pk_fma_f32 v[22:23], v[22:23], s[12:13], v[32:33] op_sel_hi:[1,0,1]
	s_waitcnt lgkmcnt(7)
	v_pk_add_f32 v[32:33], v[104:105], v[36:37]
	ds_bpermute_b32 v41, v135, v55
	v_pk_fma_f32 v[12:13], v[12:13], s[12:13], v[32:33] op_sel_hi:[1,0,1]
	s_waitcnt lgkmcnt(6)
	v_pk_add_f32 v[32:33], v[96:97], v[120:121]
	ds_bpermute_b32 v128, v135, v50
	ds_bpermute_b32 v129, v135, v51
	v_pk_fma_f32 v[16:17], v[16:17], s[12:13], v[32:33] op_sel_hi:[1,0,1]
	v_add_f32_e32 v32, v34, v12
	v_add_f32_e32 v34, v32, v13
	s_waitcnt lgkmcnt(6)
	v_pk_add_f32 v[32:33], v[98:99], v[38:39]
	ds_bpermute_b32 v42, v135, v58
	ds_bpermute_b32 v43, v135, v59
	v_pk_fma_f32 v[14:15], v[14:15], s[12:13], v[32:33] op_sel_hi:[1,0,1]
	s_waitcnt lgkmcnt(6)
	v_pk_add_f32 v[32:33], v[56:57], v[122:123]
	ds_bpermute_b32 v44, v135, v52
	v_pk_fma_f32 v[18:19], v[18:19], s[12:13], v[32:33] op_sel_hi:[1,0,1]
	v_add_f32_e32 v32, v34, v14
	v_add_f32_e32 v34, v32, v15
	s_waitcnt lgkmcnt(5)
	v_pk_add_f32 v[32:33], v[54:55], v[40:41]
	ds_bpermute_b32 v45, v135, v53
	v_pk_fma_f32 v[32:33], v[4:5], s[12:13], v[32:33] op_sel_hi:[1,0,1]
	s_waitcnt lgkmcnt(4)
	v_pk_add_f32 v[4:5], v[50:51], v[128:129]
	ds_bpermute_b32 v46, v135, v48
	v_pk_fma_f32 v[8:9], v[8:9], s[12:13], v[4:5] op_sel_hi:[1,0,1]
	v_add_f32_e32 v4, v34, v32
	v_add_f32_e32 v36, v4, v33
	s_waitcnt lgkmcnt(3)
	v_pk_add_f32 v[4:5], v[58:59], v[42:43]
	ds_bpermute_b32 v47, v135, v49
	v_pk_fma_f32 v[34:35], v[6:7], s[12:13], v[4:5] op_sel_hi:[1,0,1]
	ds_bpermute_b32 v124, v135, v114
	v_add_f32_e32 v4, v36, v34
	v_add_f32_e32 v6, v4, v35
	s_waitcnt lgkmcnt(3)
	v_pk_add_f32 v[4:5], v[52:53], v[44:45]
	ds_bpermute_b32 v125, v135, v115
	v_pk_fma_f32 v[36:37], v[0:1], s[12:13], v[4:5] op_sel_hi:[1,0,1]
	v_mov_b32_e32 v92, v144
	v_add_f32_e32 v0, v6, v36
	v_add_f32_e32 v4, v0, v37
	s_waitcnt lgkmcnt(2)
	v_pk_add_f32 v[0:1], v[48:49], v[46:47]
	s_waitcnt lgkmcnt(0)
	v_pk_add_f32 v[114:115], v[114:115], v[124:125]
	v_pk_fma_f32 v[38:39], v[2:3], s[12:13], v[0:1] op_sel_hi:[1,0,1]
	v_pk_fma_f32 v[10:11], v[10:11], s[12:13], v[114:115] op_sel_hi:[1,0,1]
	v_add_f32_e32 v0, v4, v38
	v_add_f32_e32 v0, v0, v39
	v_add_f32_e32 v0, v0, v28
	v_add_f32_e32 v0, v0, v29
	v_add_f32_e32 v0, v0, v30
	v_add_f32_e32 v0, v0, v31
	v_add_f32_e32 v0, v0, v16
	v_add_f32_e32 v0, v0, v17
	v_add_f32_e32 v0, v0, v18
	v_add_f32_e32 v0, v0, v19
	v_add_f32_e32 v0, v0, v8
	v_add_f32_e32 v0, v0, v9
	v_add_f32_e32 v0, v0, v10
	v_add_f32_e32 v0, v0, v11
	v_add_f32_e32 v0, v0, v20
	v_add_f32_e32 v0, v0, v21
	v_add_f32_e32 v0, v0, v22
	v_add_f32_e32 v0, v0, v23
	ds_bpermute_b32 v1, v61, v0
	v_mov_b32_e32 v94, v145
	s_waitcnt lgkmcnt(0)
	v_add_f32_e32 v0, v0, v1
	ds_bpermute_b32 v1, v63, v0
	s_waitcnt lgkmcnt(0)
	v_add_f32_e32 v0, v0, v1
	ds_bpermute_b32 v1, v132, v0
	s_waitcnt lgkmcnt(0)
	v_add_f32_e32 v0, v0, v1
	ds_bpermute_b32 v1, v133, v0
	s_waitcnt lgkmcnt(0)
	v_add_f32_e32 v40, v0, v1
	ds_bpermute_b32 v41, v134, v40
	global_load_dwordx4 v[0:3], v[70:71], off
	global_load_dwordx4 v[4:7], v[72:73], off
	s_waitcnt lgkmcnt(0)
	v_add_f32_e32 v40, v40, v41
	v_mul_f32_e32 v40, 0x3a800000, v40
	v_pk_add_f32 v[24:25], v[24:25], v[40:41] op_sel_hi:[1,0] neg_lo:[0,1] neg_hi:[0,1]
	v_pk_add_f32 v[26:27], v[26:27], v[40:41] op_sel_hi:[1,0] neg_lo:[0,1] neg_hi:[0,1]
	v_pk_mul_f32 v[42:43], v[24:25], v[24:25]
	v_pk_mul_f32 v[44:45], v[26:27], v[26:27]
	v_add_f32_e32 v42, v42, v43
	v_pk_add_f32 v[12:13], v[12:13], v[40:41] op_sel_hi:[1,0] neg_lo:[0,1] neg_hi:[0,1]
	v_add_f32_e32 v42, v44, v42
	v_pk_mul_f32 v[46:47], v[12:13], v[12:13]
	v_add_f32_e32 v42, v45, v42
	v_pk_add_f32 v[14:15], v[14:15], v[40:41] op_sel_hi:[1,0] neg_lo:[0,1] neg_hi:[0,1]
	v_add_f32_e32 v42, v46, v42
	v_pk_mul_f32 v[48:49], v[14:15], v[14:15]
	v_add_f32_e32 v42, v47, v42
	v_pk_add_f32 v[32:33], v[32:33], v[40:41] op_sel_hi:[1,0] neg_lo:[0,1] neg_hi:[0,1]
	v_add_f32_e32 v42, v48, v42
	v_pk_mul_f32 v[50:51], v[32:33], v[32:33]
	v_add_f32_e32 v42, v49, v42
	v_pk_add_f32 v[34:35], v[34:35], v[40:41] op_sel_hi:[1,0] neg_lo:[0,1] neg_hi:[0,1]
	v_add_f32_e32 v42, v50, v42
	v_pk_mul_f32 v[52:53], v[34:35], v[34:35]
	v_add_f32_e32 v42, v51, v42
	v_pk_add_f32 v[36:37], v[36:37], v[40:41] op_sel_hi:[1,0] neg_lo:[0,1] neg_hi:[0,1]
	v_add_f32_e32 v42, v52, v42
	v_pk_mul_f32 v[54:55], v[36:37], v[36:37]
	v_add_f32_e32 v42, v53, v42
	v_pk_add_f32 v[38:39], v[38:39], v[40:41] op_sel_hi:[1,0] neg_lo:[0,1] neg_hi:[0,1]
	v_add_f32_e32 v42, v54, v42
	v_pk_mul_f32 v[56:57], v[38:39], v[38:39]
	v_add_f32_e32 v42, v55, v42
	v_pk_add_f32 v[28:29], v[28:29], v[40:41] op_sel_hi:[1,0] neg_lo:[0,1] neg_hi:[0,1]
	v_add_f32_e32 v42, v56, v42
	v_pk_mul_f32 v[58:59], v[28:29], v[28:29]
	v_add_f32_e32 v42, v57, v42
	v_pk_add_f32 v[30:31], v[30:31], v[40:41] op_sel_hi:[1,0] neg_lo:[0,1] neg_hi:[0,1]
	v_add_f32_e32 v42, v58, v42
	v_pk_mul_f32 v[96:97], v[30:31], v[30:31]
	v_add_f32_e32 v42, v59, v42
	v_pk_add_f32 v[16:17], v[16:17], v[40:41] op_sel_hi:[1,0] neg_lo:[0,1] neg_hi:[0,1]
	v_add_f32_e32 v42, v96, v42
	v_pk_mul_f32 v[98:99], v[16:17], v[16:17]
	v_add_f32_e32 v42, v97, v42
	v_pk_add_f32 v[18:19], v[18:19], v[40:41] op_sel_hi:[1,0] neg_lo:[0,1] neg_hi:[0,1]
	v_add_f32_e32 v42, v98, v42
	v_pk_mul_f32 v[100:101], v[18:19], v[18:19]
	v_add_f32_e32 v42, v99, v42
	v_pk_add_f32 v[8:9], v[8:9], v[40:41] op_sel_hi:[1,0] neg_lo:[0,1] neg_hi:[0,1]
	v_add_f32_e32 v42, v100, v42
	v_pk_mul_f32 v[102:103], v[8:9], v[8:9]
	v_add_f32_e32 v42, v101, v42
	v_pk_add_f32 v[10:11], v[10:11], v[40:41] op_sel_hi:[1,0] neg_lo:[0,1] neg_hi:[0,1]
	v_add_f32_e32 v42, v102, v42
	v_pk_mul_f32 v[104:105], v[10:11], v[10:11]
	v_add_f32_e32 v42, v103, v42
	v_pk_add_f32 v[20:21], v[20:21], v[40:41] op_sel_hi:[1,0] neg_lo:[0,1] neg_hi:[0,1]
	v_add_f32_e32 v42, v104, v42
	v_pk_mul_f32 v[106:107], v[20:21], v[20:21]
	v_add_f32_e32 v42, v105, v42
	v_pk_add_f32 v[22:23], v[22:23], v[40:41] op_sel_hi:[1,0] neg_lo:[0,1] neg_hi:[0,1]
	v_add_f32_e32 v42, v106, v42
	v_pk_mul_f32 v[40:41], v[22:23], v[22:23]
	v_add_f32_e32 v42, v107, v42
	v_add_f32_e32 v40, v40, v42
	v_add_f32_e32 v40, v41, v40
	ds_bpermute_b32 v41, v61, v40
	v_cndmask_b32_e64 v27, v31, v27, s[2:3]
	v_cndmask_b32_e64 v26, v30, v26, s[2:3]
	v_cndmask_b32_e64 v25, v29, v25, s[2:3]
	v_cndmask_b32_e64 v24, v28, v24, s[2:3]
	s_waitcnt lgkmcnt(0)
	v_add_f32_e32 v40, v40, v41
	ds_bpermute_b32 v41, v63, v40
	v_cndmask_b32_e64 v13, v17, v13, s[2:3]
	v_cndmask_b32_e64 v12, v16, v12, s[2:3]
	v_cndmask_b32_e64 v15, v19, v15, s[2:3]
	v_cndmask_b32_e64 v14, v18, v14, s[2:3]
	s_waitcnt lgkmcnt(0)
	v_add_f32_e32 v40, v40, v41
	ds_bpermute_b32 v41, v132, v40
	v_cndmask_b32_e64 v9, v9, v33, s[2:3]
	v_cndmask_b32_e64 v8, v8, v32, s[2:3]
	v_cndmask_b32_e64 v11, v11, v35, s[2:3]
	v_cndmask_b32_e64 v10, v10, v34, s[2:3]
	s_waitcnt lgkmcnt(0)
	v_add_f32_e32 v40, v40, v41
	ds_bpermute_b32 v41, v133, v40
	v_mov_b32_e32 v32, v95
	s_waitcnt lgkmcnt(0)
	v_add_f32_e32 v40, v40, v41
	ds_bpermute_b32 v41, v134, v40
	s_waitcnt lgkmcnt(0)
	v_add_f32_e32 v40, v40, v41
	v_fmamk_f32 v40, v40, 0x3a800000, v143
	v_mul_f32_e32 v41, 0x4b800000, v40
	v_cmp_gt_f32_e64 s[4:5], s17, v40
	s_nop 1
	v_cndmask_b32_e64 v40, v40, v41, s[4:5]
	v_rsq_f32_e32 v42, v40
	v_lshl_add_u64 v[40:41], v[88:89], 0, v[90:91]
	v_mul_f32_e32 v43, 0x45800000, v42
	v_cndmask_b32_e64 v42, v42, v43, s[4:5]
	v_pk_mul_f32 v[24:25], v[24:25], v[42:43] op_sel_hi:[1,0]
	v_pk_mul_f32 v[26:27], v[26:27], v[42:43] op_sel_hi:[1,0]
	s_waitcnt vmcnt(0)
	v_pk_fma_f32 v[0:1], v[0:1], v[24:25], v[4:5]
	v_pk_fma_f32 v[2:3], v[2:3], v[26:27], v[6:7]
	global_store_dwordx4 v[40:41], v[0:3], off
	global_load_dwordx4 v[0:3], v[74:75], off
	s_nop 0
	global_load_dwordx4 v[4:7], v[76:77], off
	v_pk_mul_f32 v[14:15], v[14:15], v[42:43] op_sel_hi:[1,0]
	v_pk_mul_f32 v[12:13], v[12:13], v[42:43] op_sel_hi:[1,0]
	v_pk_mul_f32 v[10:11], v[10:11], v[42:43] op_sel_hi:[1,0]
	v_pk_mul_f32 v[8:9], v[8:9], v[42:43] op_sel_hi:[1,0]
	s_waitcnt vmcnt(0)
	v_pk_fma_f32 v[0:1], v[0:1], v[12:13], v[4:5]
	v_pk_fma_f32 v[2:3], v[2:3], v[14:15], v[6:7]
	global_store_dwordx4 v[40:41], v[0:3], off offset:16
	global_load_dwordx4 v[0:3], v[78:79], off
	s_nop 0
	global_load_dwordx4 v[4:7], v[80:81], off
	s_waitcnt vmcnt(0)
	v_pk_fma_f32 v[0:1], v[0:1], v[8:9], v[4:5]
	v_pk_fma_f32 v[2:3], v[2:3], v[10:11], v[6:7]
	global_store_dwordx4 v[40:41], v[0:3], off offset:32
	global_load_dwordx4 v[0:3], v[82:83], off
	s_nop 0
	global_load_dwordx4 v[4:7], v[84:85], off
	v_cndmask_b32_e64 v9, v21, v37, s[2:3]
	v_cndmask_b32_e64 v8, v20, v36, s[2:3]
	v_cndmask_b32_e64 v11, v23, v39, s[2:3]
	v_cndmask_b32_e64 v10, v22, v38, s[2:3]
	v_pk_mul_f32 v[10:11], v[10:11], v[42:43] op_sel_hi:[1,0]
	v_pk_mul_f32 v[8:9], v[8:9], v[42:43] op_sel_hi:[1,0]
	s_waitcnt vmcnt(0)
	v_pk_fma_f32 v[2:3], v[2:3], v[10:11], v[6:7]
	v_pk_fma_f32 v[0:1], v[0:1], v[8:9], v[4:5]
	global_store_dwordx4 v[40:41], v[0:3], off offset:48
	s_andn2_b64 exec, exec, s[10:11]
	s_cbranch_execnz .LBB0_698
